# handover variant + the mid-segment s_setprio 0/1 flip between the two MMA blocks of every super-phase removed (44 sites)
# speedup vs baseline: 1.0029x; 1.0013x over previous
.LBB0_297:
	s_add_u32 s0, s36, 0xfff80080
	s_addc_u32 s6, s37, -1
	s_add_i32 s49, 0, 0x10000
	s_cmp_eq_u32 s55, 28
	s_cselect_b32 s35, s25, s6
	s_cselect_b32 s34, s33, s0
	v_add_u32_e32 v156, s49, v159
	s_cselect_b32 s31, s40, s39
	s_cselect_b32 s30, s50, s38
	s_add_i32 s0, 0, 0x14000
	ds_read_b128 v[144:147], v156
	ds_read_b128 v[148:151], v156 offset:1024
	ds_read_b128 v[152:155], v156 offset:2048
	ds_read_b128 v[164:167], v156 offset:3072
	v_add_u32_e32 v156, s0, v159
	ds_read_b128 v[168:171], v156
	ds_read_b128 v[172:175], v156 offset:1024
	ds_read_b128 v[176:179], v156 offset:2048
	ds_read_b128 v[180:183], v156 offset:3072
	v_lshl_add_u64 v[156:157], s[36:37], 0, v[140:141]
	s_add_i32 m0, s47, 0xc000
	ds_read_b128 v[184:187], v163
	ds_read_b128 v[188:191], v163 offset:1024
	ds_read_b128 v[192:195], v163 offset:2048
	ds_read_b128 v[200:203], v163 offset:3072
	ds_read_b128 v[204:207], v163 offset:4096
	ds_read_b128 v[208:211], v163 offset:5120
	ds_read_b128 v[212:215], v163 offset:6144
	ds_read_b128 v[216:219], v163 offset:7168
	global_load_lds_dwordx4 v[156:157], off
	v_lshl_add_u64 v[156:157], s[36:37], 0, v[142:143]
	s_add_i32 m0, s47, 0xe000
	s_nop 0
	global_load_lds_dwordx4 v[156:157], off
	s_waitcnt vmcnt(8)
	s_waitcnt lgkmcnt(0)
	s_setprio 1
	s_barrier
	v_mfma_f32_16x16x32_bf16 v[128:131], v[144:147], v[184:187], v[128:131]
	v_mfma_f32_16x16x32_bf16 v[124:127], v[152:155], v[184:187], v[124:127]
	v_mfma_f32_16x16x32_bf16 v[112:115], v[144:147], v[192:195], v[112:115]
	v_mfma_f32_16x16x32_bf16 v[108:111], v[152:155], v[192:195], v[108:111]
	v_mfma_f32_16x16x32_bf16 v[96:99], v[144:147], v[204:207], v[96:99]
	v_mfma_f32_16x16x32_bf16 v[92:95], v[152:155], v[204:207], v[92:95]
	v_mfma_f32_16x16x32_bf16 v[80:83], v[144:147], v[212:215], v[80:83]
	v_mfma_f32_16x16x32_bf16 v[76:79], v[152:155], v[212:215], v[76:79]
	v_mfma_f32_16x16x32_bf16 v[128:131], v[148:151], v[188:191], v[128:131]
	v_mfma_f32_16x16x32_bf16 v[124:127], v[164:167], v[188:191], v[124:127]
	v_mfma_f32_16x16x32_bf16 v[112:115], v[148:151], v[200:203], v[112:115]
	v_mfma_f32_16x16x32_bf16 v[108:111], v[164:167], v[200:203], v[108:111]
	v_mfma_f32_16x16x32_bf16 v[96:99], v[148:151], v[208:211], v[96:99]
	v_mfma_f32_16x16x32_bf16 v[92:95], v[164:167], v[208:211], v[92:95]
	v_mfma_f32_16x16x32_bf16 v[80:83], v[148:151], v[216:219], v[80:83]
	v_mfma_f32_16x16x32_bf16 v[76:79], v[164:167], v[216:219], v[76:79]
	v_mfma_f32_16x16x32_bf16 v[120:123], v[168:171], v[184:187], v[120:123]
	v_mfma_f32_16x16x32_bf16 v[116:119], v[176:179], v[184:187], v[116:119]
	v_mfma_f32_16x16x32_bf16 v[104:107], v[168:171], v[192:195], v[104:107]
	v_mfma_f32_16x16x32_bf16 v[100:103], v[176:179], v[192:195], v[100:103]
	v_mfma_f32_16x16x32_bf16 v[88:91], v[168:171], v[204:207], v[88:91]
	v_mfma_f32_16x16x32_bf16 v[84:87], v[176:179], v[204:207], v[84:87]
	v_mfma_f32_16x16x32_bf16 v[72:75], v[168:171], v[212:215], v[72:75]
	v_mfma_f32_16x16x32_bf16 v[68:71], v[176:179], v[212:215], v[68:71]
	v_mfma_f32_16x16x32_bf16 v[120:123], v[172:175], v[188:191], v[120:123]
	v_mfma_f32_16x16x32_bf16 v[116:119], v[180:183], v[188:191], v[116:119]
	v_mfma_f32_16x16x32_bf16 v[104:107], v[172:175], v[200:203], v[104:107]
	v_mfma_f32_16x16x32_bf16 v[100:103], v[180:183], v[200:203], v[100:103]
	v_mfma_f32_16x16x32_bf16 v[88:91], v[172:175], v[208:211], v[88:91]
	v_mfma_f32_16x16x32_bf16 v[84:87], v[180:183], v[208:211], v[84:87]
	v_mfma_f32_16x16x32_bf16 v[72:75], v[172:175], v[216:219], v[72:75]
	v_mfma_f32_16x16x32_bf16 v[68:71], v[180:183], v[216:219], v[68:71]
	s_barrier
	s_setprio 0
	s_add_i32 s6, s49, s46
	v_lshl_add_u64 v[156:157], s[30:31], 0, v[136:137]
	s_mov_b32 m0, s6
	ds_read_b128 v[184:187], v163 offset:16384
	ds_read_b128 v[188:191], v163 offset:17408
	ds_read_b128 v[192:195], v163 offset:18432
	ds_read_b128 v[200:203], v163 offset:19456
	ds_read_b128 v[204:207], v163 offset:20480
	ds_read_b128 v[208:211], v163 offset:21504
	ds_read_b128 v[212:215], v163 offset:22528
	ds_read_b128 v[216:219], v163 offset:23552
	global_load_lds_dwordx4 v[156:157], off
	s_add_i32 m0, s6, 0x2000
	s_add_u32 s66, s30, 0x80000
	v_lshl_add_u64 v[220:221], s[30:31], 0, v[132:133]
	s_addc_u32 s67, s31, 0
	s_add_i32 s0, s0, s46
	global_load_lds_dwordx4 v[220:221], off
	v_lshl_add_u64 v[222:223], s[66:67], 0, v[136:137]
	s_mov_b32 m0, s0
	v_lshl_add_u64 v[224:225], s[34:35], 0, v[134:135]
	global_load_lds_dwordx4 v[222:223], off
	v_lshl_add_u64 v[222:223], s[66:67], 0, v[132:133]
	s_add_i32 m0, s0, 0x2000
	s_nop 0
	global_load_lds_dwordx4 v[222:223], off
	v_lshl_add_u64 v[222:223], s[34:35], 0, v[138:139]
	s_mov_b32 m0, s47
	s_nop 0
	global_load_lds_dwordx4 v[222:223], off
	s_mov_b32 m0, s52
	s_nop 0
	global_load_lds_dwordx4 v[224:225], off
	s_waitcnt vmcnt(8)
	s_waitcnt lgkmcnt(0)
	s_setprio 1
	s_barrier
	v_mfma_f32_16x16x32_bf16 v[64:67], v[144:147], v[184:187], v[64:67]
	v_mfma_f32_16x16x32_bf16 v[60:63], v[152:155], v[184:187], v[60:63]
	v_mfma_f32_16x16x32_bf16 v[48:51], v[144:147], v[192:195], v[48:51]
	v_mfma_f32_16x16x32_bf16 v[44:47], v[152:155], v[192:195], v[44:47]
	v_mfma_f32_16x16x32_bf16 v[32:35], v[144:147], v[204:207], v[32:35]
	v_mfma_f32_16x16x32_bf16 v[28:31], v[152:155], v[204:207], v[28:31]
	v_mfma_f32_16x16x32_bf16 v[16:19], v[144:147], v[212:215], v[16:19]
	v_mfma_f32_16x16x32_bf16 v[12:15], v[152:155], v[212:215], v[12:15]
	v_mfma_f32_16x16x32_bf16 v[64:67], v[148:151], v[188:191], v[64:67]
	v_mfma_f32_16x16x32_bf16 v[60:63], v[164:167], v[188:191], v[60:63]
	v_mfma_f32_16x16x32_bf16 v[48:51], v[148:151], v[200:203], v[48:51]
	v_mfma_f32_16x16x32_bf16 v[44:47], v[164:167], v[200:203], v[44:47]
	v_mfma_f32_16x16x32_bf16 v[32:35], v[148:151], v[208:211], v[32:35]
	v_mfma_f32_16x16x32_bf16 v[28:31], v[164:167], v[208:211], v[28:31]
	v_mfma_f32_16x16x32_bf16 v[16:19], v[148:151], v[216:219], v[16:19]
	v_mfma_f32_16x16x32_bf16 v[12:15], v[164:167], v[216:219], v[12:15]
	v_mfma_f32_16x16x32_bf16 v[56:59], v[168:171], v[184:187], v[56:59]
	v_mfma_f32_16x16x32_bf16 v[52:55], v[176:179], v[184:187], v[52:55]
	v_mfma_f32_16x16x32_bf16 v[40:43], v[168:171], v[192:195], v[40:43]
	v_mfma_f32_16x16x32_bf16 v[36:39], v[176:179], v[192:195], v[36:39]
	v_mfma_f32_16x16x32_bf16 v[24:27], v[168:171], v[204:207], v[24:27]
	v_mfma_f32_16x16x32_bf16 v[20:23], v[176:179], v[204:207], v[20:23]
	v_mfma_f32_16x16x32_bf16 v[8:11], v[168:171], v[212:215], v[8:11]
	v_mfma_f32_16x16x32_bf16 v[4:7], v[176:179], v[212:215], v[4:7]
	v_mfma_f32_16x16x32_bf16 v[56:59], v[172:175], v[188:191], v[56:59]
	v_mfma_f32_16x16x32_bf16 v[52:55], v[180:183], v[188:191], v[52:55]
	v_mfma_f32_16x16x32_bf16 v[40:43], v[172:175], v[200:203], v[40:43]
	v_mfma_f32_16x16x32_bf16 v[36:39], v[180:183], v[200:203], v[36:39]
	v_mfma_f32_16x16x32_bf16 v[24:27], v[172:175], v[208:211], v[24:27]
	v_mfma_f32_16x16x32_bf16 v[20:23], v[180:183], v[208:211], v[20:23]
	v_mfma_f32_16x16x32_bf16 v[8:11], v[172:175], v[216:219], v[8:11]
	v_mfma_f32_16x16x32_bf16 v[4:7], v[180:183], v[216:219], v[4:7]
	s_barrier
	s_setprio 0
	s_add_i32 s0, 0, 0x18000
	v_add_u32_e32 v158, s0, v159
	s_add_i32 s6, 0, 0x1c000
	ds_read_b128 v[144:147], v158
	ds_read_b128 v[148:151], v158 offset:1024
	ds_read_b128 v[152:155], v158 offset:2048
	ds_read_b128 v[164:167], v158 offset:3072
	v_add_u32_e32 v158, s6, v159
	ds_read_b128 v[168:171], v158
	ds_read_b128 v[172:175], v158 offset:1024
	ds_read_b128 v[176:179], v158 offset:2048
	ds_read_b128 v[180:183], v158 offset:3072
	s_add_u32 s34, s34, 0x80000
	s_addc_u32 s35, s35, 0
	s_mov_b32 m0, s53
	v_lshl_add_u64 v[226:227], s[34:35], 0, v[138:139]
	ds_read_b128 v[184:187], v163 offset:32768
	ds_read_b128 v[188:191], v163 offset:33792
	ds_read_b128 v[192:195], v163 offset:34816
	ds_read_b128 v[200:203], v163 offset:35840
	ds_read_b128 v[204:207], v163 offset:36864
	ds_read_b128 v[208:211], v163 offset:37888
	ds_read_b128 v[212:215], v163 offset:38912
	ds_read_b128 v[216:219], v163 offset:39936
	global_load_lds_dwordx4 v[226:227], off
	v_lshl_add_u64 v[226:227], s[34:35], 0, v[134:135]
	s_mov_b32 m0, s60
	s_nop 0
	global_load_lds_dwordx4 v[226:227], off
	s_waitcnt vmcnt(8)
	s_waitcnt lgkmcnt(0)
	s_setprio 1
	s_barrier
	v_mfma_f32_16x16x32_bf16 v[128:131], v[144:147], v[184:187], v[128:131]
	v_mfma_f32_16x16x32_bf16 v[124:127], v[152:155], v[184:187], v[124:127]
	v_mfma_f32_16x16x32_bf16 v[112:115], v[144:147], v[192:195], v[112:115]
	v_mfma_f32_16x16x32_bf16 v[108:111], v[152:155], v[192:195], v[108:111]
	v_mfma_f32_16x16x32_bf16 v[96:99], v[144:147], v[204:207], v[96:99]
	v_mfma_f32_16x16x32_bf16 v[92:95], v[152:155], v[204:207], v[92:95]
	v_mfma_f32_16x16x32_bf16 v[80:83], v[144:147], v[212:215], v[80:83]
	v_mfma_f32_16x16x32_bf16 v[76:79], v[152:155], v[212:215], v[76:79]
	v_mfma_f32_16x16x32_bf16 v[128:131], v[148:151], v[188:191], v[128:131]
	v_mfma_f32_16x16x32_bf16 v[124:127], v[164:167], v[188:191], v[124:127]
	v_mfma_f32_16x16x32_bf16 v[112:115], v[148:151], v[200:203], v[112:115]
	v_mfma_f32_16x16x32_bf16 v[108:111], v[164:167], v[200:203], v[108:111]
	v_mfma_f32_16x16x32_bf16 v[96:99], v[148:151], v[208:211], v[96:99]
	v_mfma_f32_16x16x32_bf16 v[92:95], v[164:167], v[208:211], v[92:95]
	v_mfma_f32_16x16x32_bf16 v[80:83], v[148:151], v[216:219], v[80:83]
	v_mfma_f32_16x16x32_bf16 v[76:79], v[164:167], v[216:219], v[76:79]
	v_mfma_f32_16x16x32_bf16 v[120:123], v[168:171], v[184:187], v[120:123]
	v_mfma_f32_16x16x32_bf16 v[116:119], v[176:179], v[184:187], v[116:119]
	v_mfma_f32_16x16x32_bf16 v[104:107], v[168:171], v[192:195], v[104:107]
	v_mfma_f32_16x16x32_bf16 v[100:103], v[176:179], v[192:195], v[100:103]
	v_mfma_f32_16x16x32_bf16 v[88:91], v[168:171], v[204:207], v[88:91]
	v_mfma_f32_16x16x32_bf16 v[84:87], v[176:179], v[204:207], v[84:87]
	v_mfma_f32_16x16x32_bf16 v[72:75], v[168:171], v[212:215], v[72:75]
	v_mfma_f32_16x16x32_bf16 v[68:71], v[176:179], v[212:215], v[68:71]
	v_mfma_f32_16x16x32_bf16 v[120:123], v[172:175], v[188:191], v[120:123]
	v_mfma_f32_16x16x32_bf16 v[116:119], v[180:183], v[188:191], v[116:119]
	v_mfma_f32_16x16x32_bf16 v[104:107], v[172:175], v[200:203], v[104:107]
	v_mfma_f32_16x16x32_bf16 v[100:103], v[180:183], v[200:203], v[100:103]
	v_mfma_f32_16x16x32_bf16 v[88:91], v[172:175], v[208:211], v[88:91]
	v_mfma_f32_16x16x32_bf16 v[84:87], v[180:183], v[208:211], v[84:87]
	v_mfma_f32_16x16x32_bf16 v[72:75], v[172:175], v[216:219], v[72:75]
	v_mfma_f32_16x16x32_bf16 v[68:71], v[180:183], v[216:219], v[68:71]
	s_barrier
	s_setprio 0
	s_add_i32 s0, s0, s46
	v_lshl_add_u64 v[156:157], v[156:157], 0, s[90:91]
	s_mov_b32 m0, s0
	ds_read_b128 v[184:187], v163 offset:49152
	ds_read_b128 v[188:191], v163 offset:50176
	ds_read_b128 v[192:195], v163 offset:51200
	ds_read_b128 v[200:203], v163 offset:52224
	ds_read_b128 v[204:207], v163 offset:53248
	ds_read_b128 v[208:211], v163 offset:54272
	ds_read_b128 v[212:215], v163 offset:55296
	ds_read_b128 v[216:219], v163 offset:56320
	global_load_lds_dwordx4 v[156:157], off
	s_add_i32 m0, s0, 0x2000
	s_add_u32 s30, s30, 0x80080
	v_lshl_add_u64 v[156:157], v[220:221], 0, s[90:91]
	s_addc_u32 s31, s31, 0
	s_add_i32 s0, s6, s46
	global_load_lds_dwordx4 v[156:157], off
	v_lshl_add_u64 v[156:157], s[30:31], 0, v[136:137]
	s_mov_b32 m0, s0
	s_nop 0
	global_load_lds_dwordx4 v[156:157], off
	v_lshl_add_u64 v[156:157], s[30:31], 0, v[132:133]
	s_add_i32 m0, s0, 0x2000
	s_nop 0
	global_load_lds_dwordx4 v[156:157], off
	v_lshl_add_u64 v[156:157], v[222:223], 0, s[90:91]
	s_mov_b32 m0, s62
	s_nop 0
	global_load_lds_dwordx4 v[156:157], off
	v_lshl_add_u64 v[156:157], v[224:225], 0, s[90:91]
	s_mov_b32 m0, s51
	s_nop 0
	global_load_lds_dwordx4 v[156:157], off
	s_waitcnt vmcnt(8)
	s_waitcnt lgkmcnt(0)
	s_setprio 1
	s_barrier
	v_mfma_f32_16x16x32_bf16 v[64:67], v[144:147], v[184:187], v[64:67]
	v_mfma_f32_16x16x32_bf16 v[60:63], v[152:155], v[184:187], v[60:63]
	v_mfma_f32_16x16x32_bf16 v[48:51], v[144:147], v[192:195], v[48:51]
	v_mfma_f32_16x16x32_bf16 v[44:47], v[152:155], v[192:195], v[44:47]
	v_mfma_f32_16x16x32_bf16 v[32:35], v[144:147], v[204:207], v[32:35]
	v_mfma_f32_16x16x32_bf16 v[28:31], v[152:155], v[204:207], v[28:31]
	v_mfma_f32_16x16x32_bf16 v[16:19], v[144:147], v[212:215], v[16:19]
	v_mfma_f32_16x16x32_bf16 v[12:15], v[152:155], v[212:215], v[12:15]
	v_mfma_f32_16x16x32_bf16 v[64:67], v[148:151], v[188:191], v[64:67]
	v_mfma_f32_16x16x32_bf16 v[60:63], v[164:167], v[188:191], v[60:63]
	v_mfma_f32_16x16x32_bf16 v[48:51], v[148:151], v[200:203], v[48:51]
	v_mfma_f32_16x16x32_bf16 v[44:47], v[164:167], v[200:203], v[44:47]
	v_mfma_f32_16x16x32_bf16 v[32:35], v[148:151], v[208:211], v[32:35]
	v_mfma_f32_16x16x32_bf16 v[28:31], v[164:167], v[208:211], v[28:31]
	v_mfma_f32_16x16x32_bf16 v[16:19], v[148:151], v[216:219], v[16:19]
	v_mfma_f32_16x16x32_bf16 v[12:15], v[164:167], v[216:219], v[12:15]
	v_mfma_f32_16x16x32_bf16 v[56:59], v[168:171], v[184:187], v[56:59]
	v_mfma_f32_16x16x32_bf16 v[52:55], v[176:179], v[184:187], v[52:55]
	v_mfma_f32_16x16x32_bf16 v[40:43], v[168:171], v[192:195], v[40:43]
	v_mfma_f32_16x16x32_bf16 v[36:39], v[176:179], v[192:195], v[36:39]
	v_mfma_f32_16x16x32_bf16 v[24:27], v[168:171], v[204:207], v[24:27]
	v_mfma_f32_16x16x32_bf16 v[20:23], v[176:179], v[204:207], v[20:23]
	v_mfma_f32_16x16x32_bf16 v[8:11], v[168:171], v[212:215], v[8:11]
	v_mfma_f32_16x16x32_bf16 v[4:7], v[176:179], v[212:215], v[4:7]
	v_mfma_f32_16x16x32_bf16 v[56:59], v[172:175], v[188:191], v[56:59]
	v_mfma_f32_16x16x32_bf16 v[52:55], v[180:183], v[188:191], v[52:55]
	v_mfma_f32_16x16x32_bf16 v[40:43], v[172:175], v[200:203], v[40:43]
	v_mfma_f32_16x16x32_bf16 v[36:39], v[180:183], v[200:203], v[36:39]
	v_mfma_f32_16x16x32_bf16 v[24:27], v[172:175], v[208:211], v[24:27]
	v_mfma_f32_16x16x32_bf16 v[20:23], v[180:183], v[208:211], v[20:23]
	v_mfma_f32_16x16x32_bf16 v[8:11], v[172:175], v[216:219], v[8:11]
	v_mfma_f32_16x16x32_bf16 v[4:7], v[180:183], v[216:219], v[4:7]
	s_barrier
	s_setprio 0
	s_add_i32 s55, s55, 2
	s_add_u32 s36, s36, 0x100
	s_addc_u32 s37, s37, 0
	s_add_u32 s38, s38, 0x100
	s_addc_u32 s39, s39, 0
	s_cmp_gt_u32 s55, 29
	s_cbranch_scc0 .LBB0_297
	s_and_b64 vcc, exec, s[22:23]
	s_cbranch_vccz .LBB0_300
	s_barrier

.LBB0_336:
	s_add_u32 s0, s36, 0xfff80080
	s_addc_u32 s6, s37, -1
	s_add_i32 s49, 0, 0x10000
	s_cmp_eq_u32 s50, 28
	s_cselect_b32 s35, s24, s6
	s_cselect_b32 s34, s25, s0
	v_add_u32_e32 v156, s49, v159
	s_cselect_b32 s31, s33, s39
	s_cselect_b32 s30, s40, s38
	s_add_i32 s0, 0, 0x14000
	ds_read_b128 v[144:147], v156
	ds_read_b128 v[148:151], v156 offset:1024
	ds_read_b128 v[152:155], v156 offset:2048
	ds_read_b128 v[164:167], v156 offset:3072
	v_add_u32_e32 v156, s0, v159
	ds_read_b128 v[168:171], v156
	ds_read_b128 v[172:175], v156 offset:1024
	ds_read_b128 v[176:179], v156 offset:2048
	ds_read_b128 v[180:183], v156 offset:3072
	v_lshl_add_u64 v[156:157], s[36:37], 0, v[140:141]
	s_add_i32 m0, s45, 0xc000
	ds_read_b128 v[184:187], v163
	ds_read_b128 v[188:191], v163 offset:1024
	ds_read_b128 v[192:195], v163 offset:2048
	ds_read_b128 v[200:203], v163 offset:3072
	ds_read_b128 v[204:207], v163 offset:4096
	ds_read_b128 v[208:211], v163 offset:5120
	ds_read_b128 v[212:215], v163 offset:6144
	ds_read_b128 v[216:219], v163 offset:7168
	global_load_lds_dwordx4 v[156:157], off
	v_lshl_add_u64 v[156:157], s[36:37], 0, v[142:143]
	s_add_i32 m0, s45, 0xe000
	s_nop 0
	global_load_lds_dwordx4 v[156:157], off
	s_waitcnt vmcnt(8)
	s_waitcnt lgkmcnt(0)
	s_setprio 1
	s_barrier
	v_mfma_f32_16x16x32_bf16 v[128:131], v[144:147], v[184:187], v[128:131]
	v_mfma_f32_16x16x32_bf16 v[124:127], v[152:155], v[184:187], v[124:127]
	v_mfma_f32_16x16x32_bf16 v[112:115], v[144:147], v[192:195], v[112:115]
	v_mfma_f32_16x16x32_bf16 v[108:111], v[152:155], v[192:195], v[108:111]
	v_mfma_f32_16x16x32_bf16 v[96:99], v[144:147], v[204:207], v[96:99]
	v_mfma_f32_16x16x32_bf16 v[92:95], v[152:155], v[204:207], v[92:95]
	v_mfma_f32_16x16x32_bf16 v[80:83], v[144:147], v[212:215], v[80:83]
	v_mfma_f32_16x16x32_bf16 v[76:79], v[152:155], v[212:215], v[76:79]
	v_mfma_f32_16x16x32_bf16 v[128:131], v[148:151], v[188:191], v[128:131]
	v_mfma_f32_16x16x32_bf16 v[124:127], v[164:167], v[188:191], v[124:127]
	v_mfma_f32_16x16x32_bf16 v[112:115], v[148:151], v[200:203], v[112:115]
	v_mfma_f32_16x16x32_bf16 v[108:111], v[164:167], v[200:203], v[108:111]
	v_mfma_f32_16x16x32_bf16 v[96:99], v[148:151], v[208:211], v[96:99]
	v_mfma_f32_16x16x32_bf16 v[92:95], v[164:167], v[208:211], v[92:95]
	v_mfma_f32_16x16x32_bf16 v[80:83], v[148:151], v[216:219], v[80:83]
	v_mfma_f32_16x16x32_bf16 v[76:79], v[164:167], v[216:219], v[76:79]
	v_mfma_f32_16x16x32_bf16 v[120:123], v[168:171], v[184:187], v[120:123]
	v_mfma_f32_16x16x32_bf16 v[116:119], v[176:179], v[184:187], v[116:119]
	v_mfma_f32_16x16x32_bf16 v[104:107], v[168:171], v[192:195], v[104:107]
	v_mfma_f32_16x16x32_bf16 v[100:103], v[176:179], v[192:195], v[100:103]
	v_mfma_f32_16x16x32_bf16 v[88:91], v[168:171], v[204:207], v[88:91]
	v_mfma_f32_16x16x32_bf16 v[84:87], v[176:179], v[204:207], v[84:87]
	v_mfma_f32_16x16x32_bf16 v[72:75], v[168:171], v[212:215], v[72:75]
	v_mfma_f32_16x16x32_bf16 v[68:71], v[176:179], v[212:215], v[68:71]
	v_mfma_f32_16x16x32_bf16 v[120:123], v[172:175], v[188:191], v[120:123]
	v_mfma_f32_16x16x32_bf16 v[116:119], v[180:183], v[188:191], v[116:119]
	v_mfma_f32_16x16x32_bf16 v[104:107], v[172:175], v[200:203], v[104:107]
	v_mfma_f32_16x16x32_bf16 v[100:103], v[180:183], v[200:203], v[100:103]
	v_mfma_f32_16x16x32_bf16 v[88:91], v[172:175], v[208:211], v[88:91]
	v_mfma_f32_16x16x32_bf16 v[84:87], v[180:183], v[208:211], v[84:87]
	v_mfma_f32_16x16x32_bf16 v[72:75], v[172:175], v[216:219], v[72:75]
	v_mfma_f32_16x16x32_bf16 v[68:71], v[180:183], v[216:219], v[68:71]
	s_barrier
	s_setprio 0
	s_add_i32 s6, s49, s47
	v_lshl_add_u64 v[156:157], s[30:31], 0, v[136:137]
	s_mov_b32 m0, s6
	ds_read_b128 v[184:187], v163 offset:16384
	ds_read_b128 v[188:191], v163 offset:17408
	ds_read_b128 v[192:195], v163 offset:18432
	ds_read_b128 v[200:203], v163 offset:19456
	ds_read_b128 v[204:207], v163 offset:20480
	ds_read_b128 v[208:211], v163 offset:21504
	ds_read_b128 v[212:215], v163 offset:22528
	ds_read_b128 v[216:219], v163 offset:23552
	global_load_lds_dwordx4 v[156:157], off
	s_add_i32 m0, s6, 0x2000
	s_add_u32 s54, s30, 0x80000
	v_lshl_add_u64 v[220:221], s[30:31], 0, v[132:133]
	s_addc_u32 s55, s31, 0
	s_add_i32 s0, s0, s47
	global_load_lds_dwordx4 v[220:221], off
	v_lshl_add_u64 v[222:223], s[54:55], 0, v[136:137]
	s_mov_b32 m0, s0
	v_lshl_add_u64 v[224:225], s[34:35], 0, v[134:135]
	global_load_lds_dwordx4 v[222:223], off
	v_lshl_add_u64 v[222:223], s[54:55], 0, v[132:133]
	s_add_i32 m0, s0, 0x2000
	s_nop 0
	global_load_lds_dwordx4 v[222:223], off
	v_lshl_add_u64 v[222:223], s[34:35], 0, v[138:139]
	s_mov_b32 m0, s45
	s_nop 0
	global_load_lds_dwordx4 v[222:223], off
	s_mov_b32 m0, s61
	s_nop 0
	global_load_lds_dwordx4 v[224:225], off
	s_waitcnt vmcnt(8)
	s_waitcnt lgkmcnt(0)
	s_setprio 1
	s_barrier
	v_mfma_f32_16x16x32_bf16 v[64:67], v[144:147], v[184:187], v[64:67]
	v_mfma_f32_16x16x32_bf16 v[60:63], v[152:155], v[184:187], v[60:63]
	v_mfma_f32_16x16x32_bf16 v[48:51], v[144:147], v[192:195], v[48:51]
	v_mfma_f32_16x16x32_bf16 v[44:47], v[152:155], v[192:195], v[44:47]
	v_mfma_f32_16x16x32_bf16 v[32:35], v[144:147], v[204:207], v[32:35]
	v_mfma_f32_16x16x32_bf16 v[28:31], v[152:155], v[204:207], v[28:31]
	v_mfma_f32_16x16x32_bf16 v[16:19], v[144:147], v[212:215], v[16:19]
	v_mfma_f32_16x16x32_bf16 v[12:15], v[152:155], v[212:215], v[12:15]
	v_mfma_f32_16x16x32_bf16 v[64:67], v[148:151], v[188:191], v[64:67]
	v_mfma_f32_16x16x32_bf16 v[60:63], v[164:167], v[188:191], v[60:63]
	v_mfma_f32_16x16x32_bf16 v[48:51], v[148:151], v[200:203], v[48:51]
	v_mfma_f32_16x16x32_bf16 v[44:47], v[164:167], v[200:203], v[44:47]
	v_mfma_f32_16x16x32_bf16 v[32:35], v[148:151], v[208:211], v[32:35]
	v_mfma_f32_16x16x32_bf16 v[28:31], v[164:167], v[208:211], v[28:31]
	v_mfma_f32_16x16x32_bf16 v[16:19], v[148:151], v[216:219], v[16:19]
	v_mfma_f32_16x16x32_bf16 v[12:15], v[164:167], v[216:219], v[12:15]
	v_mfma_f32_16x16x32_bf16 v[56:59], v[168:171], v[184:187], v[56:59]
	v_mfma_f32_16x16x32_bf16 v[52:55], v[176:179], v[184:187], v[52:55]
	v_mfma_f32_16x16x32_bf16 v[40:43], v[168:171], v[192:195], v[40:43]
	v_mfma_f32_16x16x32_bf16 v[36:39], v[176:179], v[192:195], v[36:39]
	v_mfma_f32_16x16x32_bf16 v[24:27], v[168:171], v[204:207], v[24:27]
	v_mfma_f32_16x16x32_bf16 v[20:23], v[176:179], v[204:207], v[20:23]
	v_mfma_f32_16x16x32_bf16 v[8:11], v[168:171], v[212:215], v[8:11]
	v_mfma_f32_16x16x32_bf16 v[4:7], v[176:179], v[212:215], v[4:7]
	v_mfma_f32_16x16x32_bf16 v[56:59], v[172:175], v[188:191], v[56:59]
	v_mfma_f32_16x16x32_bf16 v[52:55], v[180:183], v[188:191], v[52:55]
	v_mfma_f32_16x16x32_bf16 v[40:43], v[172:175], v[200:203], v[40:43]
	v_mfma_f32_16x16x32_bf16 v[36:39], v[180:183], v[200:203], v[36:39]
	v_mfma_f32_16x16x32_bf16 v[24:27], v[172:175], v[208:211], v[24:27]
	v_mfma_f32_16x16x32_bf16 v[20:23], v[180:183], v[208:211], v[20:23]
	v_mfma_f32_16x16x32_bf16 v[8:11], v[172:175], v[216:219], v[8:11]
	v_mfma_f32_16x16x32_bf16 v[4:7], v[180:183], v[216:219], v[4:7]
	s_barrier
	s_setprio 0
	s_add_i32 s0, 0, 0x18000
	v_add_u32_e32 v158, s0, v159
	s_add_i32 s6, 0, 0x1c000
	ds_read_b128 v[144:147], v158
	ds_read_b128 v[148:151], v158 offset:1024
	ds_read_b128 v[152:155], v158 offset:2048
	ds_read_b128 v[164:167], v158 offset:3072
	v_add_u32_e32 v158, s6, v159
	ds_read_b128 v[168:171], v158
	ds_read_b128 v[172:175], v158 offset:1024
	ds_read_b128 v[176:179], v158 offset:2048
	ds_read_b128 v[180:183], v158 offset:3072
	s_add_u32 s34, s34, 0x80000
	s_addc_u32 s35, s35, 0
	s_mov_b32 m0, s62
	v_lshl_add_u64 v[226:227], s[34:35], 0, v[138:139]
	ds_read_b128 v[184:187], v163 offset:32768
	ds_read_b128 v[188:191], v163 offset:33792
	ds_read_b128 v[192:195], v163 offset:34816
	ds_read_b128 v[200:203], v163 offset:35840
	ds_read_b128 v[204:207], v163 offset:36864
	ds_read_b128 v[208:211], v163 offset:37888
	ds_read_b128 v[212:215], v163 offset:38912
	ds_read_b128 v[216:219], v163 offset:39936
	global_load_lds_dwordx4 v[226:227], off
	v_lshl_add_u64 v[226:227], s[34:35], 0, v[134:135]
	s_mov_b32 m0, s63
	s_nop 0
	global_load_lds_dwordx4 v[226:227], off
	s_waitcnt vmcnt(8)
	s_waitcnt lgkmcnt(0)
	s_setprio 1
	s_barrier
	v_mfma_f32_16x16x32_bf16 v[128:131], v[144:147], v[184:187], v[128:131]
	v_mfma_f32_16x16x32_bf16 v[124:127], v[152:155], v[184:187], v[124:127]
	v_mfma_f32_16x16x32_bf16 v[112:115], v[144:147], v[192:195], v[112:115]
	v_mfma_f32_16x16x32_bf16 v[108:111], v[152:155], v[192:195], v[108:111]
	v_mfma_f32_16x16x32_bf16 v[96:99], v[144:147], v[204:207], v[96:99]
	v_mfma_f32_16x16x32_bf16 v[92:95], v[152:155], v[204:207], v[92:95]
	v_mfma_f32_16x16x32_bf16 v[80:83], v[144:147], v[212:215], v[80:83]
	v_mfma_f32_16x16x32_bf16 v[76:79], v[152:155], v[212:215], v[76:79]
	v_mfma_f32_16x16x32_bf16 v[128:131], v[148:151], v[188:191], v[128:131]
	v_mfma_f32_16x16x32_bf16 v[124:127], v[164:167], v[188:191], v[124:127]
	v_mfma_f32_16x16x32_bf16 v[112:115], v[148:151], v[200:203], v[112:115]
	v_mfma_f32_16x16x32_bf16 v[108:111], v[164:167], v[200:203], v[108:111]
	v_mfma_f32_16x16x32_bf16 v[96:99], v[148:151], v[208:211], v[96:99]
	v_mfma_f32_16x16x32_bf16 v[92:95], v[164:167], v[208:211], v[92:95]
	v_mfma_f32_16x16x32_bf16 v[80:83], v[148:151], v[216:219], v[80:83]
	v_mfma_f32_16x16x32_bf16 v[76:79], v[164:167], v[216:219], v[76:79]
	v_mfma_f32_16x16x32_bf16 v[120:123], v[168:171], v[184:187], v[120:123]
	v_mfma_f32_16x16x32_bf16 v[116:119], v[176:179], v[184:187], v[116:119]
	v_mfma_f32_16x16x32_bf16 v[104:107], v[168:171], v[192:195], v[104:107]
	v_mfma_f32_16x16x32_bf16 v[100:103], v[176:179], v[192:195], v[100:103]
	v_mfma_f32_16x16x32_bf16 v[88:91], v[168:171], v[204:207], v[88:91]
	v_mfma_f32_16x16x32_bf16 v[84:87], v[176:179], v[204:207], v[84:87]
	v_mfma_f32_16x16x32_bf16 v[72:75], v[168:171], v[212:215], v[72:75]
	v_mfma_f32_16x16x32_bf16 v[68:71], v[176:179], v[212:215], v[68:71]
	v_mfma_f32_16x16x32_bf16 v[120:123], v[172:175], v[188:191], v[120:123]
	v_mfma_f32_16x16x32_bf16 v[116:119], v[180:183], v[188:191], v[116:119]
	v_mfma_f32_16x16x32_bf16 v[104:107], v[172:175], v[200:203], v[104:107]
	v_mfma_f32_16x16x32_bf16 v[100:103], v[180:183], v[200:203], v[100:103]
	v_mfma_f32_16x16x32_bf16 v[88:91], v[172:175], v[208:211], v[88:91]
	v_mfma_f32_16x16x32_bf16 v[84:87], v[180:183], v[208:211], v[84:87]
	v_mfma_f32_16x16x32_bf16 v[72:75], v[172:175], v[216:219], v[72:75]
	v_mfma_f32_16x16x32_bf16 v[68:71], v[180:183], v[216:219], v[68:71]
	s_barrier
	s_setprio 0
	s_add_i32 s0, s0, s47
	v_lshl_add_u64 v[156:157], v[156:157], 0, s[90:91]
	s_mov_b32 m0, s0
	ds_read_b128 v[184:187], v163 offset:49152
	ds_read_b128 v[188:191], v163 offset:50176
	ds_read_b128 v[192:195], v163 offset:51200
	ds_read_b128 v[200:203], v163 offset:52224
	ds_read_b128 v[204:207], v163 offset:53248
	ds_read_b128 v[208:211], v163 offset:54272
	ds_read_b128 v[212:215], v163 offset:55296
	ds_read_b128 v[216:219], v163 offset:56320
	global_load_lds_dwordx4 v[156:157], off
	s_add_i32 m0, s0, 0x2000
	s_add_u32 s30, s30, 0x80080
	v_lshl_add_u64 v[156:157], v[220:221], 0, s[90:91]
	s_addc_u32 s31, s31, 0
	s_add_i32 s0, s6, s47
	global_load_lds_dwordx4 v[156:157], off
	v_lshl_add_u64 v[156:157], s[30:31], 0, v[136:137]
	s_mov_b32 m0, s0
	s_nop 0
	global_load_lds_dwordx4 v[156:157], off
	v_lshl_add_u64 v[156:157], s[30:31], 0, v[132:133]
	s_add_i32 m0, s0, 0x2000
	s_nop 0
	global_load_lds_dwordx4 v[156:157], off
	v_lshl_add_u64 v[156:157], v[222:223], 0, s[90:91]
	s_mov_b32 m0, s51
	s_nop 0
	global_load_lds_dwordx4 v[156:157], off
	v_lshl_add_u64 v[156:157], v[224:225], 0, s[90:91]
	s_mov_b32 m0, s4
	s_nop 0
	global_load_lds_dwordx4 v[156:157], off
	s_waitcnt vmcnt(8)
	s_waitcnt lgkmcnt(0)
	s_setprio 1
	s_barrier
	v_mfma_f32_16x16x32_bf16 v[64:67], v[144:147], v[184:187], v[64:67]
	v_mfma_f32_16x16x32_bf16 v[60:63], v[152:155], v[184:187], v[60:63]
	v_mfma_f32_16x16x32_bf16 v[48:51], v[144:147], v[192:195], v[48:51]
	v_mfma_f32_16x16x32_bf16 v[44:47], v[152:155], v[192:195], v[44:47]
	v_mfma_f32_16x16x32_bf16 v[32:35], v[144:147], v[204:207], v[32:35]
	v_mfma_f32_16x16x32_bf16 v[28:31], v[152:155], v[204:207], v[28:31]
	v_mfma_f32_16x16x32_bf16 v[16:19], v[144:147], v[212:215], v[16:19]
	v_mfma_f32_16x16x32_bf16 v[12:15], v[152:155], v[212:215], v[12:15]
	v_mfma_f32_16x16x32_bf16 v[64:67], v[148:151], v[188:191], v[64:67]
	v_mfma_f32_16x16x32_bf16 v[60:63], v[164:167], v[188:191], v[60:63]
	v_mfma_f32_16x16x32_bf16 v[48:51], v[148:151], v[200:203], v[48:51]
	v_mfma_f32_16x16x32_bf16 v[44:47], v[164:167], v[200:203], v[44:47]
	v_mfma_f32_16x16x32_bf16 v[32:35], v[148:151], v[208:211], v[32:35]
	v_mfma_f32_16x16x32_bf16 v[28:31], v[164:167], v[208:211], v[28:31]
	v_mfma_f32_16x16x32_bf16 v[16:19], v[148:151], v[216:219], v[16:19]
	v_mfma_f32_16x16x32_bf16 v[12:15], v[164:167], v[216:219], v[12:15]
	v_mfma_f32_16x16x32_bf16 v[56:59], v[168:171], v[184:187], v[56:59]
	v_mfma_f32_16x16x32_bf16 v[52:55], v[176:179], v[184:187], v[52:55]
	v_mfma_f32_16x16x32_bf16 v[40:43], v[168:171], v[192:195], v[40:43]
	v_mfma_f32_16x16x32_bf16 v[36:39], v[176:179], v[192:195], v[36:39]
	v_mfma_f32_16x16x32_bf16 v[24:27], v[168:171], v[204:207], v[24:27]
	v_mfma_f32_16x16x32_bf16 v[20:23], v[176:179], v[204:207], v[20:23]
	v_mfma_f32_16x16x32_bf16 v[8:11], v[168:171], v[212:215], v[8:11]
	v_mfma_f32_16x16x32_bf16 v[4:7], v[176:179], v[212:215], v[4:7]
	v_mfma_f32_16x16x32_bf16 v[56:59], v[172:175], v[188:191], v[56:59]
	v_mfma_f32_16x16x32_bf16 v[52:55], v[180:183], v[188:191], v[52:55]
	v_mfma_f32_16x16x32_bf16 v[40:43], v[172:175], v[200:203], v[40:43]
	v_mfma_f32_16x16x32_bf16 v[36:39], v[180:183], v[200:203], v[36:39]
	v_mfma_f32_16x16x32_bf16 v[24:27], v[172:175], v[208:211], v[24:27]
	v_mfma_f32_16x16x32_bf16 v[20:23], v[180:183], v[208:211], v[20:23]
	v_mfma_f32_16x16x32_bf16 v[8:11], v[172:175], v[216:219], v[8:11]
	v_mfma_f32_16x16x32_bf16 v[4:7], v[180:183], v[216:219], v[4:7]
	s_barrier
	s_setprio 0
	s_add_i32 s50, s50, 2
	s_add_u32 s36, s36, 0x100
	s_addc_u32 s37, s37, 0
	s_add_u32 s38, s38, 0x100
	s_addc_u32 s39, s39, 0
	s_cmp_gt_u32 s50, 29
	s_cbranch_scc0 .LBB0_336
	s_and_b64 vcc, exec, s[22:23]
	s_cbranch_vccz .LBB0_339
	s_barrier

.LBB0_747:
	s_add_i32 s0, s6, 2
	s_add_u32 s25, s66, 0xfffc0080
	s_addc_u32 s29, s67, -1
	s_add_i32 s33, 0, 0x10000
	s_cmp_eq_u32 s13, s6
	s_cselect_b32 s35, s45, s29
	s_cselect_b32 s34, s44, s25
	v_add_u32_e32 v3, s33, v237
	s_cselect_b32 s31, s61, s24
	s_cselect_b32 s30, s60, s15
	s_add_i32 s6, 0, 0x14000
	ds_read_b128 v[146:149], v3
	ds_read_b128 v[150:153], v3 offset:1024
	ds_read_b128 v[154:157], v3 offset:2048
	ds_read_b128 v[158:161], v3 offset:3072
	v_add_u32_e32 v3, s6, v237
	ds_read_b128 v[162:165], v3
	ds_read_b128 v[166:169], v3 offset:1024
	ds_read_b128 v[170:173], v3 offset:2048
	ds_read_b128 v[174:177], v3 offset:3072
	v_lshl_add_u64 v[4:5], s[66:67], 0, v[142:143]
	s_add_i32 m0, s52, 0xc000
	ds_read_b128 v[178:181], v249
	ds_read_b128 v[182:185], v249 offset:1024
	ds_read_b128 v[186:189], v249 offset:2048
	ds_read_b128 v[190:193], v249 offset:3072
	ds_read_b128 v[200:203], v249 offset:4096
	ds_read_b128 v[204:207], v249 offset:5120
	ds_read_b128 v[208:211], v249 offset:6144
	ds_read_b128 v[212:215], v249 offset:7168
	global_load_lds_dwordx4 v[4:5], off
	v_lshl_add_u64 v[4:5], s[66:67], 0, v[144:145]
	s_add_i32 m0, s52, 0xe000
	s_nop 0
	global_load_lds_dwordx4 v[4:5], off
	s_waitcnt vmcnt(8)
	s_waitcnt lgkmcnt(0)
	s_setprio 1
	s_barrier
	v_mfma_f32_16x16x32_bf16 v[130:133], v[146:149], v[178:181], v[130:133]
	v_mfma_f32_16x16x32_bf16 v[126:129], v[154:157], v[178:181], v[126:129]
	v_mfma_f32_16x16x32_bf16 v[122:125], v[146:149], v[186:189], v[122:125]
	v_mfma_f32_16x16x32_bf16 v[118:121], v[154:157], v[186:189], v[118:121]
	v_mfma_f32_16x16x32_bf16 v[114:117], v[146:149], v[200:203], v[114:117]
	v_mfma_f32_16x16x32_bf16 v[110:113], v[154:157], v[200:203], v[110:113]
	v_mfma_f32_16x16x32_bf16 v[106:109], v[146:149], v[208:211], v[106:109]
	v_mfma_f32_16x16x32_bf16 v[102:105], v[154:157], v[208:211], v[102:105]
	v_mfma_f32_16x16x32_bf16 v[130:133], v[150:153], v[182:185], v[130:133]
	v_mfma_f32_16x16x32_bf16 v[126:129], v[158:161], v[182:185], v[126:129]
	v_mfma_f32_16x16x32_bf16 v[122:125], v[150:153], v[190:193], v[122:125]
	v_mfma_f32_16x16x32_bf16 v[118:121], v[158:161], v[190:193], v[118:121]
	v_mfma_f32_16x16x32_bf16 v[114:117], v[150:153], v[204:207], v[114:117]
	v_mfma_f32_16x16x32_bf16 v[110:113], v[158:161], v[204:207], v[110:113]
	v_mfma_f32_16x16x32_bf16 v[106:109], v[150:153], v[212:215], v[106:109]
	v_mfma_f32_16x16x32_bf16 v[102:105], v[158:161], v[212:215], v[102:105]
	v_mfma_f32_16x16x32_bf16 v[98:101], v[162:165], v[178:181], v[98:101]
	v_mfma_f32_16x16x32_bf16 v[94:97], v[170:173], v[178:181], v[94:97]
	v_mfma_f32_16x16x32_bf16 v[90:93], v[162:165], v[186:189], v[90:93]
	v_mfma_f32_16x16x32_bf16 v[86:89], v[170:173], v[186:189], v[86:89]
	v_mfma_f32_16x16x32_bf16 v[82:85], v[162:165], v[200:203], v[82:85]
	v_mfma_f32_16x16x32_bf16 v[78:81], v[170:173], v[200:203], v[78:81]
	v_mfma_f32_16x16x32_bf16 v[74:77], v[162:165], v[208:211], v[74:77]
	v_mfma_f32_16x16x32_bf16 v[70:73], v[170:173], v[208:211], v[70:73]
	v_mfma_f32_16x16x32_bf16 v[98:101], v[166:169], v[182:185], v[98:101]
	v_mfma_f32_16x16x32_bf16 v[94:97], v[174:177], v[182:185], v[94:97]
	v_mfma_f32_16x16x32_bf16 v[90:93], v[166:169], v[190:193], v[90:93]
	v_mfma_f32_16x16x32_bf16 v[86:89], v[174:177], v[190:193], v[86:89]
	v_mfma_f32_16x16x32_bf16 v[82:85], v[166:169], v[204:207], v[82:85]
	v_mfma_f32_16x16x32_bf16 v[78:81], v[174:177], v[204:207], v[78:81]
	v_mfma_f32_16x16x32_bf16 v[74:77], v[166:169], v[212:215], v[74:77]
	v_mfma_f32_16x16x32_bf16 v[70:73], v[174:177], v[212:215], v[70:73]
	s_barrier
	s_setprio 0
	s_add_i32 s25, s33, s47
	v_lshl_add_u64 v[194:195], s[30:31], 0, v[136:137]
	s_mov_b32 m0, s25
	ds_read_b128 v[178:181], v249 offset:16384
	ds_read_b128 v[182:185], v249 offset:17408
	ds_read_b128 v[186:189], v249 offset:18432
	ds_read_b128 v[190:193], v249 offset:19456
	ds_read_b128 v[200:203], v249 offset:20480
	ds_read_b128 v[204:207], v249 offset:21504
	ds_read_b128 v[208:211], v249 offset:22528
	ds_read_b128 v[212:215], v249 offset:23552
	global_load_lds_dwordx4 v[194:195], off
	s_add_i32 m0, s25, 0x2000
	s_add_u32 s36, s30, 0x40000
	v_lshl_add_u64 v[216:217], s[30:31], 0, v[140:141]
	s_addc_u32 s37, s31, 0
	s_add_i32 s6, s6, s47
	global_load_lds_dwordx4 v[216:217], off
	v_lshl_add_u64 v[4:5], s[36:37], 0, v[136:137]
	s_mov_b32 m0, s6
	v_lshl_add_u64 v[218:219], s[34:35], 0, v[134:135]
	global_load_lds_dwordx4 v[4:5], off
	v_lshl_add_u64 v[4:5], s[36:37], 0, v[140:141]
	s_add_i32 m0, s6, 0x2000
	v_lshl_add_u64 v[220:221], s[34:35], 0, v[138:139]
	global_load_lds_dwordx4 v[4:5], off
	s_mov_b32 m0, s52
	s_nop 0
	global_load_lds_dwordx4 v[218:219], off
	s_mov_b32 m0, s53
	s_nop 0
	global_load_lds_dwordx4 v[220:221], off
	s_waitcnt vmcnt(8)
	s_waitcnt lgkmcnt(0)
	s_setprio 1
	s_barrier
	v_mfma_f32_16x16x32_bf16 v[66:69], v[146:149], v[178:181], v[66:69]
	v_mfma_f32_16x16x32_bf16 v[62:65], v[154:157], v[178:181], v[62:65]
	v_mfma_f32_16x16x32_bf16 v[58:61], v[146:149], v[186:189], v[58:61]
	v_mfma_f32_16x16x32_bf16 v[54:57], v[154:157], v[186:189], v[54:57]
	v_mfma_f32_16x16x32_bf16 v[50:53], v[146:149], v[200:203], v[50:53]
	v_mfma_f32_16x16x32_bf16 v[46:49], v[154:157], v[200:203], v[46:49]
	v_mfma_f32_16x16x32_bf16 v[42:45], v[146:149], v[208:211], v[42:45]
	v_mfma_f32_16x16x32_bf16 v[38:41], v[154:157], v[208:211], v[38:41]
	v_mfma_f32_16x16x32_bf16 v[66:69], v[150:153], v[182:185], v[66:69]
	v_mfma_f32_16x16x32_bf16 v[62:65], v[158:161], v[182:185], v[62:65]
	v_mfma_f32_16x16x32_bf16 v[58:61], v[150:153], v[190:193], v[58:61]
	v_mfma_f32_16x16x32_bf16 v[54:57], v[158:161], v[190:193], v[54:57]
	v_mfma_f32_16x16x32_bf16 v[50:53], v[150:153], v[204:207], v[50:53]
	v_mfma_f32_16x16x32_bf16 v[46:49], v[158:161], v[204:207], v[46:49]
	v_mfma_f32_16x16x32_bf16 v[42:45], v[150:153], v[212:215], v[42:45]
	v_mfma_f32_16x16x32_bf16 v[38:41], v[158:161], v[212:215], v[38:41]
	v_mfma_f32_16x16x32_bf16 v[34:37], v[162:165], v[178:181], v[34:37]
	v_mfma_f32_16x16x32_bf16 v[30:33], v[170:173], v[178:181], v[30:33]
	v_mfma_f32_16x16x32_bf16 v[26:29], v[162:165], v[186:189], v[26:29]
	v_mfma_f32_16x16x32_bf16 v[22:25], v[170:173], v[186:189], v[22:25]
	v_mfma_f32_16x16x32_bf16 v[18:21], v[162:165], v[200:203], v[18:21]
	v_mfma_f32_16x16x32_bf16 v[14:17], v[170:173], v[200:203], v[14:17]
	v_mfma_f32_16x16x32_bf16 v[10:13], v[162:165], v[208:211], v[10:13]
	v_mfma_f32_16x16x32_bf16 v[4:7], v[170:173], v[208:211], v[6:9]
	v_mfma_f32_16x16x32_bf16 v[34:37], v[166:169], v[182:185], v[34:37]
	v_mfma_f32_16x16x32_bf16 v[30:33], v[174:177], v[182:185], v[30:33]
	v_mfma_f32_16x16x32_bf16 v[26:29], v[166:169], v[190:193], v[26:29]
	v_mfma_f32_16x16x32_bf16 v[22:25], v[174:177], v[190:193], v[22:25]
	v_mfma_f32_16x16x32_bf16 v[18:21], v[166:169], v[204:207], v[18:21]
	v_mfma_f32_16x16x32_bf16 v[14:17], v[174:177], v[204:207], v[14:17]
	v_mfma_f32_16x16x32_bf16 v[10:13], v[166:169], v[212:215], v[10:13]
	v_mfma_f32_16x16x32_bf16 v[4:7], v[174:177], v[212:215], v[4:7]
	s_barrier
	s_setprio 0
	s_add_i32 s6, 0, 0x18000
	v_add_u32_e32 v3, s6, v237
	s_add_i32 s25, 0, 0x1c000
	ds_read_b128 v[146:149], v3
	ds_read_b128 v[150:153], v3 offset:1024
	ds_read_b128 v[154:157], v3 offset:2048
	ds_read_b128 v[158:161], v3 offset:3072
	v_add_u32_e32 v3, s25, v237
	ds_read_b128 v[162:165], v3
	ds_read_b128 v[166:169], v3 offset:1024
	ds_read_b128 v[170:173], v3 offset:2048
	ds_read_b128 v[174:177], v3 offset:3072
	s_add_u32 s34, s34, 0x40000
	s_addc_u32 s35, s35, 0
	s_mov_b32 m0, s59
	v_lshl_add_u64 v[8:9], s[34:35], 0, v[134:135]
	ds_read_b128 v[178:181], v249 offset:32768
	ds_read_b128 v[182:185], v249 offset:33792
	ds_read_b128 v[186:189], v249 offset:34816
	ds_read_b128 v[190:193], v249 offset:35840
	ds_read_b128 v[200:203], v249 offset:36864
	ds_read_b128 v[204:207], v249 offset:37888
	ds_read_b128 v[208:211], v249 offset:38912
	ds_read_b128 v[212:215], v249 offset:39936
	global_load_lds_dwordx4 v[8:9], off
	v_lshl_add_u64 v[8:9], s[34:35], 0, v[138:139]
	s_mov_b32 m0, s63
	s_nop 0
	global_load_lds_dwordx4 v[8:9], off
	s_waitcnt vmcnt(8)
	s_waitcnt lgkmcnt(0)
	s_setprio 1
	s_barrier
	v_mfma_f32_16x16x32_bf16 v[130:133], v[146:149], v[178:181], v[130:133]
	v_mfma_f32_16x16x32_bf16 v[126:129], v[154:157], v[178:181], v[126:129]
	v_mfma_f32_16x16x32_bf16 v[122:125], v[146:149], v[186:189], v[122:125]
	v_mfma_f32_16x16x32_bf16 v[118:121], v[154:157], v[186:189], v[118:121]
	v_mfma_f32_16x16x32_bf16 v[114:117], v[146:149], v[200:203], v[114:117]
	v_mfma_f32_16x16x32_bf16 v[110:113], v[154:157], v[200:203], v[110:113]
	v_mfma_f32_16x16x32_bf16 v[106:109], v[146:149], v[208:211], v[106:109]
	v_mfma_f32_16x16x32_bf16 v[102:105], v[154:157], v[208:211], v[102:105]
	v_mfma_f32_16x16x32_bf16 v[130:133], v[150:153], v[182:185], v[130:133]
	v_mfma_f32_16x16x32_bf16 v[126:129], v[158:161], v[182:185], v[126:129]
	v_mfma_f32_16x16x32_bf16 v[122:125], v[150:153], v[190:193], v[122:125]
	v_mfma_f32_16x16x32_bf16 v[118:121], v[158:161], v[190:193], v[118:121]
	v_mfma_f32_16x16x32_bf16 v[114:117], v[150:153], v[204:207], v[114:117]
	v_mfma_f32_16x16x32_bf16 v[110:113], v[158:161], v[204:207], v[110:113]
	v_mfma_f32_16x16x32_bf16 v[106:109], v[150:153], v[212:215], v[106:109]
	v_mfma_f32_16x16x32_bf16 v[102:105], v[158:161], v[212:215], v[102:105]
	v_mfma_f32_16x16x32_bf16 v[98:101], v[162:165], v[178:181], v[98:101]
	v_mfma_f32_16x16x32_bf16 v[94:97], v[170:173], v[178:181], v[94:97]
	v_mfma_f32_16x16x32_bf16 v[90:93], v[162:165], v[186:189], v[90:93]
	v_mfma_f32_16x16x32_bf16 v[86:89], v[170:173], v[186:189], v[86:89]
	v_mfma_f32_16x16x32_bf16 v[82:85], v[162:165], v[200:203], v[82:85]
	v_mfma_f32_16x16x32_bf16 v[78:81], v[170:173], v[200:203], v[78:81]
	v_mfma_f32_16x16x32_bf16 v[74:77], v[162:165], v[208:211], v[74:77]
	v_mfma_f32_16x16x32_bf16 v[70:73], v[170:173], v[208:211], v[70:73]
	v_mfma_f32_16x16x32_bf16 v[98:101], v[166:169], v[182:185], v[98:101]
	v_mfma_f32_16x16x32_bf16 v[94:97], v[174:177], v[182:185], v[94:97]
	v_mfma_f32_16x16x32_bf16 v[90:93], v[166:169], v[190:193], v[90:93]
	v_mfma_f32_16x16x32_bf16 v[86:89], v[174:177], v[190:193], v[86:89]
	v_mfma_f32_16x16x32_bf16 v[82:85], v[166:169], v[204:207], v[82:85]
	v_mfma_f32_16x16x32_bf16 v[78:81], v[174:177], v[204:207], v[78:81]
	v_mfma_f32_16x16x32_bf16 v[74:77], v[166:169], v[212:215], v[74:77]
	v_mfma_f32_16x16x32_bf16 v[70:73], v[174:177], v[212:215], v[70:73]
	s_barrier
	s_setprio 0
	s_add_i32 s6, s6, s47
	v_lshl_add_u64 v[8:9], v[194:195], 0, s[90:91]
	s_mov_b32 m0, s6
	ds_read_b128 v[178:181], v249 offset:49152
	ds_read_b128 v[182:185], v249 offset:50176
	ds_read_b128 v[186:189], v249 offset:51200
	ds_read_b128 v[190:193], v249 offset:52224
	ds_read_b128 v[200:203], v249 offset:53248
	ds_read_b128 v[204:207], v249 offset:54272
	ds_read_b128 v[208:211], v249 offset:55296
	ds_read_b128 v[212:215], v249 offset:56320
	global_load_lds_dwordx4 v[8:9], off
	s_add_i32 m0, s6, 0x2000
	s_add_u32 s30, s30, 0x40080
	v_lshl_add_u64 v[8:9], v[216:217], 0, s[90:91]
	s_addc_u32 s31, s31, 0
	s_add_i32 s6, s25, s47
	global_load_lds_dwordx4 v[8:9], off
	v_lshl_add_u64 v[8:9], s[30:31], 0, v[136:137]
	s_mov_b32 m0, s6
	s_nop 0
	global_load_lds_dwordx4 v[8:9], off
	v_lshl_add_u64 v[8:9], s[30:31], 0, v[140:141]
	s_add_i32 m0, s6, 0x2000
	s_nop 0
	global_load_lds_dwordx4 v[8:9], off
	v_lshl_add_u64 v[8:9], v[218:219], 0, s[90:91]
	s_mov_b32 m0, s80
	s_nop 0
	global_load_lds_dwordx4 v[8:9], off
	v_lshl_add_u64 v[8:9], v[220:221], 0, s[90:91]
	s_mov_b32 m0, s81
	s_nop 0
	global_load_lds_dwordx4 v[8:9], off
	s_waitcnt vmcnt(8)
	s_waitcnt lgkmcnt(0)
	s_setprio 1
	s_barrier
	v_mfma_f32_16x16x32_bf16 v[66:69], v[146:149], v[178:181], v[66:69]
	v_mfma_f32_16x16x32_bf16 v[62:65], v[154:157], v[178:181], v[62:65]
	v_mfma_f32_16x16x32_bf16 v[58:61], v[146:149], v[186:189], v[58:61]
	v_mfma_f32_16x16x32_bf16 v[54:57], v[154:157], v[186:189], v[54:57]
	v_mfma_f32_16x16x32_bf16 v[50:53], v[146:149], v[200:203], v[50:53]
	v_mfma_f32_16x16x32_bf16 v[46:49], v[154:157], v[200:203], v[46:49]
	v_mfma_f32_16x16x32_bf16 v[42:45], v[146:149], v[208:211], v[42:45]
	v_mfma_f32_16x16x32_bf16 v[38:41], v[154:157], v[208:211], v[38:41]
	v_mfma_f32_16x16x32_bf16 v[66:69], v[150:153], v[182:185], v[66:69]
	v_mfma_f32_16x16x32_bf16 v[62:65], v[158:161], v[182:185], v[62:65]
	v_mfma_f32_16x16x32_bf16 v[58:61], v[150:153], v[190:193], v[58:61]
	v_mfma_f32_16x16x32_bf16 v[54:57], v[158:161], v[190:193], v[54:57]
	v_mfma_f32_16x16x32_bf16 v[50:53], v[150:153], v[204:207], v[50:53]
	v_mfma_f32_16x16x32_bf16 v[46:49], v[158:161], v[204:207], v[46:49]
	v_mfma_f32_16x16x32_bf16 v[42:45], v[150:153], v[212:215], v[42:45]
	v_mfma_f32_16x16x32_bf16 v[38:41], v[158:161], v[212:215], v[38:41]
	v_mfma_f32_16x16x32_bf16 v[34:37], v[162:165], v[178:181], v[34:37]
	v_mfma_f32_16x16x32_bf16 v[30:33], v[170:173], v[178:181], v[30:33]
	v_mfma_f32_16x16x32_bf16 v[26:29], v[162:165], v[186:189], v[26:29]
	v_mfma_f32_16x16x32_bf16 v[22:25], v[170:173], v[186:189], v[22:25]
	v_mfma_f32_16x16x32_bf16 v[18:21], v[162:165], v[200:203], v[18:21]
	v_mfma_f32_16x16x32_bf16 v[14:17], v[170:173], v[200:203], v[14:17]
	v_mfma_f32_16x16x32_bf16 v[8:11], v[162:165], v[208:211], v[10:13]
	v_mfma_f32_16x16x32_bf16 v[4:7], v[170:173], v[208:211], v[4:7]
	v_mfma_f32_16x16x32_bf16 v[34:37], v[166:169], v[182:185], v[34:37]
	v_mfma_f32_16x16x32_bf16 v[30:33], v[174:177], v[182:185], v[30:33]
	v_mfma_f32_16x16x32_bf16 v[26:29], v[166:169], v[190:193], v[26:29]
	v_mfma_f32_16x16x32_bf16 v[22:25], v[174:177], v[190:193], v[22:25]
	v_mfma_f32_16x16x32_bf16 v[18:21], v[166:169], v[204:207], v[18:21]
	v_mfma_f32_16x16x32_bf16 v[14:17], v[174:177], v[204:207], v[14:17]
	v_mfma_f32_16x16x32_bf16 v[10:13], v[166:169], v[212:215], v[8:11]
	v_mfma_f32_16x16x32_bf16 v[6:9], v[174:177], v[212:215], v[4:7]
	s_barrier
	s_setprio 0
	s_add_u32 s66, s66, 0x100
	s_addc_u32 s67, s67, 0
	s_add_u32 s15, s15, 0x100
	s_addc_u32 s24, s24, 0
	s_cmp_ge_i32 s0, s1
	s_mov_b32 s6, s0
	s_cbranch_scc0 .LBB0_747

.LBB0_967:
	s_add_u32 s0, s36, 0xfff80080
	s_addc_u32 s6, s37, -1
	s_add_i32 s49, 0, 0x10000
	s_cmp_eq_u32 s55, 28
	s_cselect_b32 s35, s65, s6
	s_cselect_b32 s34, s64, s0
	s_cselect_b32 s31, s67, s39
	s_cselect_b32 s30, s66, s38
	s_add_i32 s0, 0, 0x14000
	v_add_u32_e32 v144, s49, v3
	v_add_u32_e32 v160, s0, v3
	ds_read_b128 v[124:127], v144
	ds_read_b128 v[128:131], v144 offset:1024
	ds_read_b128 v[140:143], v144 offset:2048
	ds_read_b128 v[144:147], v144 offset:3072
	ds_read_b128 v[148:151], v160
	ds_read_b128 v[152:155], v160 offset:1024
	ds_read_b128 v[156:159], v160 offset:2048
	ds_read_b128 v[160:163], v160 offset:3072
	v_lshl_add_u64 v[198:199], s[36:37], 0, v[212:213]
	s_add_i32 m0, s4, 0xc000
	ds_read_b128 v[164:167], v250
	ds_read_b128 v[168:171], v250 offset:1024
	ds_read_b128 v[172:175], v250 offset:2048
	ds_read_b128 v[176:179], v250 offset:3072
	ds_read_b128 v[180:183], v250 offset:4096
	ds_read_b128 v[184:187], v250 offset:5120
	ds_read_b128 v[188:191], v250 offset:6144
	ds_read_b128 v[192:195], v250 offset:7168
	global_load_lds_dwordx4 v[198:199], off
	v_lshl_add_u64 v[198:199], s[36:37], 0, v[214:215]
	s_add_i32 m0, s4, 0xe000
	s_nop 0
	global_load_lds_dwordx4 v[198:199], off
	s_waitcnt vmcnt(8)
	s_waitcnt lgkmcnt(0)
	s_setprio 1
	s_barrier
	v_mfma_f32_16x16x32_bf16 v[136:139], v[124:127], v[164:167], v[136:139]
	v_mfma_f32_16x16x32_bf16 v[132:135], v[140:143], v[164:167], v[132:135]
	v_mfma_f32_16x16x32_bf16 v[112:115], v[124:127], v[172:175], v[112:115]
	v_mfma_f32_16x16x32_bf16 v[108:111], v[140:143], v[172:175], v[108:111]
	v_mfma_f32_16x16x32_bf16 v[96:99], v[124:127], v[180:183], v[96:99]
	v_mfma_f32_16x16x32_bf16 v[92:95], v[140:143], v[180:183], v[92:95]
	v_mfma_f32_16x16x32_bf16 v[80:83], v[124:127], v[188:191], v[80:83]
	v_mfma_f32_16x16x32_bf16 v[76:79], v[140:143], v[188:191], v[76:79]
	v_mfma_f32_16x16x32_bf16 v[136:139], v[128:131], v[168:171], v[136:139]
	v_mfma_f32_16x16x32_bf16 v[132:135], v[144:147], v[168:171], v[132:135]
	v_mfma_f32_16x16x32_bf16 v[112:115], v[128:131], v[176:179], v[112:115]
	v_mfma_f32_16x16x32_bf16 v[108:111], v[144:147], v[176:179], v[108:111]
	v_mfma_f32_16x16x32_bf16 v[96:99], v[128:131], v[184:187], v[96:99]
	v_mfma_f32_16x16x32_bf16 v[92:95], v[144:147], v[184:187], v[92:95]
	v_mfma_f32_16x16x32_bf16 v[80:83], v[128:131], v[192:195], v[80:83]
	v_mfma_f32_16x16x32_bf16 v[76:79], v[144:147], v[192:195], v[76:79]
	v_mfma_f32_16x16x32_bf16 v[120:123], v[148:151], v[164:167], v[120:123]
	v_mfma_f32_16x16x32_bf16 v[116:119], v[156:159], v[164:167], v[116:119]
	v_mfma_f32_16x16x32_bf16 v[104:107], v[148:151], v[172:175], v[104:107]
	v_mfma_f32_16x16x32_bf16 v[100:103], v[156:159], v[172:175], v[100:103]
	v_mfma_f32_16x16x32_bf16 v[88:91], v[148:151], v[180:183], v[88:91]
	v_mfma_f32_16x16x32_bf16 v[84:87], v[156:159], v[180:183], v[84:87]
	v_mfma_f32_16x16x32_bf16 v[72:75], v[148:151], v[188:191], v[72:75]
	v_mfma_f32_16x16x32_bf16 v[68:71], v[156:159], v[188:191], v[68:71]
	v_mfma_f32_16x16x32_bf16 v[120:123], v[152:155], v[168:171], v[120:123]
	v_mfma_f32_16x16x32_bf16 v[116:119], v[160:163], v[168:171], v[116:119]
	v_mfma_f32_16x16x32_bf16 v[104:107], v[152:155], v[176:179], v[104:107]
	v_mfma_f32_16x16x32_bf16 v[100:103], v[160:163], v[176:179], v[100:103]
	v_mfma_f32_16x16x32_bf16 v[88:91], v[152:155], v[184:187], v[88:91]
	v_mfma_f32_16x16x32_bf16 v[84:87], v[160:163], v[184:187], v[84:87]
	v_mfma_f32_16x16x32_bf16 v[72:75], v[152:155], v[192:195], v[72:75]
	v_mfma_f32_16x16x32_bf16 v[68:71], v[160:163], v[192:195], v[68:71]
	s_barrier
	s_setprio 0
	s_add_i32 s6, s49, s1
	v_lshl_add_u64 v[198:199], s[30:31], 0, v[204:205]
	s_mov_b32 m0, s6
	ds_read_b128 v[164:167], v250 offset:16384
	ds_read_b128 v[168:171], v250 offset:17408
	ds_read_b128 v[172:175], v250 offset:18432
	ds_read_b128 v[176:179], v250 offset:19456
	ds_read_b128 v[180:183], v250 offset:20480
	ds_read_b128 v[184:187], v250 offset:21504
	ds_read_b128 v[188:191], v250 offset:22528
	ds_read_b128 v[192:195], v250 offset:23552
	global_load_lds_dwordx4 v[198:199], off
	s_add_i32 m0, s6, 0x2000
	s_add_u32 s68, s30, 0x80000
	v_lshl_add_u64 v[216:217], s[30:31], 0, v[200:201]
	s_addc_u32 s69, s31, 0
	s_add_i32 s0, s0, s1
	global_load_lds_dwordx4 v[216:217], off
	v_lshl_add_u64 v[218:219], s[68:69], 0, v[204:205]
	s_mov_b32 m0, s0
	v_lshl_add_u64 v[220:221], s[34:35], 0, v[202:203]
	global_load_lds_dwordx4 v[218:219], off
	v_lshl_add_u64 v[218:219], s[68:69], 0, v[200:201]
	s_add_i32 m0, s0, 0x2000
	s_nop 0
	global_load_lds_dwordx4 v[218:219], off
	v_lshl_add_u64 v[218:219], s[34:35], 0, v[206:207]
	s_mov_b32 m0, s4
	s_nop 0
	global_load_lds_dwordx4 v[218:219], off
	s_mov_b32 m0, s24
	s_nop 0
	global_load_lds_dwordx4 v[220:221], off
	s_waitcnt vmcnt(8)
	s_waitcnt lgkmcnt(0)
	s_setprio 1
	s_barrier
	v_mfma_f32_16x16x32_bf16 v[64:67], v[124:127], v[164:167], v[64:67]
	v_mfma_f32_16x16x32_bf16 v[60:63], v[140:143], v[164:167], v[60:63]
	v_mfma_f32_16x16x32_bf16 v[48:51], v[124:127], v[172:175], v[48:51]
	v_mfma_f32_16x16x32_bf16 v[44:47], v[140:143], v[172:175], v[44:47]
	v_mfma_f32_16x16x32_bf16 v[32:35], v[124:127], v[180:183], v[32:35]
	v_mfma_f32_16x16x32_bf16 v[28:31], v[140:143], v[180:183], v[28:31]
	v_mfma_f32_16x16x32_bf16 v[16:19], v[124:127], v[188:191], v[16:19]
	v_mfma_f32_16x16x32_bf16 v[12:15], v[140:143], v[188:191], v[12:15]
	v_mfma_f32_16x16x32_bf16 v[64:67], v[128:131], v[168:171], v[64:67]
	v_mfma_f32_16x16x32_bf16 v[60:63], v[144:147], v[168:171], v[60:63]
	v_mfma_f32_16x16x32_bf16 v[48:51], v[128:131], v[176:179], v[48:51]
	v_mfma_f32_16x16x32_bf16 v[44:47], v[144:147], v[176:179], v[44:47]
	v_mfma_f32_16x16x32_bf16 v[32:35], v[128:131], v[184:187], v[32:35]
	v_mfma_f32_16x16x32_bf16 v[28:31], v[144:147], v[184:187], v[28:31]
	v_mfma_f32_16x16x32_bf16 v[16:19], v[128:131], v[192:195], v[16:19]
	v_mfma_f32_16x16x32_bf16 v[12:15], v[144:147], v[192:195], v[12:15]
	v_mfma_f32_16x16x32_bf16 v[56:59], v[148:151], v[164:167], v[56:59]
	v_mfma_f32_16x16x32_bf16 v[52:55], v[156:159], v[164:167], v[52:55]
	v_mfma_f32_16x16x32_bf16 v[40:43], v[148:151], v[172:175], v[40:43]
	v_mfma_f32_16x16x32_bf16 v[36:39], v[156:159], v[172:175], v[36:39]
	v_mfma_f32_16x16x32_bf16 v[24:27], v[148:151], v[180:183], v[24:27]
	v_mfma_f32_16x16x32_bf16 v[20:23], v[156:159], v[180:183], v[20:23]
	v_mfma_f32_16x16x32_bf16 v[8:11], v[148:151], v[188:191], v[8:11]
	v_mfma_f32_16x16x32_bf16 v[4:7], v[156:159], v[188:191], v[4:7]
	v_mfma_f32_16x16x32_bf16 v[56:59], v[152:155], v[168:171], v[56:59]
	v_mfma_f32_16x16x32_bf16 v[52:55], v[160:163], v[168:171], v[52:55]
	v_mfma_f32_16x16x32_bf16 v[40:43], v[152:155], v[176:179], v[40:43]
	v_mfma_f32_16x16x32_bf16 v[36:39], v[160:163], v[176:179], v[36:39]
	v_mfma_f32_16x16x32_bf16 v[24:27], v[152:155], v[184:187], v[24:27]
	v_mfma_f32_16x16x32_bf16 v[20:23], v[160:163], v[184:187], v[20:23]
	v_mfma_f32_16x16x32_bf16 v[8:11], v[152:155], v[192:195], v[8:11]
	v_mfma_f32_16x16x32_bf16 v[4:7], v[160:163], v[192:195], v[4:7]
	s_barrier
	s_setprio 0
	s_add_i32 s0, 0, 0x18000
	s_add_i32 s6, 0, 0x1c000
	v_add_u32_e32 v144, s0, v3
	v_add_u32_e32 v160, s6, v3
	ds_read_b128 v[124:127], v144
	ds_read_b128 v[128:131], v144 offset:1024
	ds_read_b128 v[140:143], v144 offset:2048
	ds_read_b128 v[144:147], v144 offset:3072
	ds_read_b128 v[148:151], v160
	ds_read_b128 v[152:155], v160 offset:1024
	ds_read_b128 v[156:159], v160 offset:2048
	ds_read_b128 v[160:163], v160 offset:3072
	s_add_u32 s34, s34, 0x80000
	s_addc_u32 s35, s35, 0
	s_mov_b32 m0, s25
	v_lshl_add_u64 v[222:223], s[34:35], 0, v[206:207]
	ds_read_b128 v[164:167], v250 offset:32768
	ds_read_b128 v[168:171], v250 offset:33792
	ds_read_b128 v[172:175], v250 offset:34816
	ds_read_b128 v[176:179], v250 offset:35840
	ds_read_b128 v[180:183], v250 offset:36864
	ds_read_b128 v[184:187], v250 offset:37888
	ds_read_b128 v[188:191], v250 offset:38912
	ds_read_b128 v[192:195], v250 offset:39936
	global_load_lds_dwordx4 v[222:223], off
	v_lshl_add_u64 v[222:223], s[34:35], 0, v[202:203]
	s_mov_b32 m0, s29
	s_nop 0
	global_load_lds_dwordx4 v[222:223], off
	s_waitcnt vmcnt(8)
	s_waitcnt lgkmcnt(0)
	s_setprio 1
	s_barrier
	v_mfma_f32_16x16x32_bf16 v[136:139], v[124:127], v[164:167], v[136:139]
	v_mfma_f32_16x16x32_bf16 v[132:135], v[140:143], v[164:167], v[132:135]
	v_mfma_f32_16x16x32_bf16 v[112:115], v[124:127], v[172:175], v[112:115]
	v_mfma_f32_16x16x32_bf16 v[108:111], v[140:143], v[172:175], v[108:111]
	v_mfma_f32_16x16x32_bf16 v[96:99], v[124:127], v[180:183], v[96:99]
	v_mfma_f32_16x16x32_bf16 v[92:95], v[140:143], v[180:183], v[92:95]
	v_mfma_f32_16x16x32_bf16 v[80:83], v[124:127], v[188:191], v[80:83]
	v_mfma_f32_16x16x32_bf16 v[76:79], v[140:143], v[188:191], v[76:79]
	v_mfma_f32_16x16x32_bf16 v[136:139], v[128:131], v[168:171], v[136:139]
	v_mfma_f32_16x16x32_bf16 v[132:135], v[144:147], v[168:171], v[132:135]
	v_mfma_f32_16x16x32_bf16 v[112:115], v[128:131], v[176:179], v[112:115]
	v_mfma_f32_16x16x32_bf16 v[108:111], v[144:147], v[176:179], v[108:111]
	v_mfma_f32_16x16x32_bf16 v[96:99], v[128:131], v[184:187], v[96:99]
	v_mfma_f32_16x16x32_bf16 v[92:95], v[144:147], v[184:187], v[92:95]
	v_mfma_f32_16x16x32_bf16 v[80:83], v[128:131], v[192:195], v[80:83]
	v_mfma_f32_16x16x32_bf16 v[76:79], v[144:147], v[192:195], v[76:79]
	v_mfma_f32_16x16x32_bf16 v[120:123], v[148:151], v[164:167], v[120:123]
	v_mfma_f32_16x16x32_bf16 v[116:119], v[156:159], v[164:167], v[116:119]
	v_mfma_f32_16x16x32_bf16 v[104:107], v[148:151], v[172:175], v[104:107]
	v_mfma_f32_16x16x32_bf16 v[100:103], v[156:159], v[172:175], v[100:103]
	v_mfma_f32_16x16x32_bf16 v[88:91], v[148:151], v[180:183], v[88:91]
	v_mfma_f32_16x16x32_bf16 v[84:87], v[156:159], v[180:183], v[84:87]
	v_mfma_f32_16x16x32_bf16 v[72:75], v[148:151], v[188:191], v[72:75]
	v_mfma_f32_16x16x32_bf16 v[68:71], v[156:159], v[188:191], v[68:71]
	v_mfma_f32_16x16x32_bf16 v[120:123], v[152:155], v[168:171], v[120:123]
	v_mfma_f32_16x16x32_bf16 v[116:119], v[160:163], v[168:171], v[116:119]
	v_mfma_f32_16x16x32_bf16 v[104:107], v[152:155], v[176:179], v[104:107]
	v_mfma_f32_16x16x32_bf16 v[100:103], v[160:163], v[176:179], v[100:103]
	v_mfma_f32_16x16x32_bf16 v[88:91], v[152:155], v[184:187], v[88:91]
	v_mfma_f32_16x16x32_bf16 v[84:87], v[160:163], v[184:187], v[84:87]
	v_mfma_f32_16x16x32_bf16 v[72:75], v[152:155], v[192:195], v[72:75]
	v_mfma_f32_16x16x32_bf16 v[68:71], v[160:163], v[192:195], v[68:71]
	s_barrier
	s_setprio 0
	s_add_i32 s0, s0, s1
	v_lshl_add_u64 v[198:199], v[198:199], 0, s[90:91]
	s_mov_b32 m0, s0
	ds_read_b128 v[164:167], v250 offset:49152
	ds_read_b128 v[168:171], v250 offset:50176
	ds_read_b128 v[172:175], v250 offset:51200
	ds_read_b128 v[176:179], v250 offset:52224
	ds_read_b128 v[180:183], v250 offset:53248
	ds_read_b128 v[184:187], v250 offset:54272
	ds_read_b128 v[188:191], v250 offset:55296
	ds_read_b128 v[192:195], v250 offset:56320
	global_load_lds_dwordx4 v[198:199], off
	s_add_i32 m0, s0, 0x2000
	s_add_u32 s30, s30, 0x80080
	v_lshl_add_u64 v[198:199], v[216:217], 0, s[90:91]
	s_addc_u32 s31, s31, 0
	s_add_i32 s0, s6, s1
	global_load_lds_dwordx4 v[198:199], off
	v_lshl_add_u64 v[198:199], s[30:31], 0, v[204:205]
	s_mov_b32 m0, s0
	s_nop 0
	global_load_lds_dwordx4 v[198:199], off
	v_lshl_add_u64 v[198:199], s[30:31], 0, v[200:201]
	s_add_i32 m0, s0, 0x2000
	s_nop 0
	global_load_lds_dwordx4 v[198:199], off
	v_lshl_add_u64 v[198:199], v[218:219], 0, s[90:91]
	s_mov_b32 m0, s33
	s_nop 0
	global_load_lds_dwordx4 v[198:199], off
	v_lshl_add_u64 v[198:199], v[220:221], 0, s[90:91]
	s_mov_b32 m0, s40
	s_nop 0
	global_load_lds_dwordx4 v[198:199], off
	s_waitcnt vmcnt(8)
	s_waitcnt lgkmcnt(0)
	s_setprio 1
	s_barrier
	v_mfma_f32_16x16x32_bf16 v[64:67], v[124:127], v[164:167], v[64:67]
	v_mfma_f32_16x16x32_bf16 v[60:63], v[140:143], v[164:167], v[60:63]
	v_mfma_f32_16x16x32_bf16 v[48:51], v[124:127], v[172:175], v[48:51]
	v_mfma_f32_16x16x32_bf16 v[44:47], v[140:143], v[172:175], v[44:47]
	v_mfma_f32_16x16x32_bf16 v[32:35], v[124:127], v[180:183], v[32:35]
	v_mfma_f32_16x16x32_bf16 v[28:31], v[140:143], v[180:183], v[28:31]
	v_mfma_f32_16x16x32_bf16 v[16:19], v[124:127], v[188:191], v[16:19]
	v_mfma_f32_16x16x32_bf16 v[12:15], v[140:143], v[188:191], v[12:15]
	v_mfma_f32_16x16x32_bf16 v[64:67], v[128:131], v[168:171], v[64:67]
	v_mfma_f32_16x16x32_bf16 v[60:63], v[144:147], v[168:171], v[60:63]
	v_mfma_f32_16x16x32_bf16 v[48:51], v[128:131], v[176:179], v[48:51]
	v_mfma_f32_16x16x32_bf16 v[44:47], v[144:147], v[176:179], v[44:47]
	v_mfma_f32_16x16x32_bf16 v[32:35], v[128:131], v[184:187], v[32:35]
	v_mfma_f32_16x16x32_bf16 v[28:31], v[144:147], v[184:187], v[28:31]
	v_mfma_f32_16x16x32_bf16 v[16:19], v[128:131], v[192:195], v[16:19]
	v_mfma_f32_16x16x32_bf16 v[12:15], v[144:147], v[192:195], v[12:15]
	v_mfma_f32_16x16x32_bf16 v[56:59], v[148:151], v[164:167], v[56:59]
	v_mfma_f32_16x16x32_bf16 v[52:55], v[156:159], v[164:167], v[52:55]
	v_mfma_f32_16x16x32_bf16 v[40:43], v[148:151], v[172:175], v[40:43]
	v_mfma_f32_16x16x32_bf16 v[36:39], v[156:159], v[172:175], v[36:39]
	v_mfma_f32_16x16x32_bf16 v[24:27], v[148:151], v[180:183], v[24:27]
	v_mfma_f32_16x16x32_bf16 v[20:23], v[156:159], v[180:183], v[20:23]
	v_mfma_f32_16x16x32_bf16 v[8:11], v[148:151], v[188:191], v[8:11]
	v_mfma_f32_16x16x32_bf16 v[4:7], v[156:159], v[188:191], v[4:7]
	v_mfma_f32_16x16x32_bf16 v[56:59], v[152:155], v[168:171], v[56:59]
	v_mfma_f32_16x16x32_bf16 v[52:55], v[160:163], v[168:171], v[52:55]
	v_mfma_f32_16x16x32_bf16 v[40:43], v[152:155], v[176:179], v[40:43]
	v_mfma_f32_16x16x32_bf16 v[36:39], v[160:163], v[176:179], v[36:39]
	v_mfma_f32_16x16x32_bf16 v[24:27], v[152:155], v[184:187], v[24:27]
	v_mfma_f32_16x16x32_bf16 v[20:23], v[160:163], v[184:187], v[20:23]
	v_mfma_f32_16x16x32_bf16 v[8:11], v[152:155], v[192:195], v[8:11]
	v_mfma_f32_16x16x32_bf16 v[4:7], v[160:163], v[192:195], v[4:7]
	s_barrier
	s_setprio 0
	s_add_i32 s55, s55, 2
	s_add_u32 s36, s36, 0x100
	s_addc_u32 s37, s37, 0
	s_add_u32 s38, s38, 0x100
	s_addc_u32 s39, s39, 0
	s_cmp_gt_u32 s55, 29
	s_cbranch_scc0 .LBB0_967
	s_and_b64 vcc, exec, s[44:45]
	s_cbranch_vccz .LBB0_970
	s_barrier

.LBB0_1017:
	s_add_u32 s0, s68, s30
	s_addc_u32 s6, s69, 0
	s_add_u32 s31, s0, 0x100
	s_addc_u32 s38, s6, 0
	s_and_b64 s[34:35], s[36:37], exec
	s_cselect_b32 vcc_hi, s65, s38
	s_cselect_b32 vcc_lo, s64, s31
	s_add_u32 s30, s74, s30
	s_addc_u32 s31, s75, 0
	s_add_u32 s34, s30, 0x100
	s_addc_u32 s35, s31, 0
	s_add_i32 s78, 0, 0x10000
	s_and_b64 s[30:31], s[36:37], exec
	s_cselect_b32 s53, s67, s35
	s_cselect_b32 s52, s66, s34
	s_add_i32 s37, 0, 0x14000
	s_add_u32 s34, s0, 0x80080
	s_addc_u32 s35, s6, 0
	s_add_i32 s73, s78, s1
	s_add_i32 m0, s4, 0xc000
	s_add_i32 s83, s4, 0xe000
	s_add_i32 s6, s73, 0x2000
	s_add_u32 s30, s52, 0x80000
	v_add_u32_e32 v144, s78, v3
	v_add_u32_e32 v160, s37, v3
	s_addc_u32 s31, s53, 0
	s_add_i32 s49, s37, s1
	ds_read_b128 v[132:135], v144
	ds_read_b128 v[136:139], v144 offset:1024
	ds_read_b128 v[140:143], v144 offset:2048
	ds_read_b128 v[144:147], v144 offset:3072
	ds_read_b128 v[148:151], v160
	ds_read_b128 v[152:155], v160 offset:1024
	ds_read_b128 v[156:159], v160 offset:2048
	ds_read_b128 v[160:163], v160 offset:3072
	s_add_i32 s63, s49, 0x2000
	s_add_i32 s54, 0, 0x18000
	s_add_i32 s61, 0, 0x1c000
	s_add_u32 s38, vcc_lo, 0x80000
	s_addc_u32 s39, vcc_hi, 0
	s_add_i32 s0, s54, s1
	s_add_i32 s45, s0, 0x2000
	s_add_u32 s36, s52, 0x80080
	s_addc_u32 s37, s53, 0
	s_add_i32 s82, s61, s1
	s_add_i32 s78, s82, 0x2000
	v_lshl_add_u64 v[198:199], s[34:35], 0, v[206:207]
	ds_read_b128 v[164:167], v236
	ds_read_b128 v[168:171], v236 offset:1024
	ds_read_b128 v[172:175], v236 offset:2048
	ds_read_b128 v[176:179], v236 offset:3072
	ds_read_b128 v[180:183], v236 offset:4096
	ds_read_b128 v[184:187], v236 offset:5120
	ds_read_b128 v[188:191], v236 offset:6144
	ds_read_b128 v[192:195], v236 offset:7168
	global_load_lds_dwordx4 v[198:199], off
	v_lshl_add_u64 v[198:199], s[34:35], 0, v[202:203]
	s_mov_b32 m0, s83
	s_nop 0
	global_load_lds_dwordx4 v[198:199], off
	s_waitcnt vmcnt(8)
	s_waitcnt lgkmcnt(0)
	s_setprio 1
	s_barrier
	v_mfma_f32_16x16x32_bf16 v[128:131], v[132:135], v[164:167], v[128:131]
	v_mfma_f32_16x16x32_bf16 v[124:127], v[140:143], v[164:167], v[124:127]
	v_mfma_f32_16x16x32_bf16 v[112:115], v[132:135], v[172:175], v[112:115]
	v_mfma_f32_16x16x32_bf16 v[108:111], v[140:143], v[172:175], v[108:111]
	v_mfma_f32_16x16x32_bf16 v[96:99], v[132:135], v[180:183], v[96:99]
	v_mfma_f32_16x16x32_bf16 v[92:95], v[140:143], v[180:183], v[92:95]
	v_mfma_f32_16x16x32_bf16 v[80:83], v[132:135], v[188:191], v[80:83]
	v_mfma_f32_16x16x32_bf16 v[76:79], v[140:143], v[188:191], v[76:79]
	v_mfma_f32_16x16x32_bf16 v[128:131], v[136:139], v[168:171], v[128:131]
	v_mfma_f32_16x16x32_bf16 v[124:127], v[144:147], v[168:171], v[124:127]
	v_mfma_f32_16x16x32_bf16 v[112:115], v[136:139], v[176:179], v[112:115]
	v_mfma_f32_16x16x32_bf16 v[108:111], v[144:147], v[176:179], v[108:111]
	v_mfma_f32_16x16x32_bf16 v[96:99], v[136:139], v[184:187], v[96:99]
	v_mfma_f32_16x16x32_bf16 v[92:95], v[144:147], v[184:187], v[92:95]
	v_mfma_f32_16x16x32_bf16 v[80:83], v[136:139], v[192:195], v[80:83]
	v_mfma_f32_16x16x32_bf16 v[76:79], v[144:147], v[192:195], v[76:79]
	v_mfma_f32_16x16x32_bf16 v[120:123], v[148:151], v[164:167], v[120:123]
	v_mfma_f32_16x16x32_bf16 v[116:119], v[156:159], v[164:167], v[116:119]
	v_mfma_f32_16x16x32_bf16 v[104:107], v[148:151], v[172:175], v[104:107]
	v_mfma_f32_16x16x32_bf16 v[100:103], v[156:159], v[172:175], v[100:103]
	v_mfma_f32_16x16x32_bf16 v[88:91], v[148:151], v[180:183], v[88:91]
	v_mfma_f32_16x16x32_bf16 v[84:87], v[156:159], v[180:183], v[84:87]
	v_mfma_f32_16x16x32_bf16 v[72:75], v[148:151], v[188:191], v[72:75]
	v_mfma_f32_16x16x32_bf16 v[68:71], v[156:159], v[188:191], v[68:71]
	v_mfma_f32_16x16x32_bf16 v[120:123], v[152:155], v[168:171], v[120:123]
	v_mfma_f32_16x16x32_bf16 v[116:119], v[160:163], v[168:171], v[116:119]
	v_mfma_f32_16x16x32_bf16 v[104:107], v[152:155], v[176:179], v[104:107]
	v_mfma_f32_16x16x32_bf16 v[100:103], v[160:163], v[176:179], v[100:103]
	v_mfma_f32_16x16x32_bf16 v[88:91], v[152:155], v[184:187], v[88:91]
	v_mfma_f32_16x16x32_bf16 v[84:87], v[160:163], v[184:187], v[84:87]
	v_mfma_f32_16x16x32_bf16 v[72:75], v[152:155], v[192:195], v[72:75]
	v_mfma_f32_16x16x32_bf16 v[68:71], v[160:163], v[192:195], v[68:71]
	s_barrier
	s_setprio 0
	s_mov_b32 m0, s73
	v_lshl_add_u64 v[198:199], s[52:53], 0, v[204:205]
	ds_read_b128 v[164:167], v236 offset:16384
	ds_read_b128 v[168:171], v236 offset:17408
	ds_read_b128 v[172:175], v236 offset:18432
	ds_read_b128 v[176:179], v236 offset:19456
	ds_read_b128 v[180:183], v236 offset:20480
	ds_read_b128 v[184:187], v236 offset:21504
	ds_read_b128 v[188:191], v236 offset:22528
	ds_read_b128 v[192:195], v236 offset:23552
	global_load_lds_dwordx4 v[198:199], off
	v_lshl_add_u64 v[212:213], s[52:53], 0, v[200:201]
	s_mov_b32 m0, s6
	v_lshl_add_u64 v[214:215], s[30:31], 0, v[204:205]
	global_load_lds_dwordx4 v[212:213], off
	s_mov_b32 m0, s49
	v_lshl_add_u64 v[216:217], vcc, 0, v[202:203]
	global_load_lds_dwordx4 v[214:215], off
	v_lshl_add_u64 v[214:215], s[30:31], 0, v[200:201]
	s_mov_b32 m0, s63
	s_nop 0
	global_load_lds_dwordx4 v[214:215], off
	v_lshl_add_u64 v[214:215], vcc, 0, v[206:207]
	s_mov_b32 m0, s4
	s_nop 0
	global_load_lds_dwordx4 v[214:215], off
	s_mov_b32 m0, s24
	s_nop 0
	global_load_lds_dwordx4 v[216:217], off
	s_waitcnt vmcnt(8)
	s_waitcnt lgkmcnt(0)
	s_setprio 1
	s_barrier
	v_mfma_f32_16x16x32_bf16 v[64:67], v[132:135], v[164:167], v[64:67]
	v_mfma_f32_16x16x32_bf16 v[60:63], v[140:143], v[164:167], v[60:63]
	v_mfma_f32_16x16x32_bf16 v[48:51], v[132:135], v[172:175], v[48:51]
	v_mfma_f32_16x16x32_bf16 v[44:47], v[140:143], v[172:175], v[44:47]
	v_mfma_f32_16x16x32_bf16 v[32:35], v[132:135], v[180:183], v[32:35]
	v_mfma_f32_16x16x32_bf16 v[28:31], v[140:143], v[180:183], v[28:31]
	v_mfma_f32_16x16x32_bf16 v[16:19], v[132:135], v[188:191], v[16:19]
	v_mfma_f32_16x16x32_bf16 v[12:15], v[140:143], v[188:191], v[12:15]
	v_mfma_f32_16x16x32_bf16 v[64:67], v[136:139], v[168:171], v[64:67]
	v_mfma_f32_16x16x32_bf16 v[60:63], v[144:147], v[168:171], v[60:63]
	v_mfma_f32_16x16x32_bf16 v[48:51], v[136:139], v[176:179], v[48:51]
	v_mfma_f32_16x16x32_bf16 v[44:47], v[144:147], v[176:179], v[44:47]
	v_mfma_f32_16x16x32_bf16 v[32:35], v[136:139], v[184:187], v[32:35]
	v_mfma_f32_16x16x32_bf16 v[28:31], v[144:147], v[184:187], v[28:31]
	v_mfma_f32_16x16x32_bf16 v[16:19], v[136:139], v[192:195], v[16:19]
	v_mfma_f32_16x16x32_bf16 v[12:15], v[144:147], v[192:195], v[12:15]
	v_mfma_f32_16x16x32_bf16 v[56:59], v[148:151], v[164:167], v[56:59]
	v_mfma_f32_16x16x32_bf16 v[52:55], v[156:159], v[164:167], v[52:55]
	v_mfma_f32_16x16x32_bf16 v[40:43], v[148:151], v[172:175], v[40:43]
	v_mfma_f32_16x16x32_bf16 v[36:39], v[156:159], v[172:175], v[36:39]
	v_mfma_f32_16x16x32_bf16 v[24:27], v[148:151], v[180:183], v[24:27]
	v_mfma_f32_16x16x32_bf16 v[20:23], v[156:159], v[180:183], v[20:23]
	v_mfma_f32_16x16x32_bf16 v[8:11], v[148:151], v[188:191], v[8:11]
	v_mfma_f32_16x16x32_bf16 v[4:7], v[156:159], v[188:191], v[4:7]
	v_mfma_f32_16x16x32_bf16 v[56:59], v[152:155], v[168:171], v[56:59]
	v_mfma_f32_16x16x32_bf16 v[52:55], v[160:163], v[168:171], v[52:55]
	v_mfma_f32_16x16x32_bf16 v[40:43], v[152:155], v[176:179], v[40:43]
	v_mfma_f32_16x16x32_bf16 v[36:39], v[160:163], v[176:179], v[36:39]
	v_mfma_f32_16x16x32_bf16 v[24:27], v[152:155], v[184:187], v[24:27]
	v_mfma_f32_16x16x32_bf16 v[20:23], v[160:163], v[184:187], v[20:23]
	v_mfma_f32_16x16x32_bf16 v[8:11], v[152:155], v[192:195], v[8:11]
	v_mfma_f32_16x16x32_bf16 v[4:7], v[160:163], v[192:195], v[4:7]
	s_barrier
	s_setprio 0
	v_add_u32_e32 v144, s54, v3
	v_add_u32_e32 v160, s61, v3
	ds_read_b128 v[132:135], v144
	ds_read_b128 v[136:139], v144 offset:1024
	ds_read_b128 v[140:143], v144 offset:2048
	ds_read_b128 v[144:147], v144 offset:3072
	ds_read_b128 v[148:151], v160
	ds_read_b128 v[152:155], v160 offset:1024
	ds_read_b128 v[156:159], v160 offset:2048
	ds_read_b128 v[160:163], v160 offset:3072
	s_mov_b32 m0, s25
	v_lshl_add_u64 v[218:219], s[38:39], 0, v[206:207]
	ds_read_b128 v[164:167], v236 offset:32768
	ds_read_b128 v[168:171], v236 offset:33792
	ds_read_b128 v[172:175], v236 offset:34816
	ds_read_b128 v[176:179], v236 offset:35840
	ds_read_b128 v[180:183], v236 offset:36864
	ds_read_b128 v[184:187], v236 offset:37888
	ds_read_b128 v[188:191], v236 offset:38912
	ds_read_b128 v[192:195], v236 offset:39936
	global_load_lds_dwordx4 v[218:219], off
	v_lshl_add_u64 v[218:219], s[38:39], 0, v[202:203]
	s_mov_b32 m0, s33
	s_nop 0
	global_load_lds_dwordx4 v[218:219], off
	s_waitcnt vmcnt(8)
	s_waitcnt lgkmcnt(0)
	s_setprio 1
	s_barrier
	v_mfma_f32_16x16x32_bf16 v[128:131], v[132:135], v[164:167], v[128:131]
	v_mfma_f32_16x16x32_bf16 v[124:127], v[140:143], v[164:167], v[124:127]
	v_mfma_f32_16x16x32_bf16 v[112:115], v[132:135], v[172:175], v[112:115]
	v_mfma_f32_16x16x32_bf16 v[108:111], v[140:143], v[172:175], v[108:111]
	v_mfma_f32_16x16x32_bf16 v[96:99], v[132:135], v[180:183], v[96:99]
	v_mfma_f32_16x16x32_bf16 v[92:95], v[140:143], v[180:183], v[92:95]
	v_mfma_f32_16x16x32_bf16 v[80:83], v[132:135], v[188:191], v[80:83]
	v_mfma_f32_16x16x32_bf16 v[76:79], v[140:143], v[188:191], v[76:79]
	v_mfma_f32_16x16x32_bf16 v[128:131], v[136:139], v[168:171], v[128:131]
	v_mfma_f32_16x16x32_bf16 v[124:127], v[144:147], v[168:171], v[124:127]
	v_mfma_f32_16x16x32_bf16 v[112:115], v[136:139], v[176:179], v[112:115]
	v_mfma_f32_16x16x32_bf16 v[108:111], v[144:147], v[176:179], v[108:111]
	v_mfma_f32_16x16x32_bf16 v[96:99], v[136:139], v[184:187], v[96:99]
	v_mfma_f32_16x16x32_bf16 v[92:95], v[144:147], v[184:187], v[92:95]
	v_mfma_f32_16x16x32_bf16 v[80:83], v[136:139], v[192:195], v[80:83]
	v_mfma_f32_16x16x32_bf16 v[76:79], v[144:147], v[192:195], v[76:79]
	v_mfma_f32_16x16x32_bf16 v[120:123], v[148:151], v[164:167], v[120:123]
	v_mfma_f32_16x16x32_bf16 v[116:119], v[156:159], v[164:167], v[116:119]
	v_mfma_f32_16x16x32_bf16 v[104:107], v[148:151], v[172:175], v[104:107]
	v_mfma_f32_16x16x32_bf16 v[100:103], v[156:159], v[172:175], v[100:103]
	v_mfma_f32_16x16x32_bf16 v[88:91], v[148:151], v[180:183], v[88:91]
	v_mfma_f32_16x16x32_bf16 v[84:87], v[156:159], v[180:183], v[84:87]
	v_mfma_f32_16x16x32_bf16 v[72:75], v[148:151], v[188:191], v[72:75]
	v_mfma_f32_16x16x32_bf16 v[68:71], v[156:159], v[188:191], v[68:71]
	v_mfma_f32_16x16x32_bf16 v[120:123], v[152:155], v[168:171], v[120:123]
	v_mfma_f32_16x16x32_bf16 v[116:119], v[160:163], v[168:171], v[116:119]
	v_mfma_f32_16x16x32_bf16 v[104:107], v[152:155], v[176:179], v[104:107]
	v_mfma_f32_16x16x32_bf16 v[100:103], v[160:163], v[176:179], v[100:103]
	v_mfma_f32_16x16x32_bf16 v[88:91], v[152:155], v[184:187], v[88:91]
	v_mfma_f32_16x16x32_bf16 v[84:87], v[160:163], v[184:187], v[84:87]
	v_mfma_f32_16x16x32_bf16 v[72:75], v[152:155], v[192:195], v[72:75]
	v_mfma_f32_16x16x32_bf16 v[68:71], v[160:163], v[192:195], v[68:71]
	s_barrier
	s_setprio 0
	s_mov_b32 m0, s0
	v_lshl_add_u64 v[198:199], v[198:199], 0, s[90:91]
	ds_read_b128 v[164:167], v236 offset:49152
	ds_read_b128 v[168:171], v236 offset:50176
	ds_read_b128 v[172:175], v236 offset:51200
	ds_read_b128 v[176:179], v236 offset:52224
	ds_read_b128 v[180:183], v236 offset:53248
	ds_read_b128 v[184:187], v236 offset:54272
	ds_read_b128 v[188:191], v236 offset:55296
	ds_read_b128 v[192:195], v236 offset:56320
	global_load_lds_dwordx4 v[198:199], off
	v_lshl_add_u64 v[198:199], v[212:213], 0, s[90:91]
	s_mov_b32 m0, s45
	s_nop 0
	global_load_lds_dwordx4 v[198:199], off
	v_lshl_add_u64 v[198:199], s[36:37], 0, v[204:205]
	s_mov_b32 m0, s82
	s_nop 0
	global_load_lds_dwordx4 v[198:199], off
	v_lshl_add_u64 v[198:199], s[36:37], 0, v[200:201]
	s_mov_b32 m0, s78
	s_nop 0
	global_load_lds_dwordx4 v[198:199], off
	v_lshl_add_u64 v[198:199], v[214:215], 0, s[90:91]
	s_mov_b32 m0, s40
	s_nop 0
	global_load_lds_dwordx4 v[198:199], off
	v_lshl_add_u64 v[198:199], v[216:217], 0, s[90:91]
	s_mov_b32 m0, s50
	s_nop 0
	global_load_lds_dwordx4 v[198:199], off
	s_waitcnt vmcnt(8)
	s_waitcnt lgkmcnt(0)
	s_setprio 1
	s_barrier
	v_mfma_f32_16x16x32_bf16 v[64:67], v[132:135], v[164:167], v[64:67]
	v_mfma_f32_16x16x32_bf16 v[60:63], v[140:143], v[164:167], v[60:63]
	v_mfma_f32_16x16x32_bf16 v[48:51], v[132:135], v[172:175], v[48:51]
	v_mfma_f32_16x16x32_bf16 v[44:47], v[140:143], v[172:175], v[44:47]
	v_mfma_f32_16x16x32_bf16 v[32:35], v[132:135], v[180:183], v[32:35]
	v_mfma_f32_16x16x32_bf16 v[28:31], v[140:143], v[180:183], v[28:31]
	v_mfma_f32_16x16x32_bf16 v[16:19], v[132:135], v[188:191], v[16:19]
	v_mfma_f32_16x16x32_bf16 v[12:15], v[140:143], v[188:191], v[12:15]
	v_mfma_f32_16x16x32_bf16 v[64:67], v[136:139], v[168:171], v[64:67]
	v_mfma_f32_16x16x32_bf16 v[60:63], v[144:147], v[168:171], v[60:63]
	v_mfma_f32_16x16x32_bf16 v[48:51], v[136:139], v[176:179], v[48:51]
	v_mfma_f32_16x16x32_bf16 v[44:47], v[144:147], v[176:179], v[44:47]
	v_mfma_f32_16x16x32_bf16 v[32:35], v[136:139], v[184:187], v[32:35]
	v_mfma_f32_16x16x32_bf16 v[28:31], v[144:147], v[184:187], v[28:31]
	v_mfma_f32_16x16x32_bf16 v[16:19], v[136:139], v[192:195], v[16:19]
	v_mfma_f32_16x16x32_bf16 v[12:15], v[144:147], v[192:195], v[12:15]
	v_mfma_f32_16x16x32_bf16 v[56:59], v[148:151], v[164:167], v[56:59]
	v_mfma_f32_16x16x32_bf16 v[52:55], v[156:159], v[164:167], v[52:55]
	v_mfma_f32_16x16x32_bf16 v[40:43], v[148:151], v[172:175], v[40:43]
	v_mfma_f32_16x16x32_bf16 v[36:39], v[156:159], v[172:175], v[36:39]
	v_mfma_f32_16x16x32_bf16 v[24:27], v[148:151], v[180:183], v[24:27]
	v_mfma_f32_16x16x32_bf16 v[20:23], v[156:159], v[180:183], v[20:23]
	v_mfma_f32_16x16x32_bf16 v[8:11], v[148:151], v[188:191], v[8:11]
	v_mfma_f32_16x16x32_bf16 v[4:7], v[156:159], v[188:191], v[4:7]
	v_mfma_f32_16x16x32_bf16 v[56:59], v[152:155], v[168:171], v[56:59]
	v_mfma_f32_16x16x32_bf16 v[52:55], v[160:163], v[168:171], v[52:55]
	v_mfma_f32_16x16x32_bf16 v[40:43], v[152:155], v[176:179], v[40:43]
	v_mfma_f32_16x16x32_bf16 v[36:39], v[160:163], v[176:179], v[36:39]
	v_mfma_f32_16x16x32_bf16 v[24:27], v[152:155], v[184:187], v[24:27]
	v_mfma_f32_16x16x32_bf16 v[20:23], v[160:163], v[184:187], v[20:23]
	v_mfma_f32_16x16x32_bf16 v[8:11], v[152:155], v[192:195], v[8:11]
	v_mfma_f32_16x16x32_bf16 v[4:7], v[160:163], v[192:195], v[4:7]
	s_barrier
	s_setprio 0
	s_movk_i32 s30, 0x100
	s_andn2_b64 vcc, exec, s[80:81]
	s_mov_b64 s[36:37], -1
	s_mov_b64 s[80:81], 0
	s_cbranch_vccz .LBB0_1017
	s_and_b64 vcc, exec, s[42:43]
	s_cbranch_vccz .LBB0_1020
	s_barrier

.LBB0_1137:
	s_add_u32 s0, s36, 0xfff80080
	s_addc_u32 s6, s37, -1
	s_add_i32 s49, 0, 0x10000
	s_cmp_eq_u32 s66, 28
	s_cselect_b32 s35, s29, s6
	s_cselect_b32 s34, s64, s0
	v_add_u32_e32 v156, s49, v157
	s_cselect_b32 s31, s23, s39
	s_cselect_b32 s30, s65, s38
	s_add_i32 s0, 0, 0x14000
	ds_read_b128 v[144:147], v156
	ds_read_b128 v[148:151], v156 offset:1024
	ds_read_b128 v[152:155], v156 offset:2048
	ds_read_b128 v[162:165], v156 offset:3072
	v_add_u32_e32 v156, s0, v157
	ds_read_b128 v[166:169], v156
	ds_read_b128 v[170:173], v156 offset:1024
	ds_read_b128 v[174:177], v156 offset:2048
	ds_read_b128 v[178:181], v156 offset:3072
	v_lshl_add_u64 v[194:195], s[36:37], 0, v[140:141]
	s_add_i32 m0, s33, 0xc000
	ds_read_b128 v[182:185], v161
	ds_read_b128 v[186:189], v161 offset:1024
	ds_read_b128 v[190:193], v161 offset:2048
	ds_read_b128 v[200:203], v161 offset:3072
	ds_read_b128 v[204:207], v161 offset:4096
	ds_read_b128 v[208:211], v161 offset:5120
	ds_read_b128 v[212:215], v161 offset:6144
	ds_read_b128 v[216:219], v161 offset:7168
	global_load_lds_dwordx4 v[194:195], off
	v_lshl_add_u64 v[194:195], s[36:37], 0, v[142:143]
	s_add_i32 m0, s33, 0xe000
	s_nop 0
	global_load_lds_dwordx4 v[194:195], off
	s_waitcnt vmcnt(8)
	s_waitcnt lgkmcnt(0)
	s_setprio 1
	s_barrier
	v_mfma_f32_16x16x32_bf16 v[128:131], v[144:147], v[182:185], v[128:131]
	v_mfma_f32_16x16x32_bf16 v[124:127], v[152:155], v[182:185], v[124:127]
	v_mfma_f32_16x16x32_bf16 v[112:115], v[144:147], v[190:193], v[112:115]
	v_mfma_f32_16x16x32_bf16 v[108:111], v[152:155], v[190:193], v[108:111]
	v_mfma_f32_16x16x32_bf16 v[96:99], v[144:147], v[204:207], v[96:99]
	v_mfma_f32_16x16x32_bf16 v[92:95], v[152:155], v[204:207], v[92:95]
	v_mfma_f32_16x16x32_bf16 v[80:83], v[144:147], v[212:215], v[80:83]
	v_mfma_f32_16x16x32_bf16 v[76:79], v[152:155], v[212:215], v[76:79]
	v_mfma_f32_16x16x32_bf16 v[128:131], v[148:151], v[186:189], v[128:131]
	v_mfma_f32_16x16x32_bf16 v[124:127], v[162:165], v[186:189], v[124:127]
	v_mfma_f32_16x16x32_bf16 v[112:115], v[148:151], v[200:203], v[112:115]
	v_mfma_f32_16x16x32_bf16 v[108:111], v[162:165], v[200:203], v[108:111]
	v_mfma_f32_16x16x32_bf16 v[96:99], v[148:151], v[208:211], v[96:99]
	v_mfma_f32_16x16x32_bf16 v[92:95], v[162:165], v[208:211], v[92:95]
	v_mfma_f32_16x16x32_bf16 v[80:83], v[148:151], v[216:219], v[80:83]
	v_mfma_f32_16x16x32_bf16 v[76:79], v[162:165], v[216:219], v[76:79]
	v_mfma_f32_16x16x32_bf16 v[120:123], v[166:169], v[182:185], v[120:123]
	v_mfma_f32_16x16x32_bf16 v[116:119], v[174:177], v[182:185], v[116:119]
	v_mfma_f32_16x16x32_bf16 v[104:107], v[166:169], v[190:193], v[104:107]
	v_mfma_f32_16x16x32_bf16 v[100:103], v[174:177], v[190:193], v[100:103]
	v_mfma_f32_16x16x32_bf16 v[88:91], v[166:169], v[204:207], v[88:91]
	v_mfma_f32_16x16x32_bf16 v[84:87], v[174:177], v[204:207], v[84:87]
	v_mfma_f32_16x16x32_bf16 v[72:75], v[166:169], v[212:215], v[72:75]
	v_mfma_f32_16x16x32_bf16 v[68:71], v[174:177], v[212:215], v[68:71]
	v_mfma_f32_16x16x32_bf16 v[120:123], v[170:173], v[186:189], v[120:123]
	v_mfma_f32_16x16x32_bf16 v[116:119], v[178:181], v[186:189], v[116:119]
	v_mfma_f32_16x16x32_bf16 v[104:107], v[170:173], v[200:203], v[104:107]
	v_mfma_f32_16x16x32_bf16 v[100:103], v[178:181], v[200:203], v[100:103]
	v_mfma_f32_16x16x32_bf16 v[88:91], v[170:173], v[208:211], v[88:91]
	v_mfma_f32_16x16x32_bf16 v[84:87], v[178:181], v[208:211], v[84:87]
	v_mfma_f32_16x16x32_bf16 v[72:75], v[170:173], v[216:219], v[72:75]
	v_mfma_f32_16x16x32_bf16 v[68:71], v[178:181], v[216:219], v[68:71]
	s_barrier
	s_setprio 0
	s_add_i32 s6, s49, s25
	v_lshl_add_u64 v[194:195], s[30:31], 0, v[136:137]
	s_mov_b32 m0, s6
	ds_read_b128 v[182:185], v161 offset:16384
	ds_read_b128 v[186:189], v161 offset:17408
	ds_read_b128 v[190:193], v161 offset:18432
	ds_read_b128 v[200:203], v161 offset:19456
	ds_read_b128 v[204:207], v161 offset:20480
	ds_read_b128 v[208:211], v161 offset:21504
	ds_read_b128 v[212:215], v161 offset:22528
	ds_read_b128 v[216:219], v161 offset:23552
	global_load_lds_dwordx4 v[194:195], off
	s_add_i32 m0, s6, 0x2000
	s_add_u32 s68, s30, 0x80000
	v_lshl_add_u64 v[198:199], s[30:31], 0, v[132:133]
	s_addc_u32 s69, s31, 0
	s_add_i32 s0, s0, s25
	global_load_lds_dwordx4 v[198:199], off
	v_lshl_add_u64 v[220:221], s[68:69], 0, v[136:137]
	s_mov_b32 m0, s0
	v_lshl_add_u64 v[222:223], s[34:35], 0, v[134:135]
	global_load_lds_dwordx4 v[220:221], off
	v_lshl_add_u64 v[220:221], s[68:69], 0, v[132:133]
	s_add_i32 m0, s0, 0x2000
	s_nop 0
	global_load_lds_dwordx4 v[220:221], off
	v_lshl_add_u64 v[220:221], s[34:35], 0, v[138:139]
	s_mov_b32 m0, s33
	s_nop 0
	global_load_lds_dwordx4 v[220:221], off
	s_mov_b32 m0, s40
	s_nop 0
	global_load_lds_dwordx4 v[222:223], off
	s_waitcnt vmcnt(8)
	s_waitcnt lgkmcnt(0)
	s_setprio 1
	s_barrier
	v_mfma_f32_16x16x32_bf16 v[64:67], v[144:147], v[182:185], v[64:67]
	v_mfma_f32_16x16x32_bf16 v[60:63], v[152:155], v[182:185], v[60:63]
	v_mfma_f32_16x16x32_bf16 v[48:51], v[144:147], v[190:193], v[48:51]
	v_mfma_f32_16x16x32_bf16 v[44:47], v[152:155], v[190:193], v[44:47]
	v_mfma_f32_16x16x32_bf16 v[32:35], v[144:147], v[204:207], v[32:35]
	v_mfma_f32_16x16x32_bf16 v[28:31], v[152:155], v[204:207], v[28:31]
	v_mfma_f32_16x16x32_bf16 v[16:19], v[144:147], v[212:215], v[16:19]
	v_mfma_f32_16x16x32_bf16 v[12:15], v[152:155], v[212:215], v[12:15]
	v_mfma_f32_16x16x32_bf16 v[64:67], v[148:151], v[186:189], v[64:67]
	v_mfma_f32_16x16x32_bf16 v[60:63], v[162:165], v[186:189], v[60:63]
	v_mfma_f32_16x16x32_bf16 v[48:51], v[148:151], v[200:203], v[48:51]
	v_mfma_f32_16x16x32_bf16 v[44:47], v[162:165], v[200:203], v[44:47]
	v_mfma_f32_16x16x32_bf16 v[32:35], v[148:151], v[208:211], v[32:35]
	v_mfma_f32_16x16x32_bf16 v[28:31], v[162:165], v[208:211], v[28:31]
	v_mfma_f32_16x16x32_bf16 v[16:19], v[148:151], v[216:219], v[16:19]
	v_mfma_f32_16x16x32_bf16 v[12:15], v[162:165], v[216:219], v[12:15]
	v_mfma_f32_16x16x32_bf16 v[56:59], v[166:169], v[182:185], v[56:59]
	v_mfma_f32_16x16x32_bf16 v[52:55], v[174:177], v[182:185], v[52:55]
	v_mfma_f32_16x16x32_bf16 v[40:43], v[166:169], v[190:193], v[40:43]
	v_mfma_f32_16x16x32_bf16 v[36:39], v[174:177], v[190:193], v[36:39]
	v_mfma_f32_16x16x32_bf16 v[24:27], v[166:169], v[204:207], v[24:27]
	v_mfma_f32_16x16x32_bf16 v[20:23], v[174:177], v[204:207], v[20:23]
	v_mfma_f32_16x16x32_bf16 v[8:11], v[166:169], v[212:215], v[8:11]
	v_mfma_f32_16x16x32_bf16 v[4:7], v[174:177], v[212:215], v[4:7]
	v_mfma_f32_16x16x32_bf16 v[56:59], v[170:173], v[186:189], v[56:59]
	v_mfma_f32_16x16x32_bf16 v[52:55], v[178:181], v[186:189], v[52:55]
	v_mfma_f32_16x16x32_bf16 v[40:43], v[170:173], v[200:203], v[40:43]
	v_mfma_f32_16x16x32_bf16 v[36:39], v[178:181], v[200:203], v[36:39]
	v_mfma_f32_16x16x32_bf16 v[24:27], v[170:173], v[208:211], v[24:27]
	v_mfma_f32_16x16x32_bf16 v[20:23], v[178:181], v[208:211], v[20:23]
	v_mfma_f32_16x16x32_bf16 v[8:11], v[170:173], v[216:219], v[8:11]
	v_mfma_f32_16x16x32_bf16 v[4:7], v[178:181], v[216:219], v[4:7]
	s_barrier
	s_setprio 0
	s_add_i32 s0, 0, 0x18000
	v_add_u32_e32 v156, s0, v157
	s_add_i32 s6, 0, 0x1c000
	ds_read_b128 v[144:147], v156
	ds_read_b128 v[148:151], v156 offset:1024
	ds_read_b128 v[152:155], v156 offset:2048
	ds_read_b128 v[162:165], v156 offset:3072
	v_add_u32_e32 v156, s6, v157
	ds_read_b128 v[166:169], v156
	ds_read_b128 v[170:173], v156 offset:1024
	ds_read_b128 v[174:177], v156 offset:2048
	ds_read_b128 v[178:181], v156 offset:3072
	s_add_u32 s34, s34, 0x80000
	s_addc_u32 s35, s35, 0
	s_mov_b32 m0, s50
	v_lshl_add_u64 v[224:225], s[34:35], 0, v[138:139]
	ds_read_b128 v[182:185], v161 offset:32768
	ds_read_b128 v[186:189], v161 offset:33792
	ds_read_b128 v[190:193], v161 offset:34816
	ds_read_b128 v[200:203], v161 offset:35840
	ds_read_b128 v[204:207], v161 offset:36864
	ds_read_b128 v[208:211], v161 offset:37888
	ds_read_b128 v[212:215], v161 offset:38912
	ds_read_b128 v[216:219], v161 offset:39936
	global_load_lds_dwordx4 v[224:225], off
	v_lshl_add_u64 v[224:225], s[34:35], 0, v[134:135]
	s_mov_b32 m0, s51
	s_nop 0
	global_load_lds_dwordx4 v[224:225], off
	s_waitcnt vmcnt(8)
	s_waitcnt lgkmcnt(0)
	s_setprio 1
	s_barrier
	v_mfma_f32_16x16x32_bf16 v[128:131], v[144:147], v[182:185], v[128:131]
	v_mfma_f32_16x16x32_bf16 v[124:127], v[152:155], v[182:185], v[124:127]
	v_mfma_f32_16x16x32_bf16 v[112:115], v[144:147], v[190:193], v[112:115]
	v_mfma_f32_16x16x32_bf16 v[108:111], v[152:155], v[190:193], v[108:111]
	v_mfma_f32_16x16x32_bf16 v[96:99], v[144:147], v[204:207], v[96:99]
	v_mfma_f32_16x16x32_bf16 v[92:95], v[152:155], v[204:207], v[92:95]
	v_mfma_f32_16x16x32_bf16 v[80:83], v[144:147], v[212:215], v[80:83]
	v_mfma_f32_16x16x32_bf16 v[76:79], v[152:155], v[212:215], v[76:79]
	v_mfma_f32_16x16x32_bf16 v[128:131], v[148:151], v[186:189], v[128:131]
	v_mfma_f32_16x16x32_bf16 v[124:127], v[162:165], v[186:189], v[124:127]
	v_mfma_f32_16x16x32_bf16 v[112:115], v[148:151], v[200:203], v[112:115]
	v_mfma_f32_16x16x32_bf16 v[108:111], v[162:165], v[200:203], v[108:111]
	v_mfma_f32_16x16x32_bf16 v[96:99], v[148:151], v[208:211], v[96:99]
	v_mfma_f32_16x16x32_bf16 v[92:95], v[162:165], v[208:211], v[92:95]
	v_mfma_f32_16x16x32_bf16 v[80:83], v[148:151], v[216:219], v[80:83]
	v_mfma_f32_16x16x32_bf16 v[76:79], v[162:165], v[216:219], v[76:79]
	v_mfma_f32_16x16x32_bf16 v[120:123], v[166:169], v[182:185], v[120:123]
	v_mfma_f32_16x16x32_bf16 v[116:119], v[174:177], v[182:185], v[116:119]
	v_mfma_f32_16x16x32_bf16 v[104:107], v[166:169], v[190:193], v[104:107]
	v_mfma_f32_16x16x32_bf16 v[100:103], v[174:177], v[190:193], v[100:103]
	v_mfma_f32_16x16x32_bf16 v[88:91], v[166:169], v[204:207], v[88:91]
	v_mfma_f32_16x16x32_bf16 v[84:87], v[174:177], v[204:207], v[84:87]
	v_mfma_f32_16x16x32_bf16 v[72:75], v[166:169], v[212:215], v[72:75]
	v_mfma_f32_16x16x32_bf16 v[68:71], v[174:177], v[212:215], v[68:71]
	v_mfma_f32_16x16x32_bf16 v[120:123], v[170:173], v[186:189], v[120:123]
	v_mfma_f32_16x16x32_bf16 v[116:119], v[178:181], v[186:189], v[116:119]
	v_mfma_f32_16x16x32_bf16 v[104:107], v[170:173], v[200:203], v[104:107]
	v_mfma_f32_16x16x32_bf16 v[100:103], v[178:181], v[200:203], v[100:103]
	v_mfma_f32_16x16x32_bf16 v[88:91], v[170:173], v[208:211], v[88:91]
	v_mfma_f32_16x16x32_bf16 v[84:87], v[178:181], v[208:211], v[84:87]
	v_mfma_f32_16x16x32_bf16 v[72:75], v[170:173], v[216:219], v[72:75]
	v_mfma_f32_16x16x32_bf16 v[68:71], v[178:181], v[216:219], v[68:71]
	s_barrier
	s_setprio 0
	s_add_i32 s0, s0, s25
	v_lshl_add_u64 v[194:195], v[194:195], 0, s[90:91]
	s_mov_b32 m0, s0
	ds_read_b128 v[182:185], v161 offset:49152
	ds_read_b128 v[186:189], v161 offset:50176
	ds_read_b128 v[190:193], v161 offset:51200
	ds_read_b128 v[200:203], v161 offset:52224
	ds_read_b128 v[204:207], v161 offset:53248
	ds_read_b128 v[208:211], v161 offset:54272
	ds_read_b128 v[212:215], v161 offset:55296
	ds_read_b128 v[216:219], v161 offset:56320
	global_load_lds_dwordx4 v[194:195], off
	s_add_i32 m0, s0, 0x2000
	s_add_u32 s30, s30, 0x80080
	v_lshl_add_u64 v[194:195], v[198:199], 0, s[90:91]
	s_addc_u32 s31, s31, 0
	s_add_i32 s0, s6, s25
	global_load_lds_dwordx4 v[194:195], off
	v_lshl_add_u64 v[194:195], s[30:31], 0, v[136:137]
	s_mov_b32 m0, s0
	s_nop 0
	global_load_lds_dwordx4 v[194:195], off
	v_lshl_add_u64 v[194:195], s[30:31], 0, v[132:133]
	s_add_i32 m0, s0, 0x2000
	s_nop 0
	global_load_lds_dwordx4 v[194:195], off
	v_lshl_add_u64 v[194:195], v[220:221], 0, s[90:91]
	s_mov_b32 m0, s55
	s_nop 0
	global_load_lds_dwordx4 v[194:195], off
	v_lshl_add_u64 v[194:195], v[222:223], 0, s[90:91]
	s_mov_b32 m0, s60
	s_nop 0
	global_load_lds_dwordx4 v[194:195], off
	s_waitcnt vmcnt(8)
	s_waitcnt lgkmcnt(0)
	s_setprio 1
	s_barrier
	v_mfma_f32_16x16x32_bf16 v[64:67], v[144:147], v[182:185], v[64:67]
	v_mfma_f32_16x16x32_bf16 v[60:63], v[152:155], v[182:185], v[60:63]
	v_mfma_f32_16x16x32_bf16 v[48:51], v[144:147], v[190:193], v[48:51]
	v_mfma_f32_16x16x32_bf16 v[44:47], v[152:155], v[190:193], v[44:47]
	v_mfma_f32_16x16x32_bf16 v[32:35], v[144:147], v[204:207], v[32:35]
	v_mfma_f32_16x16x32_bf16 v[28:31], v[152:155], v[204:207], v[28:31]
	v_mfma_f32_16x16x32_bf16 v[16:19], v[144:147], v[212:215], v[16:19]
	v_mfma_f32_16x16x32_bf16 v[12:15], v[152:155], v[212:215], v[12:15]
	v_mfma_f32_16x16x32_bf16 v[64:67], v[148:151], v[186:189], v[64:67]
	v_mfma_f32_16x16x32_bf16 v[60:63], v[162:165], v[186:189], v[60:63]
	v_mfma_f32_16x16x32_bf16 v[48:51], v[148:151], v[200:203], v[48:51]
	v_mfma_f32_16x16x32_bf16 v[44:47], v[162:165], v[200:203], v[44:47]
	v_mfma_f32_16x16x32_bf16 v[32:35], v[148:151], v[208:211], v[32:35]
	v_mfma_f32_16x16x32_bf16 v[28:31], v[162:165], v[208:211], v[28:31]
	v_mfma_f32_16x16x32_bf16 v[16:19], v[148:151], v[216:219], v[16:19]
	v_mfma_f32_16x16x32_bf16 v[12:15], v[162:165], v[216:219], v[12:15]
	v_mfma_f32_16x16x32_bf16 v[56:59], v[166:169], v[182:185], v[56:59]
	v_mfma_f32_16x16x32_bf16 v[52:55], v[174:177], v[182:185], v[52:55]
	v_mfma_f32_16x16x32_bf16 v[40:43], v[166:169], v[190:193], v[40:43]
	v_mfma_f32_16x16x32_bf16 v[36:39], v[174:177], v[190:193], v[36:39]
	v_mfma_f32_16x16x32_bf16 v[24:27], v[166:169], v[204:207], v[24:27]
	v_mfma_f32_16x16x32_bf16 v[20:23], v[174:177], v[204:207], v[20:23]
	v_mfma_f32_16x16x32_bf16 v[8:11], v[166:169], v[212:215], v[8:11]
	v_mfma_f32_16x16x32_bf16 v[4:7], v[174:177], v[212:215], v[4:7]
	v_mfma_f32_16x16x32_bf16 v[56:59], v[170:173], v[186:189], v[56:59]
	v_mfma_f32_16x16x32_bf16 v[52:55], v[178:181], v[186:189], v[52:55]
	v_mfma_f32_16x16x32_bf16 v[40:43], v[170:173], v[200:203], v[40:43]
	v_mfma_f32_16x16x32_bf16 v[36:39], v[178:181], v[200:203], v[36:39]
	v_mfma_f32_16x16x32_bf16 v[24:27], v[170:173], v[208:211], v[24:27]
	v_mfma_f32_16x16x32_bf16 v[20:23], v[178:181], v[208:211], v[20:23]
	v_mfma_f32_16x16x32_bf16 v[8:11], v[170:173], v[216:219], v[8:11]
	v_mfma_f32_16x16x32_bf16 v[4:7], v[178:181], v[216:219], v[4:7]
	s_barrier
	s_setprio 0
	s_add_i32 s66, s66, 2
	s_add_u32 s36, s36, 0x100
	s_addc_u32 s37, s37, 0
	s_add_u32 s38, s38, 0x100
	s_addc_u32 s39, s39, 0
	s_cmp_gt_u32 s66, 29
	s_cbranch_scc0 .LBB0_1137
	s_and_b64 vcc, exec, s[20:21]
	s_cbranch_vccz .LBB0_1140
	s_barrier

.LBB0_1167:
	s_add_u32 s0, s36, 0xfff80080
	s_addc_u32 s6, s37, -1
	s_add_i32 s49, 0, 0x10000
	s_cmp_eq_u32 s67, 28
	s_cselect_b32 s35, s43, s6
	s_cselect_b32 s34, s65, s0
	v_add_u32_e32 v156, s49, v157
	s_cselect_b32 s31, s29, s39
	s_cselect_b32 s30, s66, s38
	s_add_i32 s0, 0, 0x14000
	ds_read_b128 v[144:147], v156
	ds_read_b128 v[148:151], v156 offset:1024
	ds_read_b128 v[152:155], v156 offset:2048
	ds_read_b128 v[162:165], v156 offset:3072
	v_add_u32_e32 v156, s0, v157
	ds_read_b128 v[166:169], v156
	ds_read_b128 v[170:173], v156 offset:1024
	ds_read_b128 v[174:177], v156 offset:2048
	ds_read_b128 v[178:181], v156 offset:3072
	v_lshl_add_u64 v[194:195], s[36:37], 0, v[140:141]
	s_add_i32 m0, s25, 0xc000
	ds_read_b128 v[182:185], v161
	ds_read_b128 v[186:189], v161 offset:1024
	ds_read_b128 v[190:193], v161 offset:2048
	ds_read_b128 v[200:203], v161 offset:3072
	ds_read_b128 v[204:207], v161 offset:4096
	ds_read_b128 v[208:211], v161 offset:5120
	ds_read_b128 v[212:215], v161 offset:6144
	ds_read_b128 v[216:219], v161 offset:7168
	global_load_lds_dwordx4 v[194:195], off
	v_lshl_add_u64 v[194:195], s[36:37], 0, v[142:143]
	s_add_i32 m0, s25, 0xe000
	s_nop 0
	global_load_lds_dwordx4 v[194:195], off
	s_waitcnt vmcnt(8)
	s_waitcnt lgkmcnt(0)
	s_setprio 1
	s_barrier
	v_mfma_f32_16x16x32_bf16 v[128:131], v[144:147], v[182:185], v[128:131]
	v_mfma_f32_16x16x32_bf16 v[124:127], v[152:155], v[182:185], v[124:127]
	v_mfma_f32_16x16x32_bf16 v[112:115], v[144:147], v[190:193], v[112:115]
	v_mfma_f32_16x16x32_bf16 v[108:111], v[152:155], v[190:193], v[108:111]
	v_mfma_f32_16x16x32_bf16 v[96:99], v[144:147], v[204:207], v[96:99]
	v_mfma_f32_16x16x32_bf16 v[92:95], v[152:155], v[204:207], v[92:95]
	v_mfma_f32_16x16x32_bf16 v[80:83], v[144:147], v[212:215], v[80:83]
	v_mfma_f32_16x16x32_bf16 v[76:79], v[152:155], v[212:215], v[76:79]
	v_mfma_f32_16x16x32_bf16 v[128:131], v[148:151], v[186:189], v[128:131]
	v_mfma_f32_16x16x32_bf16 v[124:127], v[162:165], v[186:189], v[124:127]
	v_mfma_f32_16x16x32_bf16 v[112:115], v[148:151], v[200:203], v[112:115]
	v_mfma_f32_16x16x32_bf16 v[108:111], v[162:165], v[200:203], v[108:111]
	v_mfma_f32_16x16x32_bf16 v[96:99], v[148:151], v[208:211], v[96:99]
	v_mfma_f32_16x16x32_bf16 v[92:95], v[162:165], v[208:211], v[92:95]
	v_mfma_f32_16x16x32_bf16 v[80:83], v[148:151], v[216:219], v[80:83]
	v_mfma_f32_16x16x32_bf16 v[76:79], v[162:165], v[216:219], v[76:79]
	v_mfma_f32_16x16x32_bf16 v[120:123], v[166:169], v[182:185], v[120:123]
	v_mfma_f32_16x16x32_bf16 v[116:119], v[174:177], v[182:185], v[116:119]
	v_mfma_f32_16x16x32_bf16 v[104:107], v[166:169], v[190:193], v[104:107]
	v_mfma_f32_16x16x32_bf16 v[100:103], v[174:177], v[190:193], v[100:103]
	v_mfma_f32_16x16x32_bf16 v[88:91], v[166:169], v[204:207], v[88:91]
	v_mfma_f32_16x16x32_bf16 v[84:87], v[174:177], v[204:207], v[84:87]
	v_mfma_f32_16x16x32_bf16 v[72:75], v[166:169], v[212:215], v[72:75]
	v_mfma_f32_16x16x32_bf16 v[68:71], v[174:177], v[212:215], v[68:71]
	v_mfma_f32_16x16x32_bf16 v[120:123], v[170:173], v[186:189], v[120:123]
	v_mfma_f32_16x16x32_bf16 v[116:119], v[178:181], v[186:189], v[116:119]
	v_mfma_f32_16x16x32_bf16 v[104:107], v[170:173], v[200:203], v[104:107]
	v_mfma_f32_16x16x32_bf16 v[100:103], v[178:181], v[200:203], v[100:103]
	v_mfma_f32_16x16x32_bf16 v[88:91], v[170:173], v[208:211], v[88:91]
	v_mfma_f32_16x16x32_bf16 v[84:87], v[178:181], v[208:211], v[84:87]
	v_mfma_f32_16x16x32_bf16 v[72:75], v[170:173], v[216:219], v[72:75]
	v_mfma_f32_16x16x32_bf16 v[68:71], v[178:181], v[216:219], v[68:71]
	s_barrier
	s_setprio 0
	s_add_i32 s6, s49, s1
	v_lshl_add_u64 v[194:195], s[30:31], 0, v[136:137]
	s_mov_b32 m0, s6
	ds_read_b128 v[182:185], v161 offset:16384
	ds_read_b128 v[186:189], v161 offset:17408
	ds_read_b128 v[190:193], v161 offset:18432
	ds_read_b128 v[200:203], v161 offset:19456
	ds_read_b128 v[204:207], v161 offset:20480
	ds_read_b128 v[208:211], v161 offset:21504
	ds_read_b128 v[212:215], v161 offset:22528
	ds_read_b128 v[216:219], v161 offset:23552
	global_load_lds_dwordx4 v[194:195], off
	s_add_i32 m0, s6, 0x2000
	s_add_u32 s68, s30, 0x80000
	v_lshl_add_u64 v[198:199], s[30:31], 0, v[132:133]
	s_addc_u32 s69, s31, 0
	s_add_i32 s0, s0, s1
	global_load_lds_dwordx4 v[198:199], off
	v_lshl_add_u64 v[220:221], s[68:69], 0, v[136:137]
	s_mov_b32 m0, s0
	v_lshl_add_u64 v[222:223], s[34:35], 0, v[134:135]
	global_load_lds_dwordx4 v[220:221], off
	v_lshl_add_u64 v[220:221], s[68:69], 0, v[132:133]
	s_add_i32 m0, s0, 0x2000
	s_nop 0
	global_load_lds_dwordx4 v[220:221], off
	v_lshl_add_u64 v[220:221], s[34:35], 0, v[138:139]
	s_mov_b32 m0, s25
	s_nop 0
	global_load_lds_dwordx4 v[220:221], off
	s_mov_b32 m0, s33
	s_nop 0
	global_load_lds_dwordx4 v[222:223], off
	s_waitcnt vmcnt(8)
	s_waitcnt lgkmcnt(0)
	s_setprio 1
	s_barrier
	v_mfma_f32_16x16x32_bf16 v[64:67], v[144:147], v[182:185], v[64:67]
	v_mfma_f32_16x16x32_bf16 v[60:63], v[152:155], v[182:185], v[60:63]
	v_mfma_f32_16x16x32_bf16 v[48:51], v[144:147], v[190:193], v[48:51]
	v_mfma_f32_16x16x32_bf16 v[44:47], v[152:155], v[190:193], v[44:47]
	v_mfma_f32_16x16x32_bf16 v[32:35], v[144:147], v[204:207], v[32:35]
	v_mfma_f32_16x16x32_bf16 v[28:31], v[152:155], v[204:207], v[28:31]
	v_mfma_f32_16x16x32_bf16 v[16:19], v[144:147], v[212:215], v[16:19]
	v_mfma_f32_16x16x32_bf16 v[12:15], v[152:155], v[212:215], v[12:15]
	v_mfma_f32_16x16x32_bf16 v[64:67], v[148:151], v[186:189], v[64:67]
	v_mfma_f32_16x16x32_bf16 v[60:63], v[162:165], v[186:189], v[60:63]
	v_mfma_f32_16x16x32_bf16 v[48:51], v[148:151], v[200:203], v[48:51]
	v_mfma_f32_16x16x32_bf16 v[44:47], v[162:165], v[200:203], v[44:47]
	v_mfma_f32_16x16x32_bf16 v[32:35], v[148:151], v[208:211], v[32:35]
	v_mfma_f32_16x16x32_bf16 v[28:31], v[162:165], v[208:211], v[28:31]
	v_mfma_f32_16x16x32_bf16 v[16:19], v[148:151], v[216:219], v[16:19]
	v_mfma_f32_16x16x32_bf16 v[12:15], v[162:165], v[216:219], v[12:15]
	v_mfma_f32_16x16x32_bf16 v[56:59], v[166:169], v[182:185], v[56:59]
	v_mfma_f32_16x16x32_bf16 v[52:55], v[174:177], v[182:185], v[52:55]
	v_mfma_f32_16x16x32_bf16 v[40:43], v[166:169], v[190:193], v[40:43]
	v_mfma_f32_16x16x32_bf16 v[36:39], v[174:177], v[190:193], v[36:39]
	v_mfma_f32_16x16x32_bf16 v[24:27], v[166:169], v[204:207], v[24:27]
	v_mfma_f32_16x16x32_bf16 v[20:23], v[174:177], v[204:207], v[20:23]
	v_mfma_f32_16x16x32_bf16 v[8:11], v[166:169], v[212:215], v[8:11]
	v_mfma_f32_16x16x32_bf16 v[4:7], v[174:177], v[212:215], v[4:7]
	v_mfma_f32_16x16x32_bf16 v[56:59], v[170:173], v[186:189], v[56:59]
	v_mfma_f32_16x16x32_bf16 v[52:55], v[178:181], v[186:189], v[52:55]
	v_mfma_f32_16x16x32_bf16 v[40:43], v[170:173], v[200:203], v[40:43]
	v_mfma_f32_16x16x32_bf16 v[36:39], v[178:181], v[200:203], v[36:39]
	v_mfma_f32_16x16x32_bf16 v[24:27], v[170:173], v[208:211], v[24:27]
	v_mfma_f32_16x16x32_bf16 v[20:23], v[178:181], v[208:211], v[20:23]
	v_mfma_f32_16x16x32_bf16 v[8:11], v[170:173], v[216:219], v[8:11]
	v_mfma_f32_16x16x32_bf16 v[4:7], v[178:181], v[216:219], v[4:7]
	s_barrier
	s_setprio 0
	s_add_i32 s0, 0, 0x18000
	v_add_u32_e32 v156, s0, v157
	s_add_i32 s6, 0, 0x1c000
	ds_read_b128 v[144:147], v156
	ds_read_b128 v[148:151], v156 offset:1024
	ds_read_b128 v[152:155], v156 offset:2048
	ds_read_b128 v[162:165], v156 offset:3072
	v_add_u32_e32 v156, s6, v157
	ds_read_b128 v[166:169], v156
	ds_read_b128 v[170:173], v156 offset:1024
	ds_read_b128 v[174:177], v156 offset:2048
	ds_read_b128 v[178:181], v156 offset:3072
	s_add_u32 s34, s34, 0x80000
	s_addc_u32 s35, s35, 0
	s_mov_b32 m0, s40
	v_lshl_add_u64 v[224:225], s[34:35], 0, v[138:139]
	ds_read_b128 v[182:185], v161 offset:32768
	ds_read_b128 v[186:189], v161 offset:33792
	ds_read_b128 v[190:193], v161 offset:34816
	ds_read_b128 v[200:203], v161 offset:35840
	ds_read_b128 v[204:207], v161 offset:36864
	ds_read_b128 v[208:211], v161 offset:37888
	ds_read_b128 v[212:215], v161 offset:38912
	ds_read_b128 v[216:219], v161 offset:39936
	global_load_lds_dwordx4 v[224:225], off
	v_lshl_add_u64 v[224:225], s[34:35], 0, v[134:135]
	s_mov_b32 m0, s50
	s_nop 0
	global_load_lds_dwordx4 v[224:225], off
	s_waitcnt vmcnt(8)
	s_waitcnt lgkmcnt(0)
	s_setprio 1
	s_barrier
	v_mfma_f32_16x16x32_bf16 v[128:131], v[144:147], v[182:185], v[128:131]
	v_mfma_f32_16x16x32_bf16 v[124:127], v[152:155], v[182:185], v[124:127]
	v_mfma_f32_16x16x32_bf16 v[112:115], v[144:147], v[190:193], v[112:115]
	v_mfma_f32_16x16x32_bf16 v[108:111], v[152:155], v[190:193], v[108:111]
	v_mfma_f32_16x16x32_bf16 v[96:99], v[144:147], v[204:207], v[96:99]
	v_mfma_f32_16x16x32_bf16 v[92:95], v[152:155], v[204:207], v[92:95]
	v_mfma_f32_16x16x32_bf16 v[80:83], v[144:147], v[212:215], v[80:83]
	v_mfma_f32_16x16x32_bf16 v[76:79], v[152:155], v[212:215], v[76:79]
	v_mfma_f32_16x16x32_bf16 v[128:131], v[148:151], v[186:189], v[128:131]
	v_mfma_f32_16x16x32_bf16 v[124:127], v[162:165], v[186:189], v[124:127]
	v_mfma_f32_16x16x32_bf16 v[112:115], v[148:151], v[200:203], v[112:115]
	v_mfma_f32_16x16x32_bf16 v[108:111], v[162:165], v[200:203], v[108:111]
	v_mfma_f32_16x16x32_bf16 v[96:99], v[148:151], v[208:211], v[96:99]
	v_mfma_f32_16x16x32_bf16 v[92:95], v[162:165], v[208:211], v[92:95]
	v_mfma_f32_16x16x32_bf16 v[80:83], v[148:151], v[216:219], v[80:83]
	v_mfma_f32_16x16x32_bf16 v[76:79], v[162:165], v[216:219], v[76:79]
	v_mfma_f32_16x16x32_bf16 v[120:123], v[166:169], v[182:185], v[120:123]
	v_mfma_f32_16x16x32_bf16 v[116:119], v[174:177], v[182:185], v[116:119]
	v_mfma_f32_16x16x32_bf16 v[104:107], v[166:169], v[190:193], v[104:107]
	v_mfma_f32_16x16x32_bf16 v[100:103], v[174:177], v[190:193], v[100:103]
	v_mfma_f32_16x16x32_bf16 v[88:91], v[166:169], v[204:207], v[88:91]
	v_mfma_f32_16x16x32_bf16 v[84:87], v[174:177], v[204:207], v[84:87]
	v_mfma_f32_16x16x32_bf16 v[72:75], v[166:169], v[212:215], v[72:75]
	v_mfma_f32_16x16x32_bf16 v[68:71], v[174:177], v[212:215], v[68:71]
	v_mfma_f32_16x16x32_bf16 v[120:123], v[170:173], v[186:189], v[120:123]
	v_mfma_f32_16x16x32_bf16 v[116:119], v[178:181], v[186:189], v[116:119]
	v_mfma_f32_16x16x32_bf16 v[104:107], v[170:173], v[200:203], v[104:107]
	v_mfma_f32_16x16x32_bf16 v[100:103], v[178:181], v[200:203], v[100:103]
	v_mfma_f32_16x16x32_bf16 v[88:91], v[170:173], v[208:211], v[88:91]
	v_mfma_f32_16x16x32_bf16 v[84:87], v[178:181], v[208:211], v[84:87]
	v_mfma_f32_16x16x32_bf16 v[72:75], v[170:173], v[216:219], v[72:75]
	v_mfma_f32_16x16x32_bf16 v[68:71], v[178:181], v[216:219], v[68:71]
	s_barrier
	s_setprio 0
	s_add_i32 s0, s0, s1
	v_lshl_add_u64 v[194:195], v[194:195], 0, s[90:91]
	s_mov_b32 m0, s0
	ds_read_b128 v[182:185], v161 offset:49152
	ds_read_b128 v[186:189], v161 offset:50176
	ds_read_b128 v[190:193], v161 offset:51200
	ds_read_b128 v[200:203], v161 offset:52224
	ds_read_b128 v[204:207], v161 offset:53248
	ds_read_b128 v[208:211], v161 offset:54272
	ds_read_b128 v[212:215], v161 offset:55296
	ds_read_b128 v[216:219], v161 offset:56320
	global_load_lds_dwordx4 v[194:195], off
	s_add_i32 m0, s0, 0x2000
	s_add_u32 s30, s30, 0x80080
	v_lshl_add_u64 v[194:195], v[198:199], 0, s[90:91]
	s_addc_u32 s31, s31, 0
	s_add_i32 s0, s6, s1
	global_load_lds_dwordx4 v[194:195], off
	v_lshl_add_u64 v[194:195], s[30:31], 0, v[136:137]
	s_mov_b32 m0, s0
	s_nop 0
	global_load_lds_dwordx4 v[194:195], off
	v_lshl_add_u64 v[194:195], s[30:31], 0, v[132:133]
	s_add_i32 m0, s0, 0x2000
	s_nop 0
	global_load_lds_dwordx4 v[194:195], off
	v_lshl_add_u64 v[194:195], v[220:221], 0, s[90:91]
	s_mov_b32 m0, s51
	s_nop 0
	global_load_lds_dwordx4 v[194:195], off
	v_lshl_add_u64 v[194:195], v[222:223], 0, s[90:91]
	s_mov_b32 m0, s55
	s_nop 0
	global_load_lds_dwordx4 v[194:195], off
	s_waitcnt vmcnt(8)
	s_waitcnt lgkmcnt(0)
	s_setprio 1
	s_barrier
	v_mfma_f32_16x16x32_bf16 v[64:67], v[144:147], v[182:185], v[64:67]
	v_mfma_f32_16x16x32_bf16 v[60:63], v[152:155], v[182:185], v[60:63]
	v_mfma_f32_16x16x32_bf16 v[48:51], v[144:147], v[190:193], v[48:51]
	v_mfma_f32_16x16x32_bf16 v[44:47], v[152:155], v[190:193], v[44:47]
	v_mfma_f32_16x16x32_bf16 v[32:35], v[144:147], v[204:207], v[32:35]
	v_mfma_f32_16x16x32_bf16 v[28:31], v[152:155], v[204:207], v[28:31]
	v_mfma_f32_16x16x32_bf16 v[16:19], v[144:147], v[212:215], v[16:19]
	v_mfma_f32_16x16x32_bf16 v[12:15], v[152:155], v[212:215], v[12:15]
	v_mfma_f32_16x16x32_bf16 v[64:67], v[148:151], v[186:189], v[64:67]
	v_mfma_f32_16x16x32_bf16 v[60:63], v[162:165], v[186:189], v[60:63]
	v_mfma_f32_16x16x32_bf16 v[48:51], v[148:151], v[200:203], v[48:51]
	v_mfma_f32_16x16x32_bf16 v[44:47], v[162:165], v[200:203], v[44:47]
	v_mfma_f32_16x16x32_bf16 v[32:35], v[148:151], v[208:211], v[32:35]
	v_mfma_f32_16x16x32_bf16 v[28:31], v[162:165], v[208:211], v[28:31]
	v_mfma_f32_16x16x32_bf16 v[16:19], v[148:151], v[216:219], v[16:19]
	v_mfma_f32_16x16x32_bf16 v[12:15], v[162:165], v[216:219], v[12:15]
	v_mfma_f32_16x16x32_bf16 v[56:59], v[166:169], v[182:185], v[56:59]
	v_mfma_f32_16x16x32_bf16 v[52:55], v[174:177], v[182:185], v[52:55]
	v_mfma_f32_16x16x32_bf16 v[40:43], v[166:169], v[190:193], v[40:43]
	v_mfma_f32_16x16x32_bf16 v[36:39], v[174:177], v[190:193], v[36:39]
	v_mfma_f32_16x16x32_bf16 v[24:27], v[166:169], v[204:207], v[24:27]
	v_mfma_f32_16x16x32_bf16 v[20:23], v[174:177], v[204:207], v[20:23]
	v_mfma_f32_16x16x32_bf16 v[8:11], v[166:169], v[212:215], v[8:11]
	v_mfma_f32_16x16x32_bf16 v[4:7], v[174:177], v[212:215], v[4:7]
	v_mfma_f32_16x16x32_bf16 v[56:59], v[170:173], v[186:189], v[56:59]
	v_mfma_f32_16x16x32_bf16 v[52:55], v[178:181], v[186:189], v[52:55]
	v_mfma_f32_16x16x32_bf16 v[40:43], v[170:173], v[200:203], v[40:43]
	v_mfma_f32_16x16x32_bf16 v[36:39], v[178:181], v[200:203], v[36:39]
	v_mfma_f32_16x16x32_bf16 v[24:27], v[170:173], v[208:211], v[24:27]
	v_mfma_f32_16x16x32_bf16 v[20:23], v[178:181], v[208:211], v[20:23]
	v_mfma_f32_16x16x32_bf16 v[8:11], v[170:173], v[216:219], v[8:11]
	v_mfma_f32_16x16x32_bf16 v[4:7], v[178:181], v[216:219], v[4:7]
	s_barrier
	s_setprio 0
	s_add_i32 s67, s67, 2
	s_add_u32 s36, s36, 0x100
	s_addc_u32 s37, s37, 0
	s_add_u32 s38, s38, 0x100
	s_addc_u32 s39, s39, 0
	s_cmp_gt_u32 s67, 29
	s_cbranch_scc0 .LBB0_1167
	s_and_b64 vcc, exec, s[20:21]
	s_cbranch_vccz .LBB0_1170
	s_barrier

.LBB0_1186:
	s_add_u32 s0, s64, s30
	s_addc_u32 s6, s65, 0
	s_add_u32 s31, s0, 0x100
	s_addc_u32 s38, s6, 0
	s_and_b64 s[34:35], s[36:37], exec
	s_cselect_b32 s69, s29, s38
	s_cselect_b32 s68, s77, s31
	s_add_u32 s30, s62, s30
	s_addc_u32 s31, s63, 0
	s_add_u32 s34, s30, 0x100
	s_addc_u32 s35, s31, 0
	s_add_i32 s82, 0, 0x10000
	s_and_b64 s[30:31], s[36:37], exec
	s_cselect_b32 s53, s23, s35
	s_cselect_b32 s52, s78, s34
	s_add_i32 s37, 0, 0x14000
	s_add_u32 s34, s0, 0x10080
	s_addc_u32 s35, s6, 0
	s_add_i32 s84, s82, s4
	s_add_i32 m0, s46, 0xc000
	s_add_i32 s85, s46, 0xe000
	s_add_i32 s6, s84, 0x2000
	v_add_u32_e32 v140, s82, v142
	s_add_u32 s30, s52, 0x10000
	ds_read_b128 v[146:149], v140
	ds_read_b128 v[150:153], v140 offset:1024
	ds_read_b128 v[154:157], v140 offset:2048
	ds_read_b128 v[158:161], v140 offset:3072
	v_add_u32_e32 v140, s37, v142
	s_addc_u32 s31, s53, 0
	s_add_i32 s49, s37, s4
	ds_read_b128 v[162:165], v140
	ds_read_b128 v[166:169], v140 offset:1024
	ds_read_b128 v[170:173], v140 offset:2048
	ds_read_b128 v[174:177], v140 offset:3072
	s_add_i32 s81, s49, 0x2000
	s_add_i32 s54, 0, 0x18000
	s_add_i32 s73, 0, 0x1c000
	s_add_u32 s38, s68, 0x10000
	s_addc_u32 s39, s69, 0
	s_add_i32 s0, s54, s4
	s_add_i32 s80, s0, 0x2000
	s_add_u32 s36, s52, 0x10080
	s_addc_u32 s37, s53, 0
	s_add_i32 s83, s73, s4
	s_add_i32 s82, s83, 0x2000
	v_lshl_add_u64 v[140:141], s[34:35], 0, v[138:139]
	ds_read_b128 v[178:181], v144
	ds_read_b128 v[182:185], v144 offset:1024
	ds_read_b128 v[186:189], v144 offset:2048
	ds_read_b128 v[190:193], v144 offset:3072
	ds_read_b128 v[200:203], v144 offset:4096
	ds_read_b128 v[204:207], v144 offset:5120
	ds_read_b128 v[208:211], v144 offset:6144
	ds_read_b128 v[212:215], v144 offset:7168
	global_load_lds_dwordx4 v[140:141], off
	v_lshl_add_u64 v[140:141], s[34:35], 0, v[134:135]
	s_mov_b32 m0, s85
	s_nop 0
	global_load_lds_dwordx4 v[140:141], off
	s_waitcnt vmcnt(8)
	s_waitcnt lgkmcnt(0)
	s_setprio 1
	s_barrier
	v_mfma_f32_16x16x32_bf16 v[128:131], v[146:149], v[178:181], v[128:131]
	v_mfma_f32_16x16x32_bf16 v[124:127], v[154:157], v[178:181], v[124:127]
	v_mfma_f32_16x16x32_bf16 v[120:123], v[146:149], v[186:189], v[120:123]
	v_mfma_f32_16x16x32_bf16 v[112:115], v[154:157], v[186:189], v[112:115]
	v_mfma_f32_16x16x32_bf16 v[104:107], v[146:149], v[200:203], v[104:107]
	v_mfma_f32_16x16x32_bf16 v[96:99], v[154:157], v[200:203], v[96:99]
	v_mfma_f32_16x16x32_bf16 v[88:91], v[146:149], v[208:211], v[88:91]
	v_mfma_f32_16x16x32_bf16 v[80:83], v[154:157], v[208:211], v[80:83]
	v_mfma_f32_16x16x32_bf16 v[128:131], v[150:153], v[182:185], v[128:131]
	v_mfma_f32_16x16x32_bf16 v[124:127], v[158:161], v[182:185], v[124:127]
	v_mfma_f32_16x16x32_bf16 v[120:123], v[150:153], v[190:193], v[120:123]
	v_mfma_f32_16x16x32_bf16 v[112:115], v[158:161], v[190:193], v[112:115]
	v_mfma_f32_16x16x32_bf16 v[104:107], v[150:153], v[204:207], v[104:107]
	v_mfma_f32_16x16x32_bf16 v[96:99], v[158:161], v[204:207], v[96:99]
	v_mfma_f32_16x16x32_bf16 v[88:91], v[150:153], v[212:215], v[88:91]
	v_mfma_f32_16x16x32_bf16 v[80:83], v[158:161], v[212:215], v[80:83]
	v_mfma_f32_16x16x32_bf16 v[116:119], v[162:165], v[178:181], v[116:119]
	v_mfma_f32_16x16x32_bf16 v[108:111], v[170:173], v[178:181], v[108:111]
	v_mfma_f32_16x16x32_bf16 v[100:103], v[162:165], v[186:189], v[100:103]
	v_mfma_f32_16x16x32_bf16 v[92:95], v[170:173], v[186:189], v[92:95]
	v_mfma_f32_16x16x32_bf16 v[84:87], v[162:165], v[200:203], v[84:87]
	v_mfma_f32_16x16x32_bf16 v[76:79], v[170:173], v[200:203], v[76:79]
	v_mfma_f32_16x16x32_bf16 v[72:75], v[162:165], v[208:211], v[72:75]
	v_mfma_f32_16x16x32_bf16 v[68:71], v[170:173], v[208:211], v[68:71]
	v_mfma_f32_16x16x32_bf16 v[116:119], v[166:169], v[182:185], v[116:119]
	v_mfma_f32_16x16x32_bf16 v[108:111], v[174:177], v[182:185], v[108:111]
	v_mfma_f32_16x16x32_bf16 v[100:103], v[166:169], v[190:193], v[100:103]
	v_mfma_f32_16x16x32_bf16 v[92:95], v[174:177], v[190:193], v[92:95]
	v_mfma_f32_16x16x32_bf16 v[84:87], v[166:169], v[204:207], v[84:87]
	v_mfma_f32_16x16x32_bf16 v[76:79], v[174:177], v[204:207], v[76:79]
	v_mfma_f32_16x16x32_bf16 v[72:75], v[166:169], v[212:215], v[72:75]
	v_mfma_f32_16x16x32_bf16 v[68:71], v[174:177], v[212:215], v[68:71]
	s_barrier
	s_setprio 0
	s_mov_b32 m0, s84
	v_lshl_add_u64 v[140:141], s[52:53], 0, v[136:137]
	ds_read_b128 v[178:181], v144 offset:16384
	ds_read_b128 v[182:185], v144 offset:17408
	ds_read_b128 v[186:189], v144 offset:18432
	ds_read_b128 v[190:193], v144 offset:19456
	ds_read_b128 v[200:203], v144 offset:20480
	ds_read_b128 v[204:207], v144 offset:21504
	ds_read_b128 v[208:211], v144 offset:22528
	ds_read_b128 v[212:215], v144 offset:23552
	global_load_lds_dwordx4 v[140:141], off
	v_lshl_add_u64 v[194:195], s[52:53], 0, v[132:133]
	s_mov_b32 m0, s6
	v_lshl_add_u64 v[198:199], s[30:31], 0, v[136:137]
	global_load_lds_dwordx4 v[194:195], off
	s_mov_b32 m0, s49
	v_lshl_add_u64 v[216:217], s[68:69], 0, v[134:135]
	global_load_lds_dwordx4 v[198:199], off
	v_lshl_add_u64 v[198:199], s[30:31], 0, v[132:133]
	s_mov_b32 m0, s81
	s_nop 0
	global_load_lds_dwordx4 v[198:199], off
	v_lshl_add_u64 v[198:199], s[68:69], 0, v[138:139]
	s_mov_b32 m0, s46
	s_nop 0
	global_load_lds_dwordx4 v[198:199], off
	s_mov_b32 m0, s47
	s_nop 0
	global_load_lds_dwordx4 v[216:217], off
	s_waitcnt vmcnt(8)
	s_waitcnt lgkmcnt(0)
	s_setprio 1
	s_barrier
	v_mfma_f32_16x16x32_bf16 v[64:67], v[146:149], v[178:181], v[64:67]
	v_mfma_f32_16x16x32_bf16 v[60:63], v[154:157], v[178:181], v[60:63]
	v_mfma_f32_16x16x32_bf16 v[56:59], v[146:149], v[186:189], v[56:59]
	v_mfma_f32_16x16x32_bf16 v[48:51], v[154:157], v[186:189], v[48:51]
	v_mfma_f32_16x16x32_bf16 v[40:43], v[146:149], v[200:203], v[40:43]
	v_mfma_f32_16x16x32_bf16 v[32:35], v[154:157], v[200:203], v[32:35]
	v_mfma_f32_16x16x32_bf16 v[24:27], v[146:149], v[208:211], v[24:27]
	v_mfma_f32_16x16x32_bf16 v[16:19], v[154:157], v[208:211], v[16:19]
	v_mfma_f32_16x16x32_bf16 v[64:67], v[150:153], v[182:185], v[64:67]
	v_mfma_f32_16x16x32_bf16 v[60:63], v[158:161], v[182:185], v[60:63]
	v_mfma_f32_16x16x32_bf16 v[56:59], v[150:153], v[190:193], v[56:59]
	v_mfma_f32_16x16x32_bf16 v[48:51], v[158:161], v[190:193], v[48:51]
	v_mfma_f32_16x16x32_bf16 v[40:43], v[150:153], v[204:207], v[40:43]
	v_mfma_f32_16x16x32_bf16 v[32:35], v[158:161], v[204:207], v[32:35]
	v_mfma_f32_16x16x32_bf16 v[24:27], v[150:153], v[212:215], v[24:27]
	v_mfma_f32_16x16x32_bf16 v[16:19], v[158:161], v[212:215], v[16:19]
	v_mfma_f32_16x16x32_bf16 v[52:55], v[162:165], v[178:181], v[52:55]
	v_mfma_f32_16x16x32_bf16 v[44:47], v[170:173], v[178:181], v[44:47]
	v_mfma_f32_16x16x32_bf16 v[36:39], v[162:165], v[186:189], v[36:39]
	v_mfma_f32_16x16x32_bf16 v[28:31], v[170:173], v[186:189], v[28:31]
	v_mfma_f32_16x16x32_bf16 v[20:23], v[162:165], v[200:203], v[20:23]
	v_mfma_f32_16x16x32_bf16 v[12:15], v[170:173], v[200:203], v[12:15]
	v_mfma_f32_16x16x32_bf16 v[8:11], v[162:165], v[208:211], v[8:11]
	v_mfma_f32_16x16x32_bf16 v[4:7], v[170:173], v[208:211], v[4:7]
	v_mfma_f32_16x16x32_bf16 v[52:55], v[166:169], v[182:185], v[52:55]
	v_mfma_f32_16x16x32_bf16 v[44:47], v[174:177], v[182:185], v[44:47]
	v_mfma_f32_16x16x32_bf16 v[36:39], v[166:169], v[190:193], v[36:39]
	v_mfma_f32_16x16x32_bf16 v[28:31], v[174:177], v[190:193], v[28:31]
	v_mfma_f32_16x16x32_bf16 v[20:23], v[166:169], v[204:207], v[20:23]
	v_mfma_f32_16x16x32_bf16 v[12:15], v[174:177], v[204:207], v[12:15]
	v_mfma_f32_16x16x32_bf16 v[8:11], v[166:169], v[212:215], v[8:11]
	v_mfma_f32_16x16x32_bf16 v[4:7], v[174:177], v[212:215], v[4:7]
	s_barrier
	s_setprio 0
	v_add_u32_e32 v145, s54, v142
	ds_read_b128 v[146:149], v145
	ds_read_b128 v[150:153], v145 offset:1024
	ds_read_b128 v[154:157], v145 offset:2048
	ds_read_b128 v[158:161], v145 offset:3072
	v_add_u32_e32 v145, s73, v142
	ds_read_b128 v[162:165], v145
	ds_read_b128 v[166:169], v145 offset:1024
	ds_read_b128 v[170:173], v145 offset:2048
	ds_read_b128 v[174:177], v145 offset:3072
	s_mov_b32 m0, s50
	v_lshl_add_u64 v[218:219], s[38:39], 0, v[138:139]
	ds_read_b128 v[178:181], v144 offset:32768
	ds_read_b128 v[182:185], v144 offset:33792
	ds_read_b128 v[186:189], v144 offset:34816
	ds_read_b128 v[190:193], v144 offset:35840
	ds_read_b128 v[200:203], v144 offset:36864
	ds_read_b128 v[204:207], v144 offset:37888
	ds_read_b128 v[208:211], v144 offset:38912
	ds_read_b128 v[212:215], v144 offset:39936
	global_load_lds_dwordx4 v[218:219], off
	v_lshl_add_u64 v[218:219], s[38:39], 0, v[134:135]
	s_mov_b32 m0, s51
	s_nop 0
	global_load_lds_dwordx4 v[218:219], off
	s_waitcnt vmcnt(8)
	s_waitcnt lgkmcnt(0)
	s_setprio 1
	s_barrier
	v_mfma_f32_16x16x32_bf16 v[128:131], v[146:149], v[178:181], v[128:131]
	v_mfma_f32_16x16x32_bf16 v[124:127], v[154:157], v[178:181], v[124:127]
	v_mfma_f32_16x16x32_bf16 v[120:123], v[146:149], v[186:189], v[120:123]
	v_mfma_f32_16x16x32_bf16 v[112:115], v[154:157], v[186:189], v[112:115]
	v_mfma_f32_16x16x32_bf16 v[104:107], v[146:149], v[200:203], v[104:107]
	v_mfma_f32_16x16x32_bf16 v[96:99], v[154:157], v[200:203], v[96:99]
	v_mfma_f32_16x16x32_bf16 v[88:91], v[146:149], v[208:211], v[88:91]
	v_mfma_f32_16x16x32_bf16 v[80:83], v[154:157], v[208:211], v[80:83]
	v_mfma_f32_16x16x32_bf16 v[128:131], v[150:153], v[182:185], v[128:131]
	v_mfma_f32_16x16x32_bf16 v[124:127], v[158:161], v[182:185], v[124:127]
	v_mfma_f32_16x16x32_bf16 v[120:123], v[150:153], v[190:193], v[120:123]
	v_mfma_f32_16x16x32_bf16 v[112:115], v[158:161], v[190:193], v[112:115]
	v_mfma_f32_16x16x32_bf16 v[104:107], v[150:153], v[204:207], v[104:107]
	v_mfma_f32_16x16x32_bf16 v[96:99], v[158:161], v[204:207], v[96:99]
	v_mfma_f32_16x16x32_bf16 v[88:91], v[150:153], v[212:215], v[88:91]
	v_mfma_f32_16x16x32_bf16 v[80:83], v[158:161], v[212:215], v[80:83]
	v_mfma_f32_16x16x32_bf16 v[116:119], v[162:165], v[178:181], v[116:119]
	v_mfma_f32_16x16x32_bf16 v[108:111], v[170:173], v[178:181], v[108:111]
	v_mfma_f32_16x16x32_bf16 v[100:103], v[162:165], v[186:189], v[100:103]
	v_mfma_f32_16x16x32_bf16 v[92:95], v[170:173], v[186:189], v[92:95]
	v_mfma_f32_16x16x32_bf16 v[84:87], v[162:165], v[200:203], v[84:87]
	v_mfma_f32_16x16x32_bf16 v[76:79], v[170:173], v[200:203], v[76:79]
	v_mfma_f32_16x16x32_bf16 v[72:75], v[162:165], v[208:211], v[72:75]
	v_mfma_f32_16x16x32_bf16 v[68:71], v[170:173], v[208:211], v[68:71]
	v_mfma_f32_16x16x32_bf16 v[116:119], v[166:169], v[182:185], v[116:119]
	v_mfma_f32_16x16x32_bf16 v[108:111], v[174:177], v[182:185], v[108:111]
	v_mfma_f32_16x16x32_bf16 v[100:103], v[166:169], v[190:193], v[100:103]
	v_mfma_f32_16x16x32_bf16 v[92:95], v[174:177], v[190:193], v[92:95]
	v_mfma_f32_16x16x32_bf16 v[84:87], v[166:169], v[204:207], v[84:87]
	v_mfma_f32_16x16x32_bf16 v[76:79], v[174:177], v[204:207], v[76:79]
	v_mfma_f32_16x16x32_bf16 v[72:75], v[166:169], v[212:215], v[72:75]
	v_mfma_f32_16x16x32_bf16 v[68:71], v[174:177], v[212:215], v[68:71]
	s_barrier
	s_setprio 0
	s_mov_b32 m0, s0
	v_lshl_add_u64 v[140:141], v[140:141], 0, s[90:91]
	ds_read_b128 v[178:181], v144 offset:49152
	ds_read_b128 v[182:185], v144 offset:50176
	ds_read_b128 v[186:189], v144 offset:51200
	ds_read_b128 v[190:193], v144 offset:52224
	ds_read_b128 v[200:203], v144 offset:53248
	ds_read_b128 v[204:207], v144 offset:54272
	ds_read_b128 v[208:211], v144 offset:55296
	ds_read_b128 v[212:215], v144 offset:56320
	global_load_lds_dwordx4 v[140:141], off
	v_lshl_add_u64 v[140:141], v[194:195], 0, s[90:91]
	s_mov_b32 m0, s80
	s_nop 0
	global_load_lds_dwordx4 v[140:141], off
	v_lshl_add_u64 v[140:141], s[36:37], 0, v[136:137]
	s_mov_b32 m0, s83
	s_nop 0
	global_load_lds_dwordx4 v[140:141], off
	v_lshl_add_u64 v[140:141], s[36:37], 0, v[132:133]
	s_mov_b32 m0, s82
	s_nop 0
	global_load_lds_dwordx4 v[140:141], off
	v_lshl_add_u64 v[140:141], v[198:199], 0, s[90:91]
	s_mov_b32 m0, s61
	s_nop 0
	global_load_lds_dwordx4 v[140:141], off
	v_lshl_add_u64 v[140:141], v[216:217], 0, s[90:91]
	s_mov_b32 m0, s74
	s_nop 0
	global_load_lds_dwordx4 v[140:141], off
	s_waitcnt vmcnt(8)
	s_waitcnt lgkmcnt(0)
	s_setprio 1
	s_barrier
	v_mfma_f32_16x16x32_bf16 v[64:67], v[146:149], v[178:181], v[64:67]
	v_mfma_f32_16x16x32_bf16 v[60:63], v[154:157], v[178:181], v[60:63]
	v_mfma_f32_16x16x32_bf16 v[56:59], v[146:149], v[186:189], v[56:59]
	v_mfma_f32_16x16x32_bf16 v[48:51], v[154:157], v[186:189], v[48:51]
	v_mfma_f32_16x16x32_bf16 v[40:43], v[146:149], v[200:203], v[40:43]
	v_mfma_f32_16x16x32_bf16 v[32:35], v[154:157], v[200:203], v[32:35]
	v_mfma_f32_16x16x32_bf16 v[24:27], v[146:149], v[208:211], v[24:27]
	v_mfma_f32_16x16x32_bf16 v[16:19], v[154:157], v[208:211], v[16:19]
	v_mfma_f32_16x16x32_bf16 v[64:67], v[150:153], v[182:185], v[64:67]
	v_mfma_f32_16x16x32_bf16 v[60:63], v[158:161], v[182:185], v[60:63]
	v_mfma_f32_16x16x32_bf16 v[56:59], v[150:153], v[190:193], v[56:59]
	v_mfma_f32_16x16x32_bf16 v[48:51], v[158:161], v[190:193], v[48:51]
	v_mfma_f32_16x16x32_bf16 v[40:43], v[150:153], v[204:207], v[40:43]
	v_mfma_f32_16x16x32_bf16 v[32:35], v[158:161], v[204:207], v[32:35]
	v_mfma_f32_16x16x32_bf16 v[24:27], v[150:153], v[212:215], v[24:27]
	v_mfma_f32_16x16x32_bf16 v[16:19], v[158:161], v[212:215], v[16:19]
	v_mfma_f32_16x16x32_bf16 v[52:55], v[162:165], v[178:181], v[52:55]
	v_mfma_f32_16x16x32_bf16 v[44:47], v[170:173], v[178:181], v[44:47]
	v_mfma_f32_16x16x32_bf16 v[36:39], v[162:165], v[186:189], v[36:39]
	v_mfma_f32_16x16x32_bf16 v[28:31], v[170:173], v[186:189], v[28:31]
	v_mfma_f32_16x16x32_bf16 v[20:23], v[162:165], v[200:203], v[20:23]
	v_mfma_f32_16x16x32_bf16 v[12:15], v[170:173], v[200:203], v[12:15]
	v_mfma_f32_16x16x32_bf16 v[8:11], v[162:165], v[208:211], v[8:11]
	v_mfma_f32_16x16x32_bf16 v[4:7], v[170:173], v[208:211], v[4:7]
	v_mfma_f32_16x16x32_bf16 v[52:55], v[166:169], v[182:185], v[52:55]
	v_mfma_f32_16x16x32_bf16 v[44:47], v[174:177], v[182:185], v[44:47]
	v_mfma_f32_16x16x32_bf16 v[36:39], v[166:169], v[190:193], v[36:39]
	v_mfma_f32_16x16x32_bf16 v[28:31], v[174:177], v[190:193], v[28:31]
	v_mfma_f32_16x16x32_bf16 v[20:23], v[166:169], v[204:207], v[20:23]
	v_mfma_f32_16x16x32_bf16 v[12:15], v[174:177], v[204:207], v[12:15]
	v_mfma_f32_16x16x32_bf16 v[8:11], v[166:169], v[212:215], v[8:11]
	v_mfma_f32_16x16x32_bf16 v[4:7], v[174:177], v[212:215], v[4:7]
	s_barrier
	s_setprio 0
	s_movk_i32 s30, 0x100
	s_andn2_b64 vcc, exec, s[66:67]
	s_mov_b64 s[36:37], -1
	s_mov_b64 s[66:67], 0
	s_cbranch_vccz .LBB0_1186
	s_and_b64 vcc, exec, s[20:21]
	s_cbranch_vccz .LBB0_1189
	s_barrier

.LBB0_1273:
	s_add_i32 s74, s30, 2
	s_add_u32 s62, s36, 0x100
	s_addc_u32 s63, s37, 0
	s_add_i32 s0, 0, 0x10000
	s_cmp_eq_u32 s29, s30
	s_cselect_b32 s35, s43, s63
	s_cselect_b32 s34, s42, s62
	s_cselect_b32 s31, s45, s72
	s_cselect_b32 s30, s44, s69
	s_add_i32 s6, 0, 0x14000
	v_add_u32_e32 v144, s0, v3
	v_add_u32_e32 v160, s6, v3
	ds_read_b128 v[124:127], v144
	ds_read_b128 v[128:131], v144 offset:1024
	ds_read_b128 v[140:143], v144 offset:2048
	ds_read_b128 v[144:147], v144 offset:3072
	ds_read_b128 v[148:151], v160
	ds_read_b128 v[152:155], v160 offset:1024
	ds_read_b128 v[156:159], v160 offset:2048
	ds_read_b128 v[160:163], v160 offset:3072
	v_lshl_add_u64 v[198:199], s[36:37], 0, v[212:213]
	s_add_i32 m0, s33, 0xc000
	ds_read_b128 v[164:167], v250
	ds_read_b128 v[168:171], v250 offset:1024
	ds_read_b128 v[172:175], v250 offset:2048
	ds_read_b128 v[176:179], v250 offset:3072
	ds_read_b128 v[180:183], v250 offset:4096
	ds_read_b128 v[184:187], v250 offset:5120
	ds_read_b128 v[188:191], v250 offset:6144
	ds_read_b128 v[192:195], v250 offset:7168
	global_load_lds_dwordx4 v[198:199], off
	v_lshl_add_u64 v[198:199], s[36:37], 0, v[214:215]
	s_add_i32 m0, s33, 0xe000
	s_nop 0
	global_load_lds_dwordx4 v[198:199], off
	s_waitcnt vmcnt(8)
	s_waitcnt lgkmcnt(0)
	s_setprio 1
	s_barrier
	v_mfma_f32_16x16x32_bf16 v[136:139], v[124:127], v[164:167], v[136:139]
	v_mfma_f32_16x16x32_bf16 v[132:135], v[140:143], v[164:167], v[132:135]
	v_mfma_f32_16x16x32_bf16 v[112:115], v[124:127], v[172:175], v[112:115]
	v_mfma_f32_16x16x32_bf16 v[108:111], v[140:143], v[172:175], v[108:111]
	v_mfma_f32_16x16x32_bf16 v[96:99], v[124:127], v[180:183], v[96:99]
	v_mfma_f32_16x16x32_bf16 v[92:95], v[140:143], v[180:183], v[92:95]
	v_mfma_f32_16x16x32_bf16 v[80:83], v[124:127], v[188:191], v[80:83]
	v_mfma_f32_16x16x32_bf16 v[76:79], v[140:143], v[188:191], v[76:79]
	v_mfma_f32_16x16x32_bf16 v[136:139], v[128:131], v[168:171], v[136:139]
	v_mfma_f32_16x16x32_bf16 v[132:135], v[144:147], v[168:171], v[132:135]
	v_mfma_f32_16x16x32_bf16 v[112:115], v[128:131], v[176:179], v[112:115]
	v_mfma_f32_16x16x32_bf16 v[108:111], v[144:147], v[176:179], v[108:111]
	v_mfma_f32_16x16x32_bf16 v[96:99], v[128:131], v[184:187], v[96:99]
	v_mfma_f32_16x16x32_bf16 v[92:95], v[144:147], v[184:187], v[92:95]
	v_mfma_f32_16x16x32_bf16 v[80:83], v[128:131], v[192:195], v[80:83]
	v_mfma_f32_16x16x32_bf16 v[76:79], v[144:147], v[192:195], v[76:79]
	v_mfma_f32_16x16x32_bf16 v[120:123], v[148:151], v[164:167], v[120:123]
	v_mfma_f32_16x16x32_bf16 v[116:119], v[156:159], v[164:167], v[116:119]
	v_mfma_f32_16x16x32_bf16 v[104:107], v[148:151], v[172:175], v[104:107]
	v_mfma_f32_16x16x32_bf16 v[100:103], v[156:159], v[172:175], v[100:103]
	v_mfma_f32_16x16x32_bf16 v[88:91], v[148:151], v[180:183], v[88:91]
	v_mfma_f32_16x16x32_bf16 v[84:87], v[156:159], v[180:183], v[84:87]
	v_mfma_f32_16x16x32_bf16 v[72:75], v[148:151], v[188:191], v[72:75]
	v_mfma_f32_16x16x32_bf16 v[68:71], v[156:159], v[188:191], v[68:71]
	v_mfma_f32_16x16x32_bf16 v[120:123], v[152:155], v[168:171], v[120:123]
	v_mfma_f32_16x16x32_bf16 v[116:119], v[160:163], v[168:171], v[116:119]
	v_mfma_f32_16x16x32_bf16 v[104:107], v[152:155], v[176:179], v[104:107]
	v_mfma_f32_16x16x32_bf16 v[100:103], v[160:163], v[176:179], v[100:103]
	v_mfma_f32_16x16x32_bf16 v[88:91], v[152:155], v[184:187], v[88:91]
	v_mfma_f32_16x16x32_bf16 v[84:87], v[160:163], v[184:187], v[84:87]
	v_mfma_f32_16x16x32_bf16 v[72:75], v[152:155], v[192:195], v[72:75]
	v_mfma_f32_16x16x32_bf16 v[68:71], v[160:163], v[192:195], v[68:71]
	s_barrier
	s_setprio 0
	s_add_i32 s0, s0, s27
	v_lshl_add_u64 v[198:199], s[30:31], 0, v[202:203]
	s_mov_b32 m0, s0
	ds_read_b128 v[164:167], v250 offset:16384
	ds_read_b128 v[168:171], v250 offset:17408
	ds_read_b128 v[172:175], v250 offset:18432
	ds_read_b128 v[176:179], v250 offset:19456
	ds_read_b128 v[180:183], v250 offset:20480
	ds_read_b128 v[184:187], v250 offset:21504
	ds_read_b128 v[188:191], v250 offset:22528
	ds_read_b128 v[192:195], v250 offset:23552
	global_load_lds_dwordx4 v[198:199], off
	s_add_i32 m0, s0, 0x2000
	s_add_u32 s36, s30, 0x204000
	v_lshl_add_u64 v[216:217], s[30:31], 0, v[206:207]
	s_addc_u32 s37, s31, 0
	s_add_i32 s0, s6, s27
	global_load_lds_dwordx4 v[216:217], off
	v_lshl_add_u64 v[218:219], s[36:37], 0, v[202:203]
	s_mov_b32 m0, s0
	v_lshl_add_u64 v[220:221], s[34:35], 0, v[204:205]
	global_load_lds_dwordx4 v[218:219], off
	v_lshl_add_u64 v[218:219], s[36:37], 0, v[206:207]
	s_add_i32 m0, s0, 0x2000
	s_nop 0
	global_load_lds_dwordx4 v[218:219], off
	v_lshl_add_u64 v[218:219], s[34:35], 0, v[200:201]
	s_mov_b32 m0, s33
	s_nop 0
	global_load_lds_dwordx4 v[218:219], off
	s_mov_b32 m0, s38
	s_nop 0
	global_load_lds_dwordx4 v[220:221], off
	s_waitcnt vmcnt(8)
	s_waitcnt lgkmcnt(0)
	s_setprio 1
	s_barrier
	v_mfma_f32_16x16x32_bf16 v[64:67], v[124:127], v[164:167], v[64:67]
	v_mfma_f32_16x16x32_bf16 v[60:63], v[140:143], v[164:167], v[60:63]
	v_mfma_f32_16x16x32_bf16 v[48:51], v[124:127], v[172:175], v[48:51]
	v_mfma_f32_16x16x32_bf16 v[44:47], v[140:143], v[172:175], v[44:47]
	v_mfma_f32_16x16x32_bf16 v[32:35], v[124:127], v[180:183], v[32:35]
	v_mfma_f32_16x16x32_bf16 v[28:31], v[140:143], v[180:183], v[28:31]
	v_mfma_f32_16x16x32_bf16 v[16:19], v[124:127], v[188:191], v[16:19]
	v_mfma_f32_16x16x32_bf16 v[12:15], v[140:143], v[188:191], v[12:15]
	v_mfma_f32_16x16x32_bf16 v[64:67], v[128:131], v[168:171], v[64:67]
	v_mfma_f32_16x16x32_bf16 v[60:63], v[144:147], v[168:171], v[60:63]
	v_mfma_f32_16x16x32_bf16 v[48:51], v[128:131], v[176:179], v[48:51]
	v_mfma_f32_16x16x32_bf16 v[44:47], v[144:147], v[176:179], v[44:47]
	v_mfma_f32_16x16x32_bf16 v[32:35], v[128:131], v[184:187], v[32:35]
	v_mfma_f32_16x16x32_bf16 v[28:31], v[144:147], v[184:187], v[28:31]
	v_mfma_f32_16x16x32_bf16 v[16:19], v[128:131], v[192:195], v[16:19]
	v_mfma_f32_16x16x32_bf16 v[12:15], v[144:147], v[192:195], v[12:15]
	v_mfma_f32_16x16x32_bf16 v[56:59], v[148:151], v[164:167], v[56:59]
	v_mfma_f32_16x16x32_bf16 v[52:55], v[156:159], v[164:167], v[52:55]
	v_mfma_f32_16x16x32_bf16 v[40:43], v[148:151], v[172:175], v[40:43]
	v_mfma_f32_16x16x32_bf16 v[36:39], v[156:159], v[172:175], v[36:39]
	v_mfma_f32_16x16x32_bf16 v[24:27], v[148:151], v[180:183], v[24:27]
	v_mfma_f32_16x16x32_bf16 v[20:23], v[156:159], v[180:183], v[20:23]
	v_mfma_f32_16x16x32_bf16 v[8:11], v[148:151], v[188:191], v[8:11]
	v_mfma_f32_16x16x32_bf16 v[4:7], v[156:159], v[188:191], v[4:7]
	v_mfma_f32_16x16x32_bf16 v[56:59], v[152:155], v[168:171], v[56:59]
	v_mfma_f32_16x16x32_bf16 v[52:55], v[160:163], v[168:171], v[52:55]
	v_mfma_f32_16x16x32_bf16 v[40:43], v[152:155], v[176:179], v[40:43]
	v_mfma_f32_16x16x32_bf16 v[36:39], v[160:163], v[176:179], v[36:39]
	v_mfma_f32_16x16x32_bf16 v[24:27], v[152:155], v[184:187], v[24:27]
	v_mfma_f32_16x16x32_bf16 v[20:23], v[160:163], v[184:187], v[20:23]
	v_mfma_f32_16x16x32_bf16 v[8:11], v[152:155], v[192:195], v[8:11]
	v_mfma_f32_16x16x32_bf16 v[4:7], v[160:163], v[192:195], v[4:7]
	s_barrier
	s_setprio 0
	s_add_i32 s0, 0, 0x18000
	s_add_i32 s6, 0, 0x1c000
	v_add_u32_e32 v144, s0, v3
	v_add_u32_e32 v160, s6, v3
	ds_read_b128 v[124:127], v144
	ds_read_b128 v[128:131], v144 offset:1024
	ds_read_b128 v[140:143], v144 offset:2048
	ds_read_b128 v[144:147], v144 offset:3072
	ds_read_b128 v[148:151], v160
	ds_read_b128 v[152:155], v160 offset:1024
	ds_read_b128 v[156:159], v160 offset:2048
	ds_read_b128 v[160:163], v160 offset:3072
	s_add_u32 s34, s34, 0x204000
	s_addc_u32 s35, s35, 0
	s_mov_b32 m0, s39
	v_lshl_add_u64 v[222:223], s[34:35], 0, v[200:201]
	ds_read_b128 v[164:167], v250 offset:32768
	ds_read_b128 v[168:171], v250 offset:33792
	ds_read_b128 v[172:175], v250 offset:34816
	ds_read_b128 v[176:179], v250 offset:35840
	ds_read_b128 v[180:183], v250 offset:36864
	ds_read_b128 v[184:187], v250 offset:37888
	ds_read_b128 v[188:191], v250 offset:38912
	ds_read_b128 v[192:195], v250 offset:39936
	global_load_lds_dwordx4 v[222:223], off
	v_lshl_add_u64 v[222:223], s[34:35], 0, v[204:205]
	s_mov_b32 m0, s40
	s_nop 0
	global_load_lds_dwordx4 v[222:223], off
	s_waitcnt vmcnt(8)
	s_waitcnt lgkmcnt(0)
	s_setprio 1
	s_barrier
	v_mfma_f32_16x16x32_bf16 v[136:139], v[124:127], v[164:167], v[136:139]
	v_mfma_f32_16x16x32_bf16 v[132:135], v[140:143], v[164:167], v[132:135]
	v_mfma_f32_16x16x32_bf16 v[112:115], v[124:127], v[172:175], v[112:115]
	v_mfma_f32_16x16x32_bf16 v[108:111], v[140:143], v[172:175], v[108:111]
	v_mfma_f32_16x16x32_bf16 v[96:99], v[124:127], v[180:183], v[96:99]
	v_mfma_f32_16x16x32_bf16 v[92:95], v[140:143], v[180:183], v[92:95]
	v_mfma_f32_16x16x32_bf16 v[80:83], v[124:127], v[188:191], v[80:83]
	v_mfma_f32_16x16x32_bf16 v[76:79], v[140:143], v[188:191], v[76:79]
	v_mfma_f32_16x16x32_bf16 v[136:139], v[128:131], v[168:171], v[136:139]
	v_mfma_f32_16x16x32_bf16 v[132:135], v[144:147], v[168:171], v[132:135]
	v_mfma_f32_16x16x32_bf16 v[112:115], v[128:131], v[176:179], v[112:115]
	v_mfma_f32_16x16x32_bf16 v[108:111], v[144:147], v[176:179], v[108:111]
	v_mfma_f32_16x16x32_bf16 v[96:99], v[128:131], v[184:187], v[96:99]
	v_mfma_f32_16x16x32_bf16 v[92:95], v[144:147], v[184:187], v[92:95]
	v_mfma_f32_16x16x32_bf16 v[80:83], v[128:131], v[192:195], v[80:83]
	v_mfma_f32_16x16x32_bf16 v[76:79], v[144:147], v[192:195], v[76:79]
	v_mfma_f32_16x16x32_bf16 v[120:123], v[148:151], v[164:167], v[120:123]
	v_mfma_f32_16x16x32_bf16 v[116:119], v[156:159], v[164:167], v[116:119]
	v_mfma_f32_16x16x32_bf16 v[104:107], v[148:151], v[172:175], v[104:107]
	v_mfma_f32_16x16x32_bf16 v[100:103], v[156:159], v[172:175], v[100:103]
	v_mfma_f32_16x16x32_bf16 v[88:91], v[148:151], v[180:183], v[88:91]
	v_mfma_f32_16x16x32_bf16 v[84:87], v[156:159], v[180:183], v[84:87]
	v_mfma_f32_16x16x32_bf16 v[72:75], v[148:151], v[188:191], v[72:75]
	v_mfma_f32_16x16x32_bf16 v[68:71], v[156:159], v[188:191], v[68:71]
	v_mfma_f32_16x16x32_bf16 v[120:123], v[152:155], v[168:171], v[120:123]
	v_mfma_f32_16x16x32_bf16 v[116:119], v[160:163], v[168:171], v[116:119]
	v_mfma_f32_16x16x32_bf16 v[104:107], v[152:155], v[176:179], v[104:107]
	v_mfma_f32_16x16x32_bf16 v[100:103], v[160:163], v[176:179], v[100:103]
	v_mfma_f32_16x16x32_bf16 v[88:91], v[152:155], v[184:187], v[88:91]
	v_mfma_f32_16x16x32_bf16 v[84:87], v[160:163], v[184:187], v[84:87]
	v_mfma_f32_16x16x32_bf16 v[72:75], v[152:155], v[192:195], v[72:75]
	v_mfma_f32_16x16x32_bf16 v[68:71], v[160:163], v[192:195], v[68:71]
	s_barrier
	s_setprio 0
	s_add_i32 s0, s0, s27
	v_lshl_add_u64 v[198:199], v[198:199], 0, s[90:91]
	s_mov_b32 m0, s0
	ds_read_b128 v[164:167], v250 offset:49152
	ds_read_b128 v[168:171], v250 offset:50176
	ds_read_b128 v[172:175], v250 offset:51200
	ds_read_b128 v[176:179], v250 offset:52224
	ds_read_b128 v[180:183], v250 offset:53248
	ds_read_b128 v[184:187], v250 offset:54272
	ds_read_b128 v[188:191], v250 offset:55296
	ds_read_b128 v[192:195], v250 offset:56320
	global_load_lds_dwordx4 v[198:199], off
	s_add_i32 m0, s0, 0x2000
	s_add_u32 s30, s30, 0x204080
	v_lshl_add_u64 v[198:199], v[216:217], 0, s[90:91]
	s_addc_u32 s31, s31, 0
	s_add_i32 s0, s6, s27
	global_load_lds_dwordx4 v[198:199], off
	v_lshl_add_u64 v[198:199], s[30:31], 0, v[202:203]
	s_mov_b32 m0, s0
	s_nop 0
	global_load_lds_dwordx4 v[198:199], off
	v_lshl_add_u64 v[198:199], s[30:31], 0, v[206:207]
	s_add_i32 m0, s0, 0x2000
	s_nop 0
	global_load_lds_dwordx4 v[198:199], off
	v_lshl_add_u64 v[198:199], v[218:219], 0, s[90:91]
	s_mov_b32 m0, s50
	s_nop 0
	global_load_lds_dwordx4 v[198:199], off
	v_lshl_add_u64 v[198:199], v[220:221], 0, s[90:91]
	s_mov_b32 m0, s51
	s_nop 0
	global_load_lds_dwordx4 v[198:199], off
	s_waitcnt vmcnt(8)
	s_waitcnt lgkmcnt(0)
	s_setprio 1
	s_barrier
	v_mfma_f32_16x16x32_bf16 v[64:67], v[124:127], v[164:167], v[64:67]
	v_mfma_f32_16x16x32_bf16 v[60:63], v[140:143], v[164:167], v[60:63]
	v_mfma_f32_16x16x32_bf16 v[48:51], v[124:127], v[172:175], v[48:51]
	v_mfma_f32_16x16x32_bf16 v[44:47], v[140:143], v[172:175], v[44:47]
	v_mfma_f32_16x16x32_bf16 v[32:35], v[124:127], v[180:183], v[32:35]
	v_mfma_f32_16x16x32_bf16 v[28:31], v[140:143], v[180:183], v[28:31]
	v_mfma_f32_16x16x32_bf16 v[16:19], v[124:127], v[188:191], v[16:19]
	v_mfma_f32_16x16x32_bf16 v[12:15], v[140:143], v[188:191], v[12:15]
	v_mfma_f32_16x16x32_bf16 v[64:67], v[128:131], v[168:171], v[64:67]
	v_mfma_f32_16x16x32_bf16 v[60:63], v[144:147], v[168:171], v[60:63]
	v_mfma_f32_16x16x32_bf16 v[48:51], v[128:131], v[176:179], v[48:51]
	v_mfma_f32_16x16x32_bf16 v[44:47], v[144:147], v[176:179], v[44:47]
	v_mfma_f32_16x16x32_bf16 v[32:35], v[128:131], v[184:187], v[32:35]
	v_mfma_f32_16x16x32_bf16 v[28:31], v[144:147], v[184:187], v[28:31]
	v_mfma_f32_16x16x32_bf16 v[16:19], v[128:131], v[192:195], v[16:19]
	v_mfma_f32_16x16x32_bf16 v[12:15], v[144:147], v[192:195], v[12:15]
	v_mfma_f32_16x16x32_bf16 v[56:59], v[148:151], v[164:167], v[56:59]
	v_mfma_f32_16x16x32_bf16 v[52:55], v[156:159], v[164:167], v[52:55]
	v_mfma_f32_16x16x32_bf16 v[40:43], v[148:151], v[172:175], v[40:43]
	v_mfma_f32_16x16x32_bf16 v[36:39], v[156:159], v[172:175], v[36:39]
	v_mfma_f32_16x16x32_bf16 v[24:27], v[148:151], v[180:183], v[24:27]
	v_mfma_f32_16x16x32_bf16 v[20:23], v[156:159], v[180:183], v[20:23]
	v_mfma_f32_16x16x32_bf16 v[8:11], v[148:151], v[188:191], v[8:11]
	v_mfma_f32_16x16x32_bf16 v[4:7], v[156:159], v[188:191], v[4:7]
	v_mfma_f32_16x16x32_bf16 v[56:59], v[152:155], v[168:171], v[56:59]
	v_mfma_f32_16x16x32_bf16 v[52:55], v[160:163], v[168:171], v[52:55]
	v_mfma_f32_16x16x32_bf16 v[40:43], v[152:155], v[176:179], v[40:43]
	v_mfma_f32_16x16x32_bf16 v[36:39], v[160:163], v[176:179], v[36:39]
	v_mfma_f32_16x16x32_bf16 v[24:27], v[152:155], v[184:187], v[24:27]
	v_mfma_f32_16x16x32_bf16 v[20:23], v[160:163], v[184:187], v[20:23]
	v_mfma_f32_16x16x32_bf16 v[8:11], v[152:155], v[192:195], v[8:11]
	v_mfma_f32_16x16x32_bf16 v[4:7], v[160:163], v[192:195], v[4:7]
	s_barrier
	s_setprio 0
	s_add_u32 s69, s69, 0x100
	s_addc_u32 s72, s72, 0
	s_cmp_ge_i32 s74, s61
	s_mov_b64 s[36:37], s[62:63]
	s_mov_b32 s30, s74
	s_cbranch_scc0 .LBB0_1273
	s_and_b64 vcc, exec, s[22:23]
	s_cbranch_vccz .LBB0_1276
	s_barrier

.LBB0_1395:
	s_add_u32 s0, s36, 0xfff80080
	s_addc_u32 s6, s37, -1
	s_add_i32 s49, 0, 0x10000
	s_cmp_eq_u32 s67, 28
	s_cselect_b32 s35, s25, s6
	s_cselect_b32 s34, s33, s0
	s_cselect_b32 s31, s43, s39
	s_cselect_b32 s30, s45, s38
	s_add_i32 s0, 0, 0x14000
	v_add_u32_e32 v144, s49, v3
	v_add_u32_e32 v176, s0, v3
	ds_read_b128 v[132:135], v144
	ds_read_b128 v[136:139], v144 offset:1024
	ds_read_b128 v[140:143], v144 offset:2048
	ds_read_b128 v[144:147], v144 offset:3072
	ds_read_b128 v[164:167], v176
	ds_read_b128 v[168:171], v176 offset:1024
	ds_read_b128 v[172:175], v176 offset:2048
	ds_read_b128 v[176:179], v176 offset:3072
	v_lshl_add_u64 v[198:199], s[36:37], 0, v[160:161]
	s_add_i32 m0, s47, 0xc000
	ds_read_b128 v[180:183], v190
	ds_read_b128 v[184:187], v190 offset:1024
	ds_read_b128 v[192:195], v190 offset:2048
	ds_read_b128 v[200:203], v190 offset:3072
	ds_read_b128 v[204:207], v190 offset:4096
	ds_read_b128 v[208:211], v190 offset:5120
	ds_read_b128 v[212:215], v190 offset:6144
	ds_read_b128 v[216:219], v190 offset:7168
	global_load_lds_dwordx4 v[198:199], off
	v_lshl_add_u64 v[198:199], s[36:37], 0, v[162:163]
	s_add_i32 m0, s47, 0xe000
	s_nop 0
	global_load_lds_dwordx4 v[198:199], off
	s_waitcnt vmcnt(8)
	s_waitcnt lgkmcnt(0)
	s_setprio 1
	s_barrier
	v_mfma_f32_16x16x32_bf16 v[128:131], v[132:135], v[180:183], v[128:131]
	v_mfma_f32_16x16x32_bf16 v[124:127], v[140:143], v[180:183], v[124:127]
	v_mfma_f32_16x16x32_bf16 v[112:115], v[132:135], v[192:195], v[112:115]
	v_mfma_f32_16x16x32_bf16 v[108:111], v[140:143], v[192:195], v[108:111]
	v_mfma_f32_16x16x32_bf16 v[96:99], v[132:135], v[204:207], v[96:99]
	v_mfma_f32_16x16x32_bf16 v[92:95], v[140:143], v[204:207], v[92:95]
	v_mfma_f32_16x16x32_bf16 v[80:83], v[132:135], v[212:215], v[80:83]
	v_mfma_f32_16x16x32_bf16 v[76:79], v[140:143], v[212:215], v[76:79]
	v_mfma_f32_16x16x32_bf16 v[128:131], v[136:139], v[184:187], v[128:131]
	v_mfma_f32_16x16x32_bf16 v[124:127], v[144:147], v[184:187], v[124:127]
	v_mfma_f32_16x16x32_bf16 v[112:115], v[136:139], v[200:203], v[112:115]
	v_mfma_f32_16x16x32_bf16 v[108:111], v[144:147], v[200:203], v[108:111]
	v_mfma_f32_16x16x32_bf16 v[96:99], v[136:139], v[208:211], v[96:99]
	v_mfma_f32_16x16x32_bf16 v[92:95], v[144:147], v[208:211], v[92:95]
	v_mfma_f32_16x16x32_bf16 v[80:83], v[136:139], v[216:219], v[80:83]
	v_mfma_f32_16x16x32_bf16 v[76:79], v[144:147], v[216:219], v[76:79]
	v_mfma_f32_16x16x32_bf16 v[120:123], v[164:167], v[180:183], v[120:123]
	v_mfma_f32_16x16x32_bf16 v[116:119], v[172:175], v[180:183], v[116:119]
	v_mfma_f32_16x16x32_bf16 v[104:107], v[164:167], v[192:195], v[104:107]
	v_mfma_f32_16x16x32_bf16 v[100:103], v[172:175], v[192:195], v[100:103]
	v_mfma_f32_16x16x32_bf16 v[88:91], v[164:167], v[204:207], v[88:91]
	v_mfma_f32_16x16x32_bf16 v[84:87], v[172:175], v[204:207], v[84:87]
	v_mfma_f32_16x16x32_bf16 v[72:75], v[164:167], v[212:215], v[72:75]
	v_mfma_f32_16x16x32_bf16 v[68:71], v[172:175], v[212:215], v[68:71]
	v_mfma_f32_16x16x32_bf16 v[120:123], v[168:171], v[184:187], v[120:123]
	v_mfma_f32_16x16x32_bf16 v[116:119], v[176:179], v[184:187], v[116:119]
	v_mfma_f32_16x16x32_bf16 v[104:107], v[168:171], v[200:203], v[104:107]
	v_mfma_f32_16x16x32_bf16 v[100:103], v[176:179], v[200:203], v[100:103]
	v_mfma_f32_16x16x32_bf16 v[88:91], v[168:171], v[208:211], v[88:91]
	v_mfma_f32_16x16x32_bf16 v[84:87], v[176:179], v[208:211], v[84:87]
	v_mfma_f32_16x16x32_bf16 v[72:75], v[168:171], v[216:219], v[72:75]
	v_mfma_f32_16x16x32_bf16 v[68:71], v[176:179], v[216:219], v[68:71]
	s_barrier
	s_setprio 0
	s_add_i32 s6, s49, s4
	v_lshl_add_u64 v[198:199], s[30:31], 0, v[152:153]
	s_mov_b32 m0, s6
	ds_read_b128 v[180:183], v190 offset:16384
	ds_read_b128 v[184:187], v190 offset:17408
	ds_read_b128 v[192:195], v190 offset:18432
	ds_read_b128 v[200:203], v190 offset:19456
	ds_read_b128 v[204:207], v190 offset:20480
	ds_read_b128 v[208:211], v190 offset:21504
	ds_read_b128 v[212:215], v190 offset:22528
	ds_read_b128 v[216:219], v190 offset:23552
	global_load_lds_dwordx4 v[198:199], off
	s_add_i32 m0, s6, 0x2000
	s_add_u32 s68, s30, 0x80000
	v_lshl_add_u64 v[220:221], s[30:31], 0, v[148:149]
	s_addc_u32 s69, s31, 0
	s_add_i32 s0, s0, s4
	global_load_lds_dwordx4 v[220:221], off
	v_lshl_add_u64 v[222:223], s[68:69], 0, v[152:153]
	s_mov_b32 m0, s0
	v_lshl_add_u64 v[224:225], s[34:35], 0, v[150:151]
	global_load_lds_dwordx4 v[222:223], off
	v_lshl_add_u64 v[222:223], s[68:69], 0, v[148:149]
	s_add_i32 m0, s0, 0x2000
	s_nop 0
	global_load_lds_dwordx4 v[222:223], off
	v_lshl_add_u64 v[222:223], s[34:35], 0, v[154:155]
	s_mov_b32 m0, s47
	s_nop 0
	global_load_lds_dwordx4 v[222:223], off
	s_mov_b32 m0, s52
	s_nop 0
	global_load_lds_dwordx4 v[224:225], off
	s_waitcnt vmcnt(8)
	s_waitcnt lgkmcnt(0)
	s_setprio 1
	s_barrier
	v_mfma_f32_16x16x32_bf16 v[64:67], v[132:135], v[180:183], v[64:67]
	v_mfma_f32_16x16x32_bf16 v[60:63], v[140:143], v[180:183], v[60:63]
	v_mfma_f32_16x16x32_bf16 v[48:51], v[132:135], v[192:195], v[48:51]
	v_mfma_f32_16x16x32_bf16 v[44:47], v[140:143], v[192:195], v[44:47]
	v_mfma_f32_16x16x32_bf16 v[32:35], v[132:135], v[204:207], v[32:35]
	v_mfma_f32_16x16x32_bf16 v[28:31], v[140:143], v[204:207], v[28:31]
	v_mfma_f32_16x16x32_bf16 v[16:19], v[132:135], v[212:215], v[16:19]
	v_mfma_f32_16x16x32_bf16 v[12:15], v[140:143], v[212:215], v[12:15]
	v_mfma_f32_16x16x32_bf16 v[64:67], v[136:139], v[184:187], v[64:67]
	v_mfma_f32_16x16x32_bf16 v[60:63], v[144:147], v[184:187], v[60:63]
	v_mfma_f32_16x16x32_bf16 v[48:51], v[136:139], v[200:203], v[48:51]
	v_mfma_f32_16x16x32_bf16 v[44:47], v[144:147], v[200:203], v[44:47]
	v_mfma_f32_16x16x32_bf16 v[32:35], v[136:139], v[208:211], v[32:35]
	v_mfma_f32_16x16x32_bf16 v[28:31], v[144:147], v[208:211], v[28:31]
	v_mfma_f32_16x16x32_bf16 v[16:19], v[136:139], v[216:219], v[16:19]
	v_mfma_f32_16x16x32_bf16 v[12:15], v[144:147], v[216:219], v[12:15]
	v_mfma_f32_16x16x32_bf16 v[56:59], v[164:167], v[180:183], v[56:59]
	v_mfma_f32_16x16x32_bf16 v[52:55], v[172:175], v[180:183], v[52:55]
	v_mfma_f32_16x16x32_bf16 v[40:43], v[164:167], v[192:195], v[40:43]
	v_mfma_f32_16x16x32_bf16 v[36:39], v[172:175], v[192:195], v[36:39]
	v_mfma_f32_16x16x32_bf16 v[24:27], v[164:167], v[204:207], v[24:27]
	v_mfma_f32_16x16x32_bf16 v[20:23], v[172:175], v[204:207], v[20:23]
	v_mfma_f32_16x16x32_bf16 v[8:11], v[164:167], v[212:215], v[8:11]
	v_mfma_f32_16x16x32_bf16 v[4:7], v[172:175], v[212:215], v[4:7]
	v_mfma_f32_16x16x32_bf16 v[56:59], v[168:171], v[184:187], v[56:59]
	v_mfma_f32_16x16x32_bf16 v[52:55], v[176:179], v[184:187], v[52:55]
	v_mfma_f32_16x16x32_bf16 v[40:43], v[168:171], v[200:203], v[40:43]
	v_mfma_f32_16x16x32_bf16 v[36:39], v[176:179], v[200:203], v[36:39]
	v_mfma_f32_16x16x32_bf16 v[24:27], v[168:171], v[208:211], v[24:27]
	v_mfma_f32_16x16x32_bf16 v[20:23], v[176:179], v[208:211], v[20:23]
	v_mfma_f32_16x16x32_bf16 v[8:11], v[168:171], v[216:219], v[8:11]
	v_mfma_f32_16x16x32_bf16 v[4:7], v[176:179], v[216:219], v[4:7]
	s_barrier
	s_setprio 0
	s_add_i32 s0, 0, 0x18000
	s_add_i32 s6, 0, 0x1c000
	v_add_u32_e32 v144, s0, v3
	v_add_u32_e32 v176, s6, v3
	ds_read_b128 v[132:135], v144
	ds_read_b128 v[136:139], v144 offset:1024
	ds_read_b128 v[140:143], v144 offset:2048
	ds_read_b128 v[144:147], v144 offset:3072
	ds_read_b128 v[164:167], v176
	ds_read_b128 v[168:171], v176 offset:1024
	ds_read_b128 v[172:175], v176 offset:2048
	ds_read_b128 v[176:179], v176 offset:3072
	s_add_u32 s34, s34, 0x80000
	s_addc_u32 s35, s35, 0
	s_mov_b32 m0, s53
	v_lshl_add_u64 v[226:227], s[34:35], 0, v[154:155]
	ds_read_b128 v[180:183], v190 offset:32768
	ds_read_b128 v[184:187], v190 offset:33792
	ds_read_b128 v[192:195], v190 offset:34816
	ds_read_b128 v[200:203], v190 offset:35840
	ds_read_b128 v[204:207], v190 offset:36864
	ds_read_b128 v[208:211], v190 offset:37888
	ds_read_b128 v[212:215], v190 offset:38912
	ds_read_b128 v[216:219], v190 offset:39936
	global_load_lds_dwordx4 v[226:227], off
	v_lshl_add_u64 v[226:227], s[34:35], 0, v[150:151]
	s_mov_b32 m0, s59
	s_nop 0
	global_load_lds_dwordx4 v[226:227], off
	s_waitcnt vmcnt(8)
	s_waitcnt lgkmcnt(0)
	s_setprio 1
	s_barrier
	v_mfma_f32_16x16x32_bf16 v[128:131], v[132:135], v[180:183], v[128:131]
	v_mfma_f32_16x16x32_bf16 v[124:127], v[140:143], v[180:183], v[124:127]
	v_mfma_f32_16x16x32_bf16 v[112:115], v[132:135], v[192:195], v[112:115]
	v_mfma_f32_16x16x32_bf16 v[108:111], v[140:143], v[192:195], v[108:111]
	v_mfma_f32_16x16x32_bf16 v[96:99], v[132:135], v[204:207], v[96:99]
	v_mfma_f32_16x16x32_bf16 v[92:95], v[140:143], v[204:207], v[92:95]
	v_mfma_f32_16x16x32_bf16 v[80:83], v[132:135], v[212:215], v[80:83]
	v_mfma_f32_16x16x32_bf16 v[76:79], v[140:143], v[212:215], v[76:79]
	v_mfma_f32_16x16x32_bf16 v[128:131], v[136:139], v[184:187], v[128:131]
	v_mfma_f32_16x16x32_bf16 v[124:127], v[144:147], v[184:187], v[124:127]
	v_mfma_f32_16x16x32_bf16 v[112:115], v[136:139], v[200:203], v[112:115]
	v_mfma_f32_16x16x32_bf16 v[108:111], v[144:147], v[200:203], v[108:111]
	v_mfma_f32_16x16x32_bf16 v[96:99], v[136:139], v[208:211], v[96:99]
	v_mfma_f32_16x16x32_bf16 v[92:95], v[144:147], v[208:211], v[92:95]
	v_mfma_f32_16x16x32_bf16 v[80:83], v[136:139], v[216:219], v[80:83]
	v_mfma_f32_16x16x32_bf16 v[76:79], v[144:147], v[216:219], v[76:79]
	v_mfma_f32_16x16x32_bf16 v[120:123], v[164:167], v[180:183], v[120:123]
	v_mfma_f32_16x16x32_bf16 v[116:119], v[172:175], v[180:183], v[116:119]
	v_mfma_f32_16x16x32_bf16 v[104:107], v[164:167], v[192:195], v[104:107]
	v_mfma_f32_16x16x32_bf16 v[100:103], v[172:175], v[192:195], v[100:103]
	v_mfma_f32_16x16x32_bf16 v[88:91], v[164:167], v[204:207], v[88:91]
	v_mfma_f32_16x16x32_bf16 v[84:87], v[172:175], v[204:207], v[84:87]
	v_mfma_f32_16x16x32_bf16 v[72:75], v[164:167], v[212:215], v[72:75]
	v_mfma_f32_16x16x32_bf16 v[68:71], v[172:175], v[212:215], v[68:71]
	v_mfma_f32_16x16x32_bf16 v[120:123], v[168:171], v[184:187], v[120:123]
	v_mfma_f32_16x16x32_bf16 v[116:119], v[176:179], v[184:187], v[116:119]
	v_mfma_f32_16x16x32_bf16 v[104:107], v[168:171], v[200:203], v[104:107]
	v_mfma_f32_16x16x32_bf16 v[100:103], v[176:179], v[200:203], v[100:103]
	v_mfma_f32_16x16x32_bf16 v[88:91], v[168:171], v[208:211], v[88:91]
	v_mfma_f32_16x16x32_bf16 v[84:87], v[176:179], v[208:211], v[84:87]
	v_mfma_f32_16x16x32_bf16 v[72:75], v[168:171], v[216:219], v[72:75]
	v_mfma_f32_16x16x32_bf16 v[68:71], v[176:179], v[216:219], v[68:71]
	s_barrier
	s_setprio 0
	s_add_i32 s0, s0, s4
	v_lshl_add_u64 v[198:199], v[198:199], 0, s[90:91]
	s_mov_b32 m0, s0
	ds_read_b128 v[180:183], v190 offset:49152
	ds_read_b128 v[184:187], v190 offset:50176
	ds_read_b128 v[192:195], v190 offset:51200
	ds_read_b128 v[200:203], v190 offset:52224
	ds_read_b128 v[204:207], v190 offset:53248
	ds_read_b128 v[208:211], v190 offset:54272
	ds_read_b128 v[212:215], v190 offset:55296
	ds_read_b128 v[216:219], v190 offset:56320
	global_load_lds_dwordx4 v[198:199], off
	s_add_i32 m0, s0, 0x2000
	s_add_u32 s30, s30, 0x80080
	v_lshl_add_u64 v[198:199], v[220:221], 0, s[90:91]
	s_addc_u32 s31, s31, 0
	s_add_i32 s0, s6, s4
	global_load_lds_dwordx4 v[198:199], off
	v_lshl_add_u64 v[198:199], s[30:31], 0, v[152:153]
	s_mov_b32 m0, s0
	s_nop 0
	global_load_lds_dwordx4 v[198:199], off
	v_lshl_add_u64 v[198:199], s[30:31], 0, v[148:149]
	s_add_i32 m0, s0, 0x2000
	s_nop 0
	global_load_lds_dwordx4 v[198:199], off
	v_lshl_add_u64 v[198:199], v[222:223], 0, s[90:91]
	s_mov_b32 m0, s40
	s_nop 0
	global_load_lds_dwordx4 v[198:199], off
	v_lshl_add_u64 v[198:199], v[224:225], 0, s[90:91]
	s_mov_b32 m0, s66
	s_nop 0
	global_load_lds_dwordx4 v[198:199], off
	s_waitcnt vmcnt(8)
	s_waitcnt lgkmcnt(0)
	s_setprio 1
	s_barrier
	v_mfma_f32_16x16x32_bf16 v[64:67], v[132:135], v[180:183], v[64:67]
	v_mfma_f32_16x16x32_bf16 v[60:63], v[140:143], v[180:183], v[60:63]
	v_mfma_f32_16x16x32_bf16 v[48:51], v[132:135], v[192:195], v[48:51]
	v_mfma_f32_16x16x32_bf16 v[44:47], v[140:143], v[192:195], v[44:47]
	v_mfma_f32_16x16x32_bf16 v[32:35], v[132:135], v[204:207], v[32:35]
	v_mfma_f32_16x16x32_bf16 v[28:31], v[140:143], v[204:207], v[28:31]
	v_mfma_f32_16x16x32_bf16 v[16:19], v[132:135], v[212:215], v[16:19]
	v_mfma_f32_16x16x32_bf16 v[12:15], v[140:143], v[212:215], v[12:15]
	v_mfma_f32_16x16x32_bf16 v[64:67], v[136:139], v[184:187], v[64:67]
	v_mfma_f32_16x16x32_bf16 v[60:63], v[144:147], v[184:187], v[60:63]
	v_mfma_f32_16x16x32_bf16 v[48:51], v[136:139], v[200:203], v[48:51]
	v_mfma_f32_16x16x32_bf16 v[44:47], v[144:147], v[200:203], v[44:47]
	v_mfma_f32_16x16x32_bf16 v[32:35], v[136:139], v[208:211], v[32:35]
	v_mfma_f32_16x16x32_bf16 v[28:31], v[144:147], v[208:211], v[28:31]
	v_mfma_f32_16x16x32_bf16 v[16:19], v[136:139], v[216:219], v[16:19]
	v_mfma_f32_16x16x32_bf16 v[12:15], v[144:147], v[216:219], v[12:15]
	v_mfma_f32_16x16x32_bf16 v[56:59], v[164:167], v[180:183], v[56:59]
	v_mfma_f32_16x16x32_bf16 v[52:55], v[172:175], v[180:183], v[52:55]
	v_mfma_f32_16x16x32_bf16 v[40:43], v[164:167], v[192:195], v[40:43]
	v_mfma_f32_16x16x32_bf16 v[36:39], v[172:175], v[192:195], v[36:39]
	v_mfma_f32_16x16x32_bf16 v[24:27], v[164:167], v[204:207], v[24:27]
	v_mfma_f32_16x16x32_bf16 v[20:23], v[172:175], v[204:207], v[20:23]
	v_mfma_f32_16x16x32_bf16 v[8:11], v[164:167], v[212:215], v[8:11]
	v_mfma_f32_16x16x32_bf16 v[4:7], v[172:175], v[212:215], v[4:7]
	v_mfma_f32_16x16x32_bf16 v[56:59], v[168:171], v[184:187], v[56:59]
	v_mfma_f32_16x16x32_bf16 v[52:55], v[176:179], v[184:187], v[52:55]
	v_mfma_f32_16x16x32_bf16 v[40:43], v[168:171], v[200:203], v[40:43]
	v_mfma_f32_16x16x32_bf16 v[36:39], v[176:179], v[200:203], v[36:39]
	v_mfma_f32_16x16x32_bf16 v[24:27], v[168:171], v[208:211], v[24:27]
	v_mfma_f32_16x16x32_bf16 v[20:23], v[176:179], v[208:211], v[20:23]
	v_mfma_f32_16x16x32_bf16 v[8:11], v[168:171], v[216:219], v[8:11]
	v_mfma_f32_16x16x32_bf16 v[4:7], v[176:179], v[216:219], v[4:7]
	s_barrier
	s_setprio 0
	s_add_i32 s67, s67, 2
	s_add_u32 s36, s36, 0x100
	s_addc_u32 s37, s37, 0
	s_add_u32 s38, s38, 0x100
	s_addc_u32 s39, s39, 0
	s_cmp_gt_u32 s67, 29
	s_cbranch_scc0 .LBB0_1395
	s_and_b64 vcc, exec, s[28:29]
	s_cbranch_vccz .LBB0_1398
	s_barrier

.LBB0_1441:
	s_add_u32 s0, s62, s30
	s_addc_u32 s6, s63, 0
	s_add_u32 s31, s0, 0x100
	s_addc_u32 s46, s6, 0
	s_and_b64 s[34:35], s[38:39], exec
	s_cselect_b32 s53, s43, s46
	s_cselect_b32 s52, s75, s31
	s_add_u32 s30, s66, s30
	s_addc_u32 s31, s67, 0
	s_add_u32 s34, s30, 0x100
	s_addc_u32 s35, s31, 0
	s_add_i32 s83, 0, 0x10000
	s_and_b64 s[30:31], s[38:39], exec
	s_cselect_b32 s31, s45, s35
	s_cselect_b32 s30, s81, s34
	s_add_i32 s39, 0, 0x14000
	s_add_u32 s46, s0, 0x80080
	s_addc_u32 s47, s6, 0
	s_add_i32 s49, s83, s4
	s_add_i32 m0, s59, 0xc000
	s_add_i32 s97, s59, 0xe000
	s_add_i32 s82, s49, 0x2000
	s_add_u32 s34, s30, 0x80000
	v_add_u32_e32 v144, s83, v3
	v_add_u32_e32 v172, s39, v3
	s_addc_u32 s35, s31, 0
	s_add_i32 s85, s39, s4
	ds_read_b128 v[132:135], v144
	ds_read_b128 v[136:139], v144 offset:1024
	ds_read_b128 v[140:143], v144 offset:2048
	ds_read_b128 v[144:147], v144 offset:3072
	ds_read_b128 v[160:163], v172
	ds_read_b128 v[164:167], v172 offset:1024
	ds_read_b128 v[168:171], v172 offset:2048
	ds_read_b128 v[172:175], v172 offset:3072
	s_add_i32 s84, s85, 0x2000
	s_add_i32 s0, 0, 0x18000
	s_add_i32 s54, 0, 0x1c000
	s_add_u32 vcc_lo, s52, 0x80000
	s_addc_u32 vcc_hi, s53, 0
	s_add_i32 s73, s0, s4
	s_add_i32 s6, s73, 0x2000
	s_add_u32 s38, s30, 0x80080
	s_addc_u32 s39, s31, 0
	s_add_i32 s83, s54, s4
	s_add_i32 s96, s83, 0x2000
	v_lshl_add_u64 v[198:199], s[46:47], 0, v[154:155]
	ds_read_b128 v[176:179], v186
	ds_read_b128 v[180:183], v186 offset:1024
	ds_read_b128 v[188:191], v186 offset:2048
	ds_read_b128 v[192:195], v186 offset:3072
	ds_read_b128 v[200:203], v186 offset:4096
	ds_read_b128 v[204:207], v186 offset:5120
	ds_read_b128 v[208:211], v186 offset:6144
	ds_read_b128 v[212:215], v186 offset:7168
	global_load_lds_dwordx4 v[198:199], off
	v_lshl_add_u64 v[198:199], s[46:47], 0, v[150:151]
	s_mov_b32 m0, s97
	s_nop 0
	global_load_lds_dwordx4 v[198:199], off
	s_waitcnt vmcnt(8)
	s_waitcnt lgkmcnt(0)
	s_setprio 1
	s_barrier
	v_mfma_f32_16x16x32_bf16 v[128:131], v[132:135], v[176:179], v[128:131]
	v_mfma_f32_16x16x32_bf16 v[124:127], v[140:143], v[176:179], v[124:127]
	v_mfma_f32_16x16x32_bf16 v[112:115], v[132:135], v[188:191], v[112:115]
	v_mfma_f32_16x16x32_bf16 v[108:111], v[140:143], v[188:191], v[108:111]
	v_mfma_f32_16x16x32_bf16 v[96:99], v[132:135], v[200:203], v[96:99]
	v_mfma_f32_16x16x32_bf16 v[92:95], v[140:143], v[200:203], v[92:95]
	v_mfma_f32_16x16x32_bf16 v[80:83], v[132:135], v[208:211], v[80:83]
	v_mfma_f32_16x16x32_bf16 v[76:79], v[140:143], v[208:211], v[76:79]
	v_mfma_f32_16x16x32_bf16 v[128:131], v[136:139], v[180:183], v[128:131]
	v_mfma_f32_16x16x32_bf16 v[124:127], v[144:147], v[180:183], v[124:127]
	v_mfma_f32_16x16x32_bf16 v[112:115], v[136:139], v[192:195], v[112:115]
	v_mfma_f32_16x16x32_bf16 v[108:111], v[144:147], v[192:195], v[108:111]
	v_mfma_f32_16x16x32_bf16 v[96:99], v[136:139], v[204:207], v[96:99]
	v_mfma_f32_16x16x32_bf16 v[92:95], v[144:147], v[204:207], v[92:95]
	v_mfma_f32_16x16x32_bf16 v[80:83], v[136:139], v[212:215], v[80:83]
	v_mfma_f32_16x16x32_bf16 v[76:79], v[144:147], v[212:215], v[76:79]
	v_mfma_f32_16x16x32_bf16 v[120:123], v[160:163], v[176:179], v[120:123]
	v_mfma_f32_16x16x32_bf16 v[116:119], v[168:171], v[176:179], v[116:119]
	v_mfma_f32_16x16x32_bf16 v[104:107], v[160:163], v[188:191], v[104:107]
	v_mfma_f32_16x16x32_bf16 v[100:103], v[168:171], v[188:191], v[100:103]
	v_mfma_f32_16x16x32_bf16 v[88:91], v[160:163], v[200:203], v[88:91]
	v_mfma_f32_16x16x32_bf16 v[84:87], v[168:171], v[200:203], v[84:87]
	v_mfma_f32_16x16x32_bf16 v[72:75], v[160:163], v[208:211], v[72:75]
	v_mfma_f32_16x16x32_bf16 v[68:71], v[168:171], v[208:211], v[68:71]
	v_mfma_f32_16x16x32_bf16 v[120:123], v[164:167], v[180:183], v[120:123]
	v_mfma_f32_16x16x32_bf16 v[116:119], v[172:175], v[180:183], v[116:119]
	v_mfma_f32_16x16x32_bf16 v[104:107], v[164:167], v[192:195], v[104:107]
	v_mfma_f32_16x16x32_bf16 v[100:103], v[172:175], v[192:195], v[100:103]
	v_mfma_f32_16x16x32_bf16 v[88:91], v[164:167], v[204:207], v[88:91]
	v_mfma_f32_16x16x32_bf16 v[84:87], v[172:175], v[204:207], v[84:87]
	v_mfma_f32_16x16x32_bf16 v[72:75], v[164:167], v[212:215], v[72:75]
	v_mfma_f32_16x16x32_bf16 v[68:71], v[172:175], v[212:215], v[68:71]
	s_barrier
	s_setprio 0
	s_mov_b32 m0, s49
	v_lshl_add_u64 v[198:199], s[30:31], 0, v[152:153]
	ds_read_b128 v[176:179], v186 offset:16384
	ds_read_b128 v[180:183], v186 offset:17408
	ds_read_b128 v[188:191], v186 offset:18432
	ds_read_b128 v[192:195], v186 offset:19456
	ds_read_b128 v[200:203], v186 offset:20480
	ds_read_b128 v[204:207], v186 offset:21504
	ds_read_b128 v[208:211], v186 offset:22528
	ds_read_b128 v[212:215], v186 offset:23552
	global_load_lds_dwordx4 v[198:199], off
	v_lshl_add_u64 v[216:217], s[30:31], 0, v[148:149]
	s_mov_b32 m0, s82
	v_lshl_add_u64 v[218:219], s[34:35], 0, v[152:153]
	global_load_lds_dwordx4 v[216:217], off
	s_mov_b32 m0, s85
	v_lshl_add_u64 v[220:221], s[52:53], 0, v[150:151]
	global_load_lds_dwordx4 v[218:219], off
	v_lshl_add_u64 v[218:219], s[34:35], 0, v[148:149]
	s_mov_b32 m0, s84
	s_nop 0
	global_load_lds_dwordx4 v[218:219], off
	v_lshl_add_u64 v[218:219], s[52:53], 0, v[154:155]
	s_mov_b32 m0, s59
	s_nop 0
	global_load_lds_dwordx4 v[218:219], off
	s_mov_b32 m0, s40
	s_nop 0
	global_load_lds_dwordx4 v[220:221], off
	s_waitcnt vmcnt(8)
	s_waitcnt lgkmcnt(0)
	s_setprio 1
	s_barrier
	v_mfma_f32_16x16x32_bf16 v[64:67], v[132:135], v[176:179], v[64:67]
	v_mfma_f32_16x16x32_bf16 v[60:63], v[140:143], v[176:179], v[60:63]
	v_mfma_f32_16x16x32_bf16 v[48:51], v[132:135], v[188:191], v[48:51]
	v_mfma_f32_16x16x32_bf16 v[44:47], v[140:143], v[188:191], v[44:47]
	v_mfma_f32_16x16x32_bf16 v[32:35], v[132:135], v[200:203], v[32:35]
	v_mfma_f32_16x16x32_bf16 v[28:31], v[140:143], v[200:203], v[28:31]
	v_mfma_f32_16x16x32_bf16 v[16:19], v[132:135], v[208:211], v[16:19]
	v_mfma_f32_16x16x32_bf16 v[12:15], v[140:143], v[208:211], v[12:15]
	v_mfma_f32_16x16x32_bf16 v[64:67], v[136:139], v[180:183], v[64:67]
	v_mfma_f32_16x16x32_bf16 v[60:63], v[144:147], v[180:183], v[60:63]
	v_mfma_f32_16x16x32_bf16 v[48:51], v[136:139], v[192:195], v[48:51]
	v_mfma_f32_16x16x32_bf16 v[44:47], v[144:147], v[192:195], v[44:47]
	v_mfma_f32_16x16x32_bf16 v[32:35], v[136:139], v[204:207], v[32:35]
	v_mfma_f32_16x16x32_bf16 v[28:31], v[144:147], v[204:207], v[28:31]
	v_mfma_f32_16x16x32_bf16 v[16:19], v[136:139], v[212:215], v[16:19]
	v_mfma_f32_16x16x32_bf16 v[12:15], v[144:147], v[212:215], v[12:15]
	v_mfma_f32_16x16x32_bf16 v[56:59], v[160:163], v[176:179], v[56:59]
	v_mfma_f32_16x16x32_bf16 v[52:55], v[168:171], v[176:179], v[52:55]
	v_mfma_f32_16x16x32_bf16 v[40:43], v[160:163], v[188:191], v[40:43]
	v_mfma_f32_16x16x32_bf16 v[36:39], v[168:171], v[188:191], v[36:39]
	v_mfma_f32_16x16x32_bf16 v[24:27], v[160:163], v[200:203], v[24:27]
	v_mfma_f32_16x16x32_bf16 v[20:23], v[168:171], v[200:203], v[20:23]
	v_mfma_f32_16x16x32_bf16 v[8:11], v[160:163], v[208:211], v[8:11]
	v_mfma_f32_16x16x32_bf16 v[4:7], v[168:171], v[208:211], v[4:7]
	v_mfma_f32_16x16x32_bf16 v[56:59], v[164:167], v[180:183], v[56:59]
	v_mfma_f32_16x16x32_bf16 v[52:55], v[172:175], v[180:183], v[52:55]
	v_mfma_f32_16x16x32_bf16 v[40:43], v[164:167], v[192:195], v[40:43]
	v_mfma_f32_16x16x32_bf16 v[36:39], v[172:175], v[192:195], v[36:39]
	v_mfma_f32_16x16x32_bf16 v[24:27], v[164:167], v[204:207], v[24:27]
	v_mfma_f32_16x16x32_bf16 v[20:23], v[172:175], v[204:207], v[20:23]
	v_mfma_f32_16x16x32_bf16 v[8:11], v[164:167], v[212:215], v[8:11]
	v_mfma_f32_16x16x32_bf16 v[4:7], v[172:175], v[212:215], v[4:7]
	s_barrier
	s_setprio 0
	v_add_u32_e32 v144, s0, v3
	v_add_u32_e32 v172, s54, v3
	ds_read_b128 v[132:135], v144
	ds_read_b128 v[136:139], v144 offset:1024
	ds_read_b128 v[140:143], v144 offset:2048
	ds_read_b128 v[144:147], v144 offset:3072
	ds_read_b128 v[160:163], v172
	ds_read_b128 v[164:167], v172 offset:1024
	ds_read_b128 v[168:171], v172 offset:2048
	ds_read_b128 v[172:175], v172 offset:3072
	s_mov_b32 m0, s55
	v_lshl_add_u64 v[222:223], vcc, 0, v[154:155]
	ds_read_b128 v[176:179], v186 offset:32768
	ds_read_b128 v[180:183], v186 offset:33792
	ds_read_b128 v[188:191], v186 offset:34816
	ds_read_b128 v[192:195], v186 offset:35840
	ds_read_b128 v[200:203], v186 offset:36864
	ds_read_b128 v[204:207], v186 offset:37888
	ds_read_b128 v[208:211], v186 offset:38912
	ds_read_b128 v[212:215], v186 offset:39936
	global_load_lds_dwordx4 v[222:223], off
	v_lshl_add_u64 v[222:223], vcc, 0, v[150:151]
	s_mov_b32 m0, s50
	s_nop 0
	global_load_lds_dwordx4 v[222:223], off
	s_waitcnt vmcnt(8)
	s_waitcnt lgkmcnt(0)
	s_setprio 1
	s_barrier
	v_mfma_f32_16x16x32_bf16 v[128:131], v[132:135], v[176:179], v[128:131]
	v_mfma_f32_16x16x32_bf16 v[124:127], v[140:143], v[176:179], v[124:127]
	v_mfma_f32_16x16x32_bf16 v[112:115], v[132:135], v[188:191], v[112:115]
	v_mfma_f32_16x16x32_bf16 v[108:111], v[140:143], v[188:191], v[108:111]
	v_mfma_f32_16x16x32_bf16 v[96:99], v[132:135], v[200:203], v[96:99]
	v_mfma_f32_16x16x32_bf16 v[92:95], v[140:143], v[200:203], v[92:95]
	v_mfma_f32_16x16x32_bf16 v[80:83], v[132:135], v[208:211], v[80:83]
	v_mfma_f32_16x16x32_bf16 v[76:79], v[140:143], v[208:211], v[76:79]
	v_mfma_f32_16x16x32_bf16 v[128:131], v[136:139], v[180:183], v[128:131]
	v_mfma_f32_16x16x32_bf16 v[124:127], v[144:147], v[180:183], v[124:127]
	v_mfma_f32_16x16x32_bf16 v[112:115], v[136:139], v[192:195], v[112:115]
	v_mfma_f32_16x16x32_bf16 v[108:111], v[144:147], v[192:195], v[108:111]
	v_mfma_f32_16x16x32_bf16 v[96:99], v[136:139], v[204:207], v[96:99]
	v_mfma_f32_16x16x32_bf16 v[92:95], v[144:147], v[204:207], v[92:95]
	v_mfma_f32_16x16x32_bf16 v[80:83], v[136:139], v[212:215], v[80:83]
	v_mfma_f32_16x16x32_bf16 v[76:79], v[144:147], v[212:215], v[76:79]
	v_mfma_f32_16x16x32_bf16 v[120:123], v[160:163], v[176:179], v[120:123]
	v_mfma_f32_16x16x32_bf16 v[116:119], v[168:171], v[176:179], v[116:119]
	v_mfma_f32_16x16x32_bf16 v[104:107], v[160:163], v[188:191], v[104:107]
	v_mfma_f32_16x16x32_bf16 v[100:103], v[168:171], v[188:191], v[100:103]
	v_mfma_f32_16x16x32_bf16 v[88:91], v[160:163], v[200:203], v[88:91]
	v_mfma_f32_16x16x32_bf16 v[84:87], v[168:171], v[200:203], v[84:87]
	v_mfma_f32_16x16x32_bf16 v[72:75], v[160:163], v[208:211], v[72:75]
	v_mfma_f32_16x16x32_bf16 v[68:71], v[168:171], v[208:211], v[68:71]
	v_mfma_f32_16x16x32_bf16 v[120:123], v[164:167], v[180:183], v[120:123]
	v_mfma_f32_16x16x32_bf16 v[116:119], v[172:175], v[180:183], v[116:119]
	v_mfma_f32_16x16x32_bf16 v[104:107], v[164:167], v[192:195], v[104:107]
	v_mfma_f32_16x16x32_bf16 v[100:103], v[172:175], v[192:195], v[100:103]
	v_mfma_f32_16x16x32_bf16 v[88:91], v[164:167], v[204:207], v[88:91]
	v_mfma_f32_16x16x32_bf16 v[84:87], v[172:175], v[204:207], v[84:87]
	v_mfma_f32_16x16x32_bf16 v[72:75], v[164:167], v[212:215], v[72:75]
	v_mfma_f32_16x16x32_bf16 v[68:71], v[172:175], v[212:215], v[68:71]
	s_barrier
	s_setprio 0
	s_mov_b32 m0, s73
	v_lshl_add_u64 v[198:199], v[198:199], 0, s[90:91]
	ds_read_b128 v[176:179], v186 offset:49152
	ds_read_b128 v[180:183], v186 offset:50176
	ds_read_b128 v[188:191], v186 offset:51200
	ds_read_b128 v[192:195], v186 offset:52224
	ds_read_b128 v[200:203], v186 offset:53248
	ds_read_b128 v[204:207], v186 offset:54272
	ds_read_b128 v[208:211], v186 offset:55296
	ds_read_b128 v[212:215], v186 offset:56320
	global_load_lds_dwordx4 v[198:199], off
	v_lshl_add_u64 v[198:199], v[216:217], 0, s[90:91]
	s_mov_b32 m0, s6
	s_nop 0
	global_load_lds_dwordx4 v[198:199], off
	v_lshl_add_u64 v[198:199], s[38:39], 0, v[152:153]
	s_mov_b32 m0, s83
	s_nop 0
	global_load_lds_dwordx4 v[198:199], off
	v_lshl_add_u64 v[198:199], s[38:39], 0, v[148:149]
	s_mov_b32 m0, s96
	s_nop 0
	global_load_lds_dwordx4 v[198:199], off
	v_lshl_add_u64 v[198:199], v[218:219], 0, s[90:91]
	s_mov_b32 m0, s1
	s_nop 0
	global_load_lds_dwordx4 v[198:199], off
	v_lshl_add_u64 v[198:199], v[220:221], 0, s[90:91]
	s_mov_b32 m0, s24
	s_nop 0
	global_load_lds_dwordx4 v[198:199], off
	s_waitcnt vmcnt(8)
	s_waitcnt lgkmcnt(0)
	s_setprio 1
	s_barrier
	v_mfma_f32_16x16x32_bf16 v[64:67], v[132:135], v[176:179], v[64:67]
	v_mfma_f32_16x16x32_bf16 v[60:63], v[140:143], v[176:179], v[60:63]
	v_mfma_f32_16x16x32_bf16 v[48:51], v[132:135], v[188:191], v[48:51]
	v_mfma_f32_16x16x32_bf16 v[44:47], v[140:143], v[188:191], v[44:47]
	v_mfma_f32_16x16x32_bf16 v[32:35], v[132:135], v[200:203], v[32:35]
	v_mfma_f32_16x16x32_bf16 v[28:31], v[140:143], v[200:203], v[28:31]
	v_mfma_f32_16x16x32_bf16 v[16:19], v[132:135], v[208:211], v[16:19]
	v_mfma_f32_16x16x32_bf16 v[12:15], v[140:143], v[208:211], v[12:15]
	v_mfma_f32_16x16x32_bf16 v[64:67], v[136:139], v[180:183], v[64:67]
	v_mfma_f32_16x16x32_bf16 v[60:63], v[144:147], v[180:183], v[60:63]
	v_mfma_f32_16x16x32_bf16 v[48:51], v[136:139], v[192:195], v[48:51]
	v_mfma_f32_16x16x32_bf16 v[44:47], v[144:147], v[192:195], v[44:47]
	v_mfma_f32_16x16x32_bf16 v[32:35], v[136:139], v[204:207], v[32:35]
	v_mfma_f32_16x16x32_bf16 v[28:31], v[144:147], v[204:207], v[28:31]
	v_mfma_f32_16x16x32_bf16 v[16:19], v[136:139], v[212:215], v[16:19]
	v_mfma_f32_16x16x32_bf16 v[12:15], v[144:147], v[212:215], v[12:15]
	v_mfma_f32_16x16x32_bf16 v[56:59], v[160:163], v[176:179], v[56:59]
	v_mfma_f32_16x16x32_bf16 v[52:55], v[168:171], v[176:179], v[52:55]
	v_mfma_f32_16x16x32_bf16 v[40:43], v[160:163], v[188:191], v[40:43]
	v_mfma_f32_16x16x32_bf16 v[36:39], v[168:171], v[188:191], v[36:39]
	v_mfma_f32_16x16x32_bf16 v[24:27], v[160:163], v[200:203], v[24:27]
	v_mfma_f32_16x16x32_bf16 v[20:23], v[168:171], v[200:203], v[20:23]
	v_mfma_f32_16x16x32_bf16 v[8:11], v[160:163], v[208:211], v[8:11]
	v_mfma_f32_16x16x32_bf16 v[4:7], v[168:171], v[208:211], v[4:7]
	v_mfma_f32_16x16x32_bf16 v[56:59], v[164:167], v[180:183], v[56:59]
	v_mfma_f32_16x16x32_bf16 v[52:55], v[172:175], v[180:183], v[52:55]
	v_mfma_f32_16x16x32_bf16 v[40:43], v[164:167], v[192:195], v[40:43]
	v_mfma_f32_16x16x32_bf16 v[36:39], v[172:175], v[192:195], v[36:39]
	v_mfma_f32_16x16x32_bf16 v[24:27], v[164:167], v[204:207], v[24:27]
	v_mfma_f32_16x16x32_bf16 v[20:23], v[172:175], v[204:207], v[20:23]
	v_mfma_f32_16x16x32_bf16 v[8:11], v[164:167], v[212:215], v[8:11]
	v_mfma_f32_16x16x32_bf16 v[4:7], v[172:175], v[212:215], v[4:7]
	s_barrier
	s_setprio 0
	s_movk_i32 s30, 0x100
	s_andn2_b64 vcc, exec, s[36:37]
	s_mov_b64 s[38:39], -1
	s_mov_b64 s[36:37], 0
	s_cbranch_vccz .LBB0_1441
	s_and_b64 vcc, exec, s[28:29]
	s_cbranch_vccz .LBB0_1444
	s_barrier
